# baseline (speedup 1.0000x reference)
; #define PG8_STAGE(bufoff, gbase, voff) do { _Pragma("unroll") for (int _i = 0; _i < 2; ++_i) \
;         __builtin_amdgcn_global_load_lds((const unsigned*)((const char*)(gbase) + (voff)[_i]), (PG8_LAS unsigned*)(lds + (bufoff) + ldsw + _i * 8192), 16, 0, 0); } while (0)
; #define PG8_LDA(dst, b, h) do { _Pragma("unroll") for (int m = 0; m < 4; ++m) _Pragma("unroll") for (int k = 0; k < 2; ++k) dst[m][k] = *(const PG8_LAS bf16x8*)(lds + PG8_SA(b, h) + aoff + m * 2048 + k * 1024); } while (0)
; #define PG8_LDB(dst, b, h) do { _Pragma("unroll") for (int n = 0; n < 2; ++n) _Pragma("unroll") for (int k = 0; k < 2; ++k) dst[n][k] = *(const PG8_LAS bf16x8*)(lds + PG8_SB(b, h) + boff + n * 2048 + k * 1024); } while (0)
; #define PG8_WAIT_V(n) asm volatile("s_waitcnt vmcnt(" #n ")" ::: "memory")
; #define PG8_WAIT_L(n) asm volatile("s_waitcnt lgkmcnt(" #n ")" ::: "memory")
; #define PG8_BAR __builtin_amdgcn_s_barrier()
; #define PG8_SCHED __builtin_amdgcn_sched_barrier(0)
; template <class Epi, class Sched, bool ALIGN_EPI = false, bool SP2 = false>
; __device__ __forceinline__ void gemm_phase(PG8_LAS unsigned char* lds, const Gemm g, const Sched& S, const Epi& E) {
;     ...
;         const char* nA = has_next ? (const char*)g.A + (size_t)nxt.pm * tstep : cA; const char* nB = has_next ? (const char*)g.Bt + (size_t)nxt.pn * tstep : cB;
;         for (int t = 0; t < nt; t += 2) {
;             if constexpr (Epi::MID_HOOK) { if (t == Epi::MID_T) E.mid(acc, cur, wr, wc, fr, fq); }
;             const bool last = (t == nt - 2);
;             const char* a1 = cA + (size_t)(t + 1) * kstep;
;             const char* a2 = last ? nA : cA + (size_t)(t + 2) * kstep; const char* b2 = last ? nB : cB + (size_t)(t + 2) * kstep;
;             const char* a3 = a2 + kstep; const char* b3 = b2 + kstep;
;             if (last && has_next) S.a_ready(nxt);
;             if constexpr (SP2) {
;             PG8_LDB(B0, 0, 0); PG8_LDB(B1, 0, 1); PG8_SCHED; PG8_LDA(At, 0, 0); PG8_STAGE(PG8_SA(1, 1), a1 + hstep, voffA);
;             PG8_WAIT_V(8); PG8_WAIT_L(0); PG8_BAR; PG8_MMA(0, 0, At, B0); PG8_MMA(0, 1, At, B1); PG8_BAR; PG8_SCHED;
;             PG8_LDA(At, 0, 1); PG8_STAGE(PG8_SB(0, 0), b2, voffB); PG8_STAGE(PG8_SB(0, 1), b2 + hstep, voffB); PG8_STAGE(PG8_SA(0, 0), a2, voffA);
;             PG8_WAIT_V(8); PG8_WAIT_L(0); PG8_BAR; PG8_MMA(1, 0, At, B0); PG8_MMA(1, 1, At, B1); PG8_BAR; PG8_SCHED;
.LBB0_128:
	s_ashr_i32 s67, s66, 31
	s_lshl_b64 s[14:15], s[66:67], 20
	s_add_u32 s70, s37, s14
	s_addc_u32 s71, s38, s15
	s_and_b64 s[14:15], s[68:69], exec
	s_cselect_b32 s2, s71, s1
	s_cselect_b32 s11, s70, s0
	s_ashr_i32 s65, s64, 31
	s_lshl_b64 s[14:15], s[64:65], 20
	s_add_u32 s72, s31, s14
	s_addc_u32 s73, s36, s15
	s_and_b64 s[14:15], s[68:69], exec
	s_cselect_b32 s18, s73, s13
	s_cselect_b32 s19, s72, s12
	s_add_u32 s0, s0, 0x80080
	s_addc_u32 s1, s1, 0
	s_add_u32 s34, s12, 0x100
	s_addc_u32 s41, s13, 0
	s_mov_b32 s42, -2
	v_lshl_add_u64 v[194:195], s[0:1], 0, v[144:145]
	s_add_i32 m0, s74, 0xc000
	global_load_lds_dwordx4 v[194:195], off
	s_add_i32 m0, s74, 0xe000
	v_lshl_add_u64 v[194:195], s[0:1], 0, v[146:147]
	global_load_lds_dwordx4 v[194:195], off
	s_add_u32 s12, s0, 0xfff80080
	s_addc_u32 s13, s1, -1
	s_add_i32 s43, 0, 0x10000
	s_cmp_eq_u32 s42, 28
	s_cselect_b32 s15, s2, s13
	s_cselect_b32 s14, s11, s12
	s_cselect_b32 s13, s18, s41
	s_cselect_b32 s12, s19, s34
	s_add_i32 s65, 0, 0x14000
	s_waitcnt vmcnt(8)
	s_waitcnt lgkmcnt(0)
	s_barrier
	s_setprio 1
	s_waitcnt lgkmcnt(0)
	v_mfma_f32_16x16x32_bf16 v[124:127], v[128:131], v[172:175], 0
	v_mfma_f32_16x16x32_bf16 v[120:123], v[148:151], v[172:175], 0
	v_mfma_f32_16x16x32_bf16 v[108:111], v[128:131], v[184:187], 0
	v_mfma_f32_16x16x32_bf16 v[104:107], v[148:151], v[184:187], 0
	v_mfma_f32_16x16x32_bf16 v[92:95], v[128:131], v[206:209], 0
	v_mfma_f32_16x16x32_bf16 v[88:91], v[148:151], v[206:209], 0
	v_mfma_f32_16x16x32_bf16 v[76:79], v[128:131], v[214:217], 0
	v_mfma_f32_16x16x32_bf16 v[72:75], v[148:151], v[214:217], 0
	v_mfma_f32_16x16x32_bf16 v[124:127], v[132:135], v[180:183], v[124:127]
	v_mfma_f32_16x16x32_bf16 v[120:123], v[152:155], v[180:183], v[120:123]
	v_mfma_f32_16x16x32_bf16 v[108:111], v[132:135], v[188:191], v[108:111]
	v_mfma_f32_16x16x32_bf16 v[104:107], v[152:155], v[188:191], v[104:107]
	v_mfma_f32_16x16x32_bf16 v[92:95], v[132:135], v[210:213], v[92:95]
	v_mfma_f32_16x16x32_bf16 v[88:91], v[152:155], v[210:213], v[88:91]
	v_mfma_f32_16x16x32_bf16 v[76:79], v[132:135], v[218:221], v[76:79]
	v_mfma_f32_16x16x32_bf16 v[72:75], v[152:155], v[218:221], v[72:75]
	s_setprio 0
	s_setprio 1
	v_mfma_f32_16x16x32_bf16 v[116:119], v[156:159], v[172:175], 0
	v_mfma_f32_16x16x32_bf16 v[112:115], v[164:167], v[172:175], 0
	v_mfma_f32_16x16x32_bf16 v[100:103], v[156:159], v[184:187], 0
	v_mfma_f32_16x16x32_bf16 v[96:99], v[164:167], v[184:187], 0
	v_mfma_f32_16x16x32_bf16 v[84:87], v[156:159], v[206:209], 0
	v_mfma_f32_16x16x32_bf16 v[80:83], v[164:167], v[206:209], 0
	v_mfma_f32_16x16x32_bf16 v[68:71], v[156:159], v[214:217], 0
	v_mfma_f32_16x16x32_bf16 v[64:67], v[164:167], v[214:217], 0
	v_mfma_f32_16x16x32_bf16 v[116:119], v[160:163], v[180:183], v[116:119]
	v_mfma_f32_16x16x32_bf16 v[112:115], v[168:171], v[180:183], v[112:115]
	v_mfma_f32_16x16x32_bf16 v[100:103], v[160:163], v[188:191], v[100:103]
	v_mfma_f32_16x16x32_bf16 v[96:99], v[168:171], v[188:191], v[96:99]
	v_mfma_f32_16x16x32_bf16 v[84:87], v[160:163], v[210:213], v[84:87]
	v_mfma_f32_16x16x32_bf16 v[80:83], v[168:171], v[210:213], v[80:83]
	s_barrier
	v_mfma_f32_16x16x32_bf16 v[68:71], v[160:163], v[218:221], v[68:71]
	v_mfma_f32_16x16x32_bf16 v[64:67], v[168:171], v[218:221], v[64:67]
	s_setprio 0
	s_add_i32 s43, s43, s39
	v_lshl_add_u64 v[194:195], s[12:13], 0, v[138:139]
	s_mov_b32 m0, s43
	ds_read_b128 v[172:175], v179 offset:16384
	ds_read_b128 v[180:183], v179 offset:17408
	ds_read_b128 v[184:187], v179 offset:18432
	ds_read_b128 v[188:191], v179 offset:19456
	ds_read_b128 v[206:209], v179 offset:20480
	ds_read_b128 v[210:213], v179 offset:21504
	ds_read_b128 v[214:217], v179 offset:22528
	ds_read_b128 v[218:221], v179 offset:23552
	global_load_lds_dwordx4 v[194:195], off
	s_add_i32 m0, s43, 0x2000
	s_add_u32 s86, s12, 0x80000
	v_lshl_add_u64 v[196:197], s[12:13], 0, v[142:143]
	s_addc_u32 s87, s13, 0
	s_add_i32 s43, s65, s39
	global_load_lds_dwordx4 v[196:197], off
	v_lshl_add_u64 v[202:203], s[86:87], 0, v[138:139]
	s_mov_b32 m0, s43
	v_lshl_add_u64 v[204:205], s[14:15], 0, v[140:141]
	global_load_lds_dwordx4 v[202:203], off
	s_add_i32 m0, s43, 0x2000
	v_lshl_add_u64 v[202:203], s[86:87], 0, v[142:143]
	global_load_lds_dwordx4 v[202:203], off
	s_mov_b32 m0, s74
	v_lshl_add_u64 v[202:203], s[14:15], 0, v[136:137]
	global_load_lds_dwordx4 v[202:203], off
	s_mov_b32 m0, s75
	s_nop 0
	global_load_lds_dwordx4 v[204:205], off
	s_waitcnt vmcnt(8)
	s_waitcnt lgkmcnt(0)
	s_barrier
	s_setprio 1
	s_waitcnt lgkmcnt(0)
	v_mfma_f32_16x16x32_bf16 v[60:63], v[128:131], v[172:175], 0
	v_mfma_f32_16x16x32_bf16 v[56:59], v[148:151], v[172:175], 0
	v_mfma_f32_16x16x32_bf16 v[44:47], v[128:131], v[184:187], 0
	v_mfma_f32_16x16x32_bf16 v[40:43], v[148:151], v[184:187], 0
	v_mfma_f32_16x16x32_bf16 v[28:31], v[128:131], v[206:209], 0
	v_mfma_f32_16x16x32_bf16 v[24:27], v[148:151], v[206:209], 0
	v_mfma_f32_16x16x32_bf16 v[12:15], v[128:131], v[214:217], 0
	v_mfma_f32_16x16x32_bf16 v[8:11], v[148:151], v[214:217], 0
	v_mfma_f32_16x16x32_bf16 v[60:63], v[132:135], v[180:183], v[60:63]
	v_mfma_f32_16x16x32_bf16 v[56:59], v[152:155], v[180:183], v[56:59]
	v_mfma_f32_16x16x32_bf16 v[44:47], v[132:135], v[188:191], v[44:47]
	v_mfma_f32_16x16x32_bf16 v[40:43], v[152:155], v[188:191], v[40:43]
	v_mfma_f32_16x16x32_bf16 v[28:31], v[132:135], v[210:213], v[28:31]
	v_mfma_f32_16x16x32_bf16 v[24:27], v[152:155], v[210:213], v[24:27]
	v_mfma_f32_16x16x32_bf16 v[12:15], v[132:135], v[218:221], v[12:15]
	v_mfma_f32_16x16x32_bf16 v[8:11], v[152:155], v[218:221], v[8:11]
	s_setprio 0
	s_setprio 1
	v_mfma_f32_16x16x32_bf16 v[52:55], v[156:159], v[172:175], 0
	v_mfma_f32_16x16x32_bf16 v[48:51], v[164:167], v[172:175], 0
	v_mfma_f32_16x16x32_bf16 v[36:39], v[156:159], v[184:187], 0
	v_mfma_f32_16x16x32_bf16 v[32:35], v[164:167], v[184:187], 0
	v_mfma_f32_16x16x32_bf16 v[20:23], v[156:159], v[206:209], 0
	v_mfma_f32_16x16x32_bf16 v[16:19], v[164:167], v[206:209], 0
	v_mfma_f32_16x16x32_bf16 v[4:7], v[156:159], v[214:217], 0
	v_mfma_f32_16x16x32_bf16 v[0:3], v[164:167], v[214:217], 0
	v_mfma_f32_16x16x32_bf16 v[52:55], v[160:163], v[180:183], v[52:55]
	v_mfma_f32_16x16x32_bf16 v[48:51], v[168:171], v[180:183], v[48:51]
	v_mfma_f32_16x16x32_bf16 v[36:39], v[160:163], v[188:191], v[36:39]
	v_mfma_f32_16x16x32_bf16 v[32:35], v[168:171], v[188:191], v[32:35]
	v_mfma_f32_16x16x32_bf16 v[20:23], v[160:163], v[210:213], v[20:23]
	v_mfma_f32_16x16x32_bf16 v[16:19], v[168:171], v[210:213], v[16:19]
	s_barrier
; #define PG8_STAGE(bufoff, gbase, voff) do { _Pragma("unroll") for (int _i = 0; _i < 2; ++_i) \
;         __builtin_amdgcn_global_load_lds((const unsigned*)((const char*)(gbase) + (voff)[_i]), (PG8_LAS unsigned*)(lds + (bufoff) + ldsw + _i * 8192), 16, 0, 0); } while (0)
; #define PG8_LDA(dst, b, h) do { _Pragma("unroll") for (int m = 0; m < 4; ++m) _Pragma("unroll") for (int k = 0; k < 2; ++k) dst[m][k] = *(const PG8_LAS bf16x8*)(lds + PG8_SA(b, h) + aoff + m * 2048 + k * 1024); } while (0)
; #define PG8_LDB(dst, b, h) do { _Pragma("unroll") for (int n = 0; n < 2; ++n) _Pragma("unroll") for (int k = 0; k < 2; ++k) dst[n][k] = *(const PG8_LAS bf16x8*)(lds + PG8_SB(b, h) + boff + n * 2048 + k * 1024); } while (0)
; #define PG8_MMA(ai, bj, At, Bt) do { __builtin_amdgcn_s_setprio(1); _Pragma("unroll") for (int m = 0; m < 4; ++m) _Pragma("unroll") for (int n = 0; n < 2; ++n) _Pragma("unroll") for (int k = 0; k < 2; ++k) \
;         acc[ai][bj][m][n] = __builtin_amdgcn_mfma_f32_16x16x32_bf16(Bt[n][k], At[m][k], acc[ai][bj][m][n], 0, 0, 0); __builtin_amdgcn_s_setprio(0); } while (0)
; #define PG8_WAIT_V(n) asm volatile("s_waitcnt vmcnt(" #n ")" ::: "memory")
; #define PG8_WAIT_L(n) asm volatile("s_waitcnt lgkmcnt(" #n ")" ::: "memory")
; #define PG8_BAR __builtin_amdgcn_s_barrier()
; #define PG8_SCHED __builtin_amdgcn_sched_barrier(0)
; template <class Epi, class Sched, bool ALIGN_EPI = false, bool SP2 = false>
; __device__ __forceinline__ void gemm_phase(PG8_LAS unsigned char* lds, const Gemm g, const Sched& S, const Epi& E) {
;     ...
;             PG8_WAIT_V(8); PG8_WAIT_L(0); PG8_BAR; PG8_MMA(1, 0, At, B0); PG8_MMA(1, 1, At, B1); PG8_BAR; PG8_SCHED;
;             PG8_LDB(B0, 1, 0); PG8_LDB(B1, 1, 1); PG8_SCHED; PG8_LDA(At, 1, 0); PG8_STAGE(PG8_SA(0, 1), a2 + hstep, voffA);
;             PG8_WAIT_V(8); PG8_WAIT_L(0); PG8_BAR; PG8_MMA(0, 0, At, B0); PG8_MMA(0, 1, At, B1); PG8_BAR; PG8_SCHED;
;             PG8_LDA(At, 1, 1); PG8_STAGE(PG8_SB(1, 0), b3, voffB); PG8_STAGE(PG8_SB(1, 1), b3 + hstep, voffB); PG8_STAGE(PG8_SA(1, 0), a3, voffA);
	v_mfma_f32_16x16x32_bf16 v[4:7], v[160:163], v[218:221], v[4:7]
	v_mfma_f32_16x16x32_bf16 v[0:3], v[168:171], v[218:221], v[0:3]
	s_setprio 0
	s_add_i32 s43, 0, 0x18000
	s_add_i32 s65, 0, 0x1c000
	v_add_u32_e32 v152, 0x18000, v178
	v_add_u32_e32 v168, 0x1c000, v178
	ds_read_b128 v[128:131], v152
	ds_read_b128 v[132:135], v152 offset:1024
	ds_read_b128 v[148:151], v152 offset:2048
	ds_read_b128 v[152:155], v152 offset:3072
	ds_read_b128 v[156:159], v168
	ds_read_b128 v[160:163], v168 offset:1024
	ds_read_b128 v[164:167], v168 offset:2048
	ds_read_b128 v[168:171], v168 offset:3072
	s_add_u32 s14, s14, 0x80000
	s_addc_u32 s15, s15, 0
	s_mov_b32 m0, s76
	v_lshl_add_u64 v[232:233], s[14:15], 0, v[136:137]
	ds_read_b128 v[172:175], v179 offset:32768
	ds_read_b128 v[180:183], v179 offset:33792
	ds_read_b128 v[184:187], v179 offset:34816
	ds_read_b128 v[188:191], v179 offset:35840
	ds_read_b128 v[206:209], v179 offset:36864
	ds_read_b128 v[210:213], v179 offset:37888
	ds_read_b128 v[214:217], v179 offset:38912
	ds_read_b128 v[218:221], v179 offset:39936
	global_load_lds_dwordx4 v[232:233], off
	s_mov_b32 m0, s77
	v_lshl_add_u64 v[232:233], s[14:15], 0, v[140:141]
	global_load_lds_dwordx4 v[232:233], off
	s_waitcnt vmcnt(8)
	s_waitcnt lgkmcnt(0)
	s_barrier
	s_setprio 1
	s_waitcnt lgkmcnt(0)
	v_mfma_f32_16x16x32_bf16 v[124:127], v[128:131], v[172:175], v[124:127]
	v_mfma_f32_16x16x32_bf16 v[120:123], v[148:151], v[172:175], v[120:123]
	v_mfma_f32_16x16x32_bf16 v[108:111], v[128:131], v[184:187], v[108:111]
	v_mfma_f32_16x16x32_bf16 v[104:107], v[148:151], v[184:187], v[104:107]
	v_mfma_f32_16x16x32_bf16 v[92:95], v[128:131], v[206:209], v[92:95]
	v_mfma_f32_16x16x32_bf16 v[88:91], v[148:151], v[206:209], v[88:91]
	v_mfma_f32_16x16x32_bf16 v[76:79], v[128:131], v[214:217], v[76:79]
	v_mfma_f32_16x16x32_bf16 v[72:75], v[148:151], v[214:217], v[72:75]
	v_mfma_f32_16x16x32_bf16 v[124:127], v[132:135], v[180:183], v[124:127]
	v_mfma_f32_16x16x32_bf16 v[120:123], v[152:155], v[180:183], v[120:123]
	v_mfma_f32_16x16x32_bf16 v[108:111], v[132:135], v[188:191], v[108:111]
	v_mfma_f32_16x16x32_bf16 v[104:107], v[152:155], v[188:191], v[104:107]
	v_mfma_f32_16x16x32_bf16 v[92:95], v[132:135], v[210:213], v[92:95]
	v_mfma_f32_16x16x32_bf16 v[88:91], v[152:155], v[210:213], v[88:91]
	v_mfma_f32_16x16x32_bf16 v[76:79], v[132:135], v[218:221], v[76:79]
	v_mfma_f32_16x16x32_bf16 v[72:75], v[152:155], v[218:221], v[72:75]
	s_setprio 0
	s_setprio 1
	v_mfma_f32_16x16x32_bf16 v[116:119], v[156:159], v[172:175], v[116:119]
	v_mfma_f32_16x16x32_bf16 v[112:115], v[164:167], v[172:175], v[112:115]
	v_mfma_f32_16x16x32_bf16 v[100:103], v[156:159], v[184:187], v[100:103]
	v_mfma_f32_16x16x32_bf16 v[96:99], v[164:167], v[184:187], v[96:99]
	v_mfma_f32_16x16x32_bf16 v[84:87], v[156:159], v[206:209], v[84:87]
	v_mfma_f32_16x16x32_bf16 v[80:83], v[164:167], v[206:209], v[80:83]
	v_mfma_f32_16x16x32_bf16 v[68:71], v[156:159], v[214:217], v[68:71]
	v_mfma_f32_16x16x32_bf16 v[64:67], v[164:167], v[214:217], v[64:67]
	v_mfma_f32_16x16x32_bf16 v[116:119], v[160:163], v[180:183], v[116:119]
	v_mfma_f32_16x16x32_bf16 v[112:115], v[168:171], v[180:183], v[112:115]
	v_mfma_f32_16x16x32_bf16 v[100:103], v[160:163], v[188:191], v[100:103]
	v_mfma_f32_16x16x32_bf16 v[96:99], v[168:171], v[188:191], v[96:99]
	v_mfma_f32_16x16x32_bf16 v[84:87], v[160:163], v[210:213], v[84:87]
	v_mfma_f32_16x16x32_bf16 v[80:83], v[168:171], v[210:213], v[80:83]
	s_barrier
	v_mfma_f32_16x16x32_bf16 v[68:71], v[160:163], v[218:221], v[68:71]
	v_mfma_f32_16x16x32_bf16 v[64:67], v[168:171], v[218:221], v[64:67]
	s_setprio 0
	s_add_i32 s14, s43, s39
	v_lshl_add_u64 v[194:195], v[194:195], 0, s[16:17]
	s_mov_b32 m0, s14
	ds_read_b128 v[172:175], v179 offset:49152
	ds_read_b128 v[180:183], v179 offset:50176
	ds_read_b128 v[184:187], v179 offset:51200
	ds_read_b128 v[188:191], v179 offset:52224
	ds_read_b128 v[206:209], v179 offset:53248
	ds_read_b128 v[210:213], v179 offset:54272
	ds_read_b128 v[214:217], v179 offset:55296
	ds_read_b128 v[218:221], v179 offset:56320
	global_load_lds_dwordx4 v[194:195], off
	s_add_i32 m0, s14, 0x2000
	s_add_u32 s12, s12, 0x80080
	v_lshl_add_u64 v[194:195], v[196:197], 0, s[16:17]
	s_addc_u32 s13, s13, 0
	s_add_i32 s14, s65, s39
	global_load_lds_dwordx4 v[194:195], off
	s_mov_b32 m0, s14
	v_lshl_add_u64 v[194:195], s[12:13], 0, v[138:139]
	global_load_lds_dwordx4 v[194:195], off
	s_add_i32 m0, s14, 0x2000
	v_lshl_add_u64 v[194:195], s[12:13], 0, v[142:143]
	global_load_lds_dwordx4 v[194:195], off
	s_mov_b32 m0, s80
	v_lshl_add_u64 v[194:195], v[202:203], 0, s[16:17]
	global_load_lds_dwordx4 v[194:195], off
	s_mov_b32 m0, s81
	v_lshl_add_u64 v[194:195], v[204:205], 0, s[16:17]
	global_load_lds_dwordx4 v[194:195], off
	s_waitcnt vmcnt(8)
	s_waitcnt lgkmcnt(0)
	s_barrier
; #define PG8_STAGE(bufoff, gbase, voff) do { _Pragma("unroll") for (int _i = 0; _i < 2; ++_i) \
;         __builtin_amdgcn_global_load_lds((const unsigned*)((const char*)(gbase) + (voff)[_i]), (PG8_LAS unsigned*)(lds + (bufoff) + ldsw + _i * 8192), 16, 0, 0); } while (0)
; #define PG8_LDA(dst, b, h) do { _Pragma("unroll") for (int m = 0; m < 4; ++m) _Pragma("unroll") for (int k = 0; k < 2; ++k) dst[m][k] = *(const PG8_LAS bf16x8*)(lds + PG8_SA(b, h) + aoff + m * 2048 + k * 1024); } while (0)
; #define PG8_LDB(dst, b, h) do { _Pragma("unroll") for (int n = 0; n < 2; ++n) _Pragma("unroll") for (int k = 0; k < 2; ++k) dst[n][k] = *(const PG8_LAS bf16x8*)(lds + PG8_SB(b, h) + boff + n * 2048 + k * 1024); } while (0)
; #define PG8_MMA(ai, bj, At, Bt) do { __builtin_amdgcn_s_setprio(1); _Pragma("unroll") for (int m = 0; m < 4; ++m) _Pragma("unroll") for (int n = 0; n < 2; ++n) _Pragma("unroll") for (int k = 0; k < 2; ++k) \
;         acc[ai][bj][m][n] = __builtin_amdgcn_mfma_f32_16x16x32_bf16(Bt[n][k], At[m][k], acc[ai][bj][m][n], 0, 0, 0); __builtin_amdgcn_s_setprio(0); } while (0)
; #define PG8_WAIT_V(n) asm volatile("s_waitcnt vmcnt(" #n ")" ::: "memory")
; template <class Epi, class Sched, bool ALIGN_EPI = false, bool SP2 = false>
; __device__ __forceinline__ void gemm_phase(PG8_LAS unsigned char* lds, const Gemm g, const Sched& S, const Epi& E) {
;     ...
;             PG8_LDB(B0, 0, 0); PG8_LDB(B1, 0, 1); PG8_SCHED; PG8_LDA(At, 0, 0); PG8_STAGE(PG8_SA(1, 1), a1 + hstep, voffA);
;             PG8_WAIT_V(8); PG8_WAIT_L(0); PG8_BAR; PG8_MMA(0, 0, At, B0); PG8_MMA(0, 1, At, B1); PG8_BAR; PG8_SCHED;
;             PG8_LDA(At, 0, 1); PG8_STAGE(PG8_SB(0, 0), b2, voffB); PG8_STAGE(PG8_SB(0, 1), b2 + hstep, voffB); PG8_STAGE(PG8_SA(0, 0), a2, voffA);
;             PG8_WAIT_V(8); PG8_WAIT_L(0); PG8_BAR; PG8_MMA(1, 0, At, B0); PG8_MMA(1, 1, At, B1); PG8_BAR; PG8_SCHED;
;             PG8_LDB(B0, 1, 0); PG8_LDB(B1, 1, 1); PG8_SCHED; PG8_LDA(At, 1, 0); PG8_STAGE(PG8_SA(0, 1), a2 + hstep, voffA);
;             PG8_WAIT_V(8); PG8_WAIT_L(0); PG8_BAR; PG8_MMA(0, 0, At, B0); PG8_MMA(0, 1, At, B1); PG8_BAR; PG8_SCHED;
;             PG8_LDA(At, 1, 1); PG8_STAGE(PG8_SB(1, 0), b3, voffB); PG8_STAGE(PG8_SB(1, 1), b3 + hstep, voffB); PG8_STAGE(PG8_SA(1, 0), a3, voffA);
;             PG8_WAIT_V(8); PG8_WAIT_L(0); PG8_BAR; PG8_MMA(1, 0, At, B0); PG8_MMA(1, 1, At, B1); PG8_BAR; PG8_SCHED;
	s_setprio 1
	s_waitcnt lgkmcnt(0)
	v_mfma_f32_16x16x32_bf16 v[60:63], v[128:131], v[172:175], v[60:63]
	v_mfma_f32_16x16x32_bf16 v[56:59], v[148:151], v[172:175], v[56:59]
	v_mfma_f32_16x16x32_bf16 v[44:47], v[128:131], v[184:187], v[44:47]
	v_mfma_f32_16x16x32_bf16 v[40:43], v[148:151], v[184:187], v[40:43]
	v_mfma_f32_16x16x32_bf16 v[28:31], v[128:131], v[206:209], v[28:31]
	v_mfma_f32_16x16x32_bf16 v[24:27], v[148:151], v[206:209], v[24:27]
	v_mfma_f32_16x16x32_bf16 v[12:15], v[128:131], v[214:217], v[12:15]
	v_mfma_f32_16x16x32_bf16 v[8:11], v[148:151], v[214:217], v[8:11]
	v_mfma_f32_16x16x32_bf16 v[60:63], v[132:135], v[180:183], v[60:63]
	v_mfma_f32_16x16x32_bf16 v[56:59], v[152:155], v[180:183], v[56:59]
	v_mfma_f32_16x16x32_bf16 v[44:47], v[132:135], v[188:191], v[44:47]
	v_mfma_f32_16x16x32_bf16 v[40:43], v[152:155], v[188:191], v[40:43]
	v_mfma_f32_16x16x32_bf16 v[28:31], v[132:135], v[210:213], v[28:31]
	v_mfma_f32_16x16x32_bf16 v[24:27], v[152:155], v[210:213], v[24:27]
	v_mfma_f32_16x16x32_bf16 v[12:15], v[132:135], v[218:221], v[12:15]
	v_mfma_f32_16x16x32_bf16 v[8:11], v[152:155], v[218:221], v[8:11]
	s_setprio 0
	s_setprio 1
	v_mfma_f32_16x16x32_bf16 v[52:55], v[156:159], v[172:175], v[52:55]
	v_mfma_f32_16x16x32_bf16 v[48:51], v[164:167], v[172:175], v[48:51]
	v_mfma_f32_16x16x32_bf16 v[36:39], v[156:159], v[184:187], v[36:39]
	v_mfma_f32_16x16x32_bf16 v[32:35], v[164:167], v[184:187], v[32:35]
	v_mfma_f32_16x16x32_bf16 v[20:23], v[156:159], v[206:209], v[20:23]
	v_mfma_f32_16x16x32_bf16 v[16:19], v[164:167], v[206:209], v[16:19]
	v_mfma_f32_16x16x32_bf16 v[4:7], v[156:159], v[214:217], v[4:7]
	v_mfma_f32_16x16x32_bf16 v[0:3], v[164:167], v[214:217], v[0:3]
	v_mfma_f32_16x16x32_bf16 v[52:55], v[160:163], v[180:183], v[52:55]
	v_mfma_f32_16x16x32_bf16 v[48:51], v[168:171], v[180:183], v[48:51]
	v_mfma_f32_16x16x32_bf16 v[36:39], v[160:163], v[188:191], v[36:39]
	v_mfma_f32_16x16x32_bf16 v[32:35], v[168:171], v[188:191], v[32:35]
	v_mfma_f32_16x16x32_bf16 v[20:23], v[160:163], v[210:213], v[20:23]
	v_mfma_f32_16x16x32_bf16 v[16:19], v[168:171], v[210:213], v[16:19]
	s_barrier
	v_mfma_f32_16x16x32_bf16 v[4:7], v[160:163], v[218:221], v[4:7]
	v_mfma_f32_16x16x32_bf16 v[0:3], v[168:171], v[218:221], v[0:3]
	s_setprio 0
	s_add_i32 s42, s42, 2
	s_add_u32 s0, s0, 0x100
	s_addc_u32 s1, s1, 0
	s_add_u32 s34, s34, 0x100
	s_addc_u32 s41, s41, 0
	s_cmp_gt_u32 s42, 29
	s_branch .LBB0_129
.LBB0_129:
	v_add_u32_e32 v152, 0x10000, v178
	v_add_u32_e32 v168, 0x14000, v178
	ds_read_b128 v[128:131], v152
	ds_read_b128 v[132:135], v152 offset:1024
	ds_read_b128 v[148:151], v152 offset:2048
	ds_read_b128 v[152:155], v152 offset:3072
	ds_read_b128 v[156:159], v168
	ds_read_b128 v[160:163], v168 offset:1024
	ds_read_b128 v[164:167], v168 offset:2048
	ds_read_b128 v[168:171], v168 offset:3072
	v_lshl_add_u64 v[194:195], s[0:1], 0, v[144:145]
	s_add_i32 m0, s74, 0xc000
	ds_read_b128 v[172:175], v179
	ds_read_b128 v[180:183], v179 offset:1024
	ds_read_b128 v[184:187], v179 offset:2048
	ds_read_b128 v[188:191], v179 offset:3072
	ds_read_b128 v[206:209], v179 offset:4096
	ds_read_b128 v[210:213], v179 offset:5120
	ds_read_b128 v[214:217], v179 offset:6144
	ds_read_b128 v[218:221], v179 offset:7168
	global_load_lds_dwordx4 v[194:195], off
	s_add_i32 m0, s74, 0xe000
	v_lshl_add_u64 v[194:195], s[0:1], 0, v[146:147]
	global_load_lds_dwordx4 v[194:195], off
	s_add_u32 s12, s0, 0xfff80080
	s_addc_u32 s13, s1, -1
	s_add_i32 s43, 0, 0x10000
	s_cmp_eq_u32 s42, 28
	s_cselect_b32 s15, s2, s13
	s_cselect_b32 s14, s11, s12
	s_cselect_b32 s13, s18, s41
	s_cselect_b32 s12, s19, s34
	s_add_i32 s65, 0, 0x14000
	s_waitcnt vmcnt(8)
	s_waitcnt lgkmcnt(0)
	s_barrier
	s_setprio 1
	s_waitcnt lgkmcnt(0)
	v_mfma_f32_16x16x32_bf16 v[124:127], v[128:131], v[172:175], v[124:127]
	v_mfma_f32_16x16x32_bf16 v[120:123], v[148:151], v[172:175], v[120:123]
	v_mfma_f32_16x16x32_bf16 v[108:111], v[128:131], v[184:187], v[108:111]
	v_mfma_f32_16x16x32_bf16 v[104:107], v[148:151], v[184:187], v[104:107]
	v_mfma_f32_16x16x32_bf16 v[92:95], v[128:131], v[206:209], v[92:95]
	v_mfma_f32_16x16x32_bf16 v[88:91], v[148:151], v[206:209], v[88:91]
	v_mfma_f32_16x16x32_bf16 v[76:79], v[128:131], v[214:217], v[76:79]
	v_mfma_f32_16x16x32_bf16 v[72:75], v[148:151], v[214:217], v[72:75]
	v_mfma_f32_16x16x32_bf16 v[124:127], v[132:135], v[180:183], v[124:127]
	v_mfma_f32_16x16x32_bf16 v[120:123], v[152:155], v[180:183], v[120:123]
	v_mfma_f32_16x16x32_bf16 v[108:111], v[132:135], v[188:191], v[108:111]
	v_mfma_f32_16x16x32_bf16 v[104:107], v[152:155], v[188:191], v[104:107]
	v_mfma_f32_16x16x32_bf16 v[92:95], v[132:135], v[210:213], v[92:95]
	v_mfma_f32_16x16x32_bf16 v[88:91], v[152:155], v[210:213], v[88:91]
	v_mfma_f32_16x16x32_bf16 v[76:79], v[132:135], v[218:221], v[76:79]
	v_mfma_f32_16x16x32_bf16 v[72:75], v[152:155], v[218:221], v[72:75]
	s_setprio 0
	s_setprio 1
	v_mfma_f32_16x16x32_bf16 v[116:119], v[156:159], v[172:175], v[116:119]
	v_mfma_f32_16x16x32_bf16 v[112:115], v[164:167], v[172:175], v[112:115]
	v_mfma_f32_16x16x32_bf16 v[100:103], v[156:159], v[184:187], v[100:103]
	v_mfma_f32_16x16x32_bf16 v[96:99], v[164:167], v[184:187], v[96:99]
	v_mfma_f32_16x16x32_bf16 v[84:87], v[156:159], v[206:209], v[84:87]
	v_mfma_f32_16x16x32_bf16 v[80:83], v[164:167], v[206:209], v[80:83]
	v_mfma_f32_16x16x32_bf16 v[68:71], v[156:159], v[214:217], v[68:71]
	v_mfma_f32_16x16x32_bf16 v[64:67], v[164:167], v[214:217], v[64:67]
	v_mfma_f32_16x16x32_bf16 v[116:119], v[160:163], v[180:183], v[116:119]
	v_mfma_f32_16x16x32_bf16 v[112:115], v[168:171], v[180:183], v[112:115]
	v_mfma_f32_16x16x32_bf16 v[100:103], v[160:163], v[188:191], v[100:103]
	v_mfma_f32_16x16x32_bf16 v[96:99], v[168:171], v[188:191], v[96:99]
	v_mfma_f32_16x16x32_bf16 v[84:87], v[160:163], v[210:213], v[84:87]
	v_mfma_f32_16x16x32_bf16 v[80:83], v[168:171], v[210:213], v[80:83]
	s_barrier
; #define PG8_STAGE(bufoff, gbase, voff) do { _Pragma("unroll") for (int _i = 0; _i < 2; ++_i) \
;         __builtin_amdgcn_global_load_lds((const unsigned*)((const char*)(gbase) + (voff)[_i]), (PG8_LAS unsigned*)(lds + (bufoff) + ldsw + _i * 8192), 16, 0, 0); } while (0)
; #define PG8_LDA(dst, b, h) do { _Pragma("unroll") for (int m = 0; m < 4; ++m) _Pragma("unroll") for (int k = 0; k < 2; ++k) dst[m][k] = *(const PG8_LAS bf16x8*)(lds + PG8_SA(b, h) + aoff + m * 2048 + k * 1024); } while (0)
; #define PG8_LDB(dst, b, h) do { _Pragma("unroll") for (int n = 0; n < 2; ++n) _Pragma("unroll") for (int k = 0; k < 2; ++k) dst[n][k] = *(const PG8_LAS bf16x8*)(lds + PG8_SB(b, h) + boff + n * 2048 + k * 1024); } while (0)
; #define PG8_MMA(ai, bj, At, Bt) do { __builtin_amdgcn_s_setprio(1); _Pragma("unroll") for (int m = 0; m < 4; ++m) _Pragma("unroll") for (int n = 0; n < 2; ++n) _Pragma("unroll") for (int k = 0; k < 2; ++k) \
;         acc[ai][bj][m][n] = __builtin_amdgcn_mfma_f32_16x16x32_bf16(Bt[n][k], At[m][k], acc[ai][bj][m][n], 0, 0, 0); __builtin_amdgcn_s_setprio(0); } while (0)
; #define PG8_WAIT_V(n) asm volatile("s_waitcnt vmcnt(" #n ")" ::: "memory")
; #define PG8_WAIT_L(n) asm volatile("s_waitcnt lgkmcnt(" #n ")" ::: "memory")
; #define PG8_BAR __builtin_amdgcn_s_barrier()
; #define PG8_SCHED __builtin_amdgcn_sched_barrier(0)
; template <class Epi, class Sched, bool ALIGN_EPI = false, bool SP2 = false>
; __device__ __forceinline__ void gemm_phase(PG8_LAS unsigned char* lds, const Gemm g, const Sched& S, const Epi& E) {
;     ...
;             PG8_WAIT_V(8); PG8_WAIT_L(0); PG8_BAR; PG8_MMA(0, 0, At, B0); PG8_MMA(0, 1, At, B1); PG8_BAR; PG8_SCHED;
;             PG8_LDA(At, 0, 1); PG8_STAGE(PG8_SB(0, 0), b2, voffB); PG8_STAGE(PG8_SB(0, 1), b2 + hstep, voffB); PG8_STAGE(PG8_SA(0, 0), a2, voffA);
;             PG8_WAIT_V(8); PG8_WAIT_L(0); PG8_BAR; PG8_MMA(1, 0, At, B0); PG8_MMA(1, 1, At, B1); PG8_BAR; PG8_SCHED;
;             PG8_LDB(B0, 1, 0); PG8_LDB(B1, 1, 1); PG8_SCHED; PG8_LDA(At, 1, 0); PG8_STAGE(PG8_SA(0, 1), a2 + hstep, voffA);
	v_mfma_f32_16x16x32_bf16 v[68:71], v[160:163], v[218:221], v[68:71]
	v_mfma_f32_16x16x32_bf16 v[64:67], v[168:171], v[218:221], v[64:67]
	s_setprio 0
	s_add_i32 s43, s43, s39
	v_lshl_add_u64 v[194:195], s[12:13], 0, v[138:139]
	s_mov_b32 m0, s43
	ds_read_b128 v[172:175], v179 offset:16384
	ds_read_b128 v[180:183], v179 offset:17408
	ds_read_b128 v[184:187], v179 offset:18432
	ds_read_b128 v[188:191], v179 offset:19456
	ds_read_b128 v[206:209], v179 offset:20480
	ds_read_b128 v[210:213], v179 offset:21504
	ds_read_b128 v[214:217], v179 offset:22528
	ds_read_b128 v[218:221], v179 offset:23552
	global_load_lds_dwordx4 v[194:195], off
	s_add_i32 m0, s43, 0x2000
	s_add_u32 s86, s12, 0x80000
	v_lshl_add_u64 v[196:197], s[12:13], 0, v[142:143]
	s_addc_u32 s87, s13, 0
	s_add_i32 s43, s65, s39
	global_load_lds_dwordx4 v[196:197], off
	v_lshl_add_u64 v[202:203], s[86:87], 0, v[138:139]
	s_mov_b32 m0, s43
	v_lshl_add_u64 v[204:205], s[14:15], 0, v[140:141]
	global_load_lds_dwordx4 v[202:203], off
	s_add_i32 m0, s43, 0x2000
	v_lshl_add_u64 v[202:203], s[86:87], 0, v[142:143]
	global_load_lds_dwordx4 v[202:203], off
	s_mov_b32 m0, s74
	v_lshl_add_u64 v[202:203], s[14:15], 0, v[136:137]
	global_load_lds_dwordx4 v[202:203], off
	s_mov_b32 m0, s75
	s_nop 0
	global_load_lds_dwordx4 v[204:205], off
	s_waitcnt vmcnt(8)
	s_waitcnt lgkmcnt(0)
	s_barrier
	s_setprio 1
	s_waitcnt lgkmcnt(0)
	v_mfma_f32_16x16x32_bf16 v[60:63], v[128:131], v[172:175], v[60:63]
	v_mfma_f32_16x16x32_bf16 v[56:59], v[148:151], v[172:175], v[56:59]
	v_mfma_f32_16x16x32_bf16 v[44:47], v[128:131], v[184:187], v[44:47]
	v_mfma_f32_16x16x32_bf16 v[40:43], v[148:151], v[184:187], v[40:43]
	v_mfma_f32_16x16x32_bf16 v[28:31], v[128:131], v[206:209], v[28:31]
	v_mfma_f32_16x16x32_bf16 v[24:27], v[148:151], v[206:209], v[24:27]
	v_mfma_f32_16x16x32_bf16 v[12:15], v[128:131], v[214:217], v[12:15]
	v_mfma_f32_16x16x32_bf16 v[8:11], v[148:151], v[214:217], v[8:11]
	v_mfma_f32_16x16x32_bf16 v[60:63], v[132:135], v[180:183], v[60:63]
	v_mfma_f32_16x16x32_bf16 v[56:59], v[152:155], v[180:183], v[56:59]
	v_mfma_f32_16x16x32_bf16 v[44:47], v[132:135], v[188:191], v[44:47]
	v_mfma_f32_16x16x32_bf16 v[40:43], v[152:155], v[188:191], v[40:43]
	v_mfma_f32_16x16x32_bf16 v[28:31], v[132:135], v[210:213], v[28:31]
	v_mfma_f32_16x16x32_bf16 v[24:27], v[152:155], v[210:213], v[24:27]
	v_mfma_f32_16x16x32_bf16 v[12:15], v[132:135], v[218:221], v[12:15]
	v_mfma_f32_16x16x32_bf16 v[8:11], v[152:155], v[218:221], v[8:11]
	s_setprio 0
	s_setprio 1
	v_mfma_f32_16x16x32_bf16 v[52:55], v[156:159], v[172:175], v[52:55]
	v_mfma_f32_16x16x32_bf16 v[48:51], v[164:167], v[172:175], v[48:51]
	v_mfma_f32_16x16x32_bf16 v[36:39], v[156:159], v[184:187], v[36:39]
	v_mfma_f32_16x16x32_bf16 v[32:35], v[164:167], v[184:187], v[32:35]
	v_mfma_f32_16x16x32_bf16 v[20:23], v[156:159], v[206:209], v[20:23]
	v_mfma_f32_16x16x32_bf16 v[16:19], v[164:167], v[206:209], v[16:19]
	v_mfma_f32_16x16x32_bf16 v[4:7], v[156:159], v[214:217], v[4:7]
	v_mfma_f32_16x16x32_bf16 v[0:3], v[164:167], v[214:217], v[0:3]
	v_mfma_f32_16x16x32_bf16 v[52:55], v[160:163], v[180:183], v[52:55]
	v_mfma_f32_16x16x32_bf16 v[48:51], v[168:171], v[180:183], v[48:51]
	v_mfma_f32_16x16x32_bf16 v[36:39], v[160:163], v[188:191], v[36:39]
	v_mfma_f32_16x16x32_bf16 v[32:35], v[168:171], v[188:191], v[32:35]
	v_mfma_f32_16x16x32_bf16 v[20:23], v[160:163], v[210:213], v[20:23]
	v_mfma_f32_16x16x32_bf16 v[16:19], v[168:171], v[210:213], v[16:19]
	s_barrier
	v_mfma_f32_16x16x32_bf16 v[4:7], v[160:163], v[218:221], v[4:7]
	v_mfma_f32_16x16x32_bf16 v[0:3], v[168:171], v[218:221], v[0:3]
	s_setprio 0
	s_add_i32 s43, 0, 0x18000
	s_add_i32 s65, 0, 0x1c000
	v_add_u32_e32 v152, 0x18000, v178
	v_add_u32_e32 v168, 0x1c000, v178
	ds_read_b128 v[128:131], v152
	ds_read_b128 v[132:135], v152 offset:1024
	ds_read_b128 v[148:151], v152 offset:2048
	ds_read_b128 v[152:155], v152 offset:3072
	ds_read_b128 v[156:159], v168
	ds_read_b128 v[160:163], v168 offset:1024
	ds_read_b128 v[164:167], v168 offset:2048
	ds_read_b128 v[168:171], v168 offset:3072
	s_add_u32 s14, s14, 0x80000
	s_addc_u32 s15, s15, 0
	s_mov_b32 m0, s76
	v_lshl_add_u64 v[232:233], s[14:15], 0, v[136:137]
	ds_read_b128 v[172:175], v179 offset:32768
	ds_read_b128 v[180:183], v179 offset:33792
	ds_read_b128 v[184:187], v179 offset:34816
	ds_read_b128 v[188:191], v179 offset:35840
	ds_read_b128 v[206:209], v179 offset:36864
	ds_read_b128 v[210:213], v179 offset:37888
	ds_read_b128 v[214:217], v179 offset:38912
	ds_read_b128 v[218:221], v179 offset:39936
	global_load_lds_dwordx4 v[232:233], off
	s_mov_b32 m0, s77
	v_lshl_add_u64 v[232:233], s[14:15], 0, v[140:141]
	global_load_lds_dwordx4 v[232:233], off
	s_waitcnt vmcnt(8)
	s_waitcnt lgkmcnt(0)
	s_barrier
; #define PG8_STAGE(bufoff, gbase, voff) do { _Pragma("unroll") for (int _i = 0; _i < 2; ++_i) \
;         __builtin_amdgcn_global_load_lds((const unsigned*)((const char*)(gbase) + (voff)[_i]), (PG8_LAS unsigned*)(lds + (bufoff) + ldsw + _i * 8192), 16, 0, 0); } while (0)
; #define PG8_LDA(dst, b, h) do { _Pragma("unroll") for (int m = 0; m < 4; ++m) _Pragma("unroll") for (int k = 0; k < 2; ++k) dst[m][k] = *(const PG8_LAS bf16x8*)(lds + PG8_SA(b, h) + aoff + m * 2048 + k * 1024); } while (0)
; #define PG8_MMA(ai, bj, At, Bt) do { __builtin_amdgcn_s_setprio(1); _Pragma("unroll") for (int m = 0; m < 4; ++m) _Pragma("unroll") for (int n = 0; n < 2; ++n) _Pragma("unroll") for (int k = 0; k < 2; ++k) \
;         acc[ai][bj][m][n] = __builtin_amdgcn_mfma_f32_16x16x32_bf16(Bt[n][k], At[m][k], acc[ai][bj][m][n], 0, 0, 0); __builtin_amdgcn_s_setprio(0); } while (0)
; #define PG8_WAIT_V(n) asm volatile("s_waitcnt vmcnt(" #n ")" ::: "memory")
; #define PG8_WAIT_L(n) asm volatile("s_waitcnt lgkmcnt(" #n ")" ::: "memory")
; #define PG8_BAR __builtin_amdgcn_s_barrier()
; #define PG8_SCHED __builtin_amdgcn_sched_barrier(0)
; template <class Epi, class Sched, bool ALIGN_EPI = false, bool SP2 = false>
; __device__ __forceinline__ void gemm_phase(PG8_LAS unsigned char* lds, const Gemm g, const Sched& S, const Epi& E) {
;     ...
;             PG8_WAIT_V(8); PG8_WAIT_L(0); PG8_BAR; PG8_MMA(0, 0, At, B0); PG8_MMA(0, 1, At, B1); PG8_BAR; PG8_SCHED;
;             PG8_LDA(At, 1, 1); PG8_STAGE(PG8_SB(1, 0), b3, voffB); PG8_STAGE(PG8_SB(1, 1), b3 + hstep, voffB); PG8_STAGE(PG8_SA(1, 0), a3, voffA);
;             PG8_WAIT_V(8); PG8_WAIT_L(0); PG8_BAR; PG8_MMA(1, 0, At, B0); PG8_MMA(1, 1, At, B1); PG8_BAR; PG8_SCHED;
;     ...
;         if constexpr (ALIGN_EPI) { if (wr == 0) PG8_BAR; }
	s_setprio 1
	s_waitcnt lgkmcnt(0)
	v_mfma_f32_16x16x32_bf16 v[124:127], v[128:131], v[172:175], v[124:127]
	v_mfma_f32_16x16x32_bf16 v[120:123], v[148:151], v[172:175], v[120:123]
	v_mfma_f32_16x16x32_bf16 v[108:111], v[128:131], v[184:187], v[108:111]
	v_mfma_f32_16x16x32_bf16 v[104:107], v[148:151], v[184:187], v[104:107]
	v_mfma_f32_16x16x32_bf16 v[92:95], v[128:131], v[206:209], v[92:95]
	v_mfma_f32_16x16x32_bf16 v[88:91], v[148:151], v[206:209], v[88:91]
	v_mfma_f32_16x16x32_bf16 v[76:79], v[128:131], v[214:217], v[76:79]
	v_mfma_f32_16x16x32_bf16 v[72:75], v[148:151], v[214:217], v[72:75]
	v_mfma_f32_16x16x32_bf16 v[124:127], v[132:135], v[180:183], v[124:127]
	v_mfma_f32_16x16x32_bf16 v[120:123], v[152:155], v[180:183], v[120:123]
	v_mfma_f32_16x16x32_bf16 v[108:111], v[132:135], v[188:191], v[108:111]
	v_mfma_f32_16x16x32_bf16 v[104:107], v[152:155], v[188:191], v[104:107]
	v_mfma_f32_16x16x32_bf16 v[92:95], v[132:135], v[210:213], v[92:95]
	v_mfma_f32_16x16x32_bf16 v[88:91], v[152:155], v[210:213], v[88:91]
	v_mfma_f32_16x16x32_bf16 v[76:79], v[132:135], v[218:221], v[76:79]
	v_mfma_f32_16x16x32_bf16 v[72:75], v[152:155], v[218:221], v[72:75]
	s_setprio 0
	s_setprio 1
	v_mfma_f32_16x16x32_bf16 v[116:119], v[156:159], v[172:175], v[116:119]
	v_mfma_f32_16x16x32_bf16 v[112:115], v[164:167], v[172:175], v[112:115]
	v_mfma_f32_16x16x32_bf16 v[100:103], v[156:159], v[184:187], v[100:103]
	v_mfma_f32_16x16x32_bf16 v[96:99], v[164:167], v[184:187], v[96:99]
	v_mfma_f32_16x16x32_bf16 v[84:87], v[156:159], v[206:209], v[84:87]
	v_mfma_f32_16x16x32_bf16 v[80:83], v[164:167], v[206:209], v[80:83]
	v_mfma_f32_16x16x32_bf16 v[68:71], v[156:159], v[214:217], v[68:71]
	v_mfma_f32_16x16x32_bf16 v[64:67], v[164:167], v[214:217], v[64:67]
	v_mfma_f32_16x16x32_bf16 v[116:119], v[160:163], v[180:183], v[116:119]
	v_mfma_f32_16x16x32_bf16 v[112:115], v[168:171], v[180:183], v[112:115]
	v_mfma_f32_16x16x32_bf16 v[100:103], v[160:163], v[188:191], v[100:103]
	v_mfma_f32_16x16x32_bf16 v[96:99], v[168:171], v[188:191], v[96:99]
	v_mfma_f32_16x16x32_bf16 v[84:87], v[160:163], v[210:213], v[84:87]
	v_mfma_f32_16x16x32_bf16 v[80:83], v[168:171], v[210:213], v[80:83]
	s_barrier
	v_mfma_f32_16x16x32_bf16 v[68:71], v[160:163], v[218:221], v[68:71]
	v_mfma_f32_16x16x32_bf16 v[64:67], v[168:171], v[218:221], v[64:67]
	s_setprio 0
	s_add_i32 s14, s43, s39
	v_lshl_add_u64 v[194:195], v[194:195], 0, s[16:17]
	s_mov_b32 m0, s14
	ds_read_b128 v[172:175], v179 offset:49152
	ds_read_b128 v[180:183], v179 offset:50176
	ds_read_b128 v[184:187], v179 offset:51200
	ds_read_b128 v[188:191], v179 offset:52224
	ds_read_b128 v[206:209], v179 offset:53248
	ds_read_b128 v[210:213], v179 offset:54272
	ds_read_b128 v[214:217], v179 offset:55296
	ds_read_b128 v[218:221], v179 offset:56320
	global_load_lds_dwordx4 v[194:195], off
	s_add_i32 m0, s14, 0x2000
	s_add_u32 s12, s12, 0x80080
	v_lshl_add_u64 v[194:195], v[196:197], 0, s[16:17]
	s_addc_u32 s13, s13, 0
	s_add_i32 s14, s65, s39
	global_load_lds_dwordx4 v[194:195], off
	s_mov_b32 m0, s14
	v_lshl_add_u64 v[194:195], s[12:13], 0, v[138:139]
	global_load_lds_dwordx4 v[194:195], off
	s_add_i32 m0, s14, 0x2000
	v_lshl_add_u64 v[194:195], s[12:13], 0, v[142:143]
	global_load_lds_dwordx4 v[194:195], off
	s_mov_b32 m0, s80
	v_lshl_add_u64 v[194:195], v[202:203], 0, s[16:17]
	global_load_lds_dwordx4 v[194:195], off
	s_mov_b32 m0, s81
	v_lshl_add_u64 v[194:195], v[204:205], 0, s[16:17]
	global_load_lds_dwordx4 v[194:195], off
	s_waitcnt vmcnt(8)
	s_waitcnt lgkmcnt(0)
	s_barrier
	s_setprio 1
	s_waitcnt lgkmcnt(0)
	v_mfma_f32_16x16x32_bf16 v[60:63], v[128:131], v[172:175], v[60:63]
	v_mfma_f32_16x16x32_bf16 v[56:59], v[148:151], v[172:175], v[56:59]
	v_mfma_f32_16x16x32_bf16 v[44:47], v[128:131], v[184:187], v[44:47]
	v_mfma_f32_16x16x32_bf16 v[40:43], v[148:151], v[184:187], v[40:43]
	v_mfma_f32_16x16x32_bf16 v[28:31], v[128:131], v[206:209], v[28:31]
	v_mfma_f32_16x16x32_bf16 v[24:27], v[148:151], v[206:209], v[24:27]
	v_mfma_f32_16x16x32_bf16 v[12:15], v[128:131], v[214:217], v[12:15]
	v_mfma_f32_16x16x32_bf16 v[8:11], v[148:151], v[214:217], v[8:11]
	v_mfma_f32_16x16x32_bf16 v[60:63], v[132:135], v[180:183], v[60:63]
	v_mfma_f32_16x16x32_bf16 v[56:59], v[152:155], v[180:183], v[56:59]
	v_mfma_f32_16x16x32_bf16 v[44:47], v[132:135], v[188:191], v[44:47]
	v_mfma_f32_16x16x32_bf16 v[40:43], v[152:155], v[188:191], v[40:43]
	v_mfma_f32_16x16x32_bf16 v[28:31], v[132:135], v[210:213], v[28:31]
	v_mfma_f32_16x16x32_bf16 v[24:27], v[152:155], v[210:213], v[24:27]
	v_mfma_f32_16x16x32_bf16 v[12:15], v[132:135], v[218:221], v[12:15]
	v_mfma_f32_16x16x32_bf16 v[8:11], v[152:155], v[218:221], v[8:11]
	s_setprio 0
	s_setprio 1
	v_mfma_f32_16x16x32_bf16 v[52:55], v[156:159], v[172:175], v[52:55]
	v_mfma_f32_16x16x32_bf16 v[48:51], v[164:167], v[172:175], v[48:51]
	v_mfma_f32_16x16x32_bf16 v[36:39], v[156:159], v[184:187], v[36:39]
	v_mfma_f32_16x16x32_bf16 v[32:35], v[164:167], v[184:187], v[32:35]
	v_mfma_f32_16x16x32_bf16 v[20:23], v[156:159], v[206:209], v[20:23]
	v_mfma_f32_16x16x32_bf16 v[16:19], v[164:167], v[206:209], v[16:19]
	v_mfma_f32_16x16x32_bf16 v[4:7], v[156:159], v[214:217], v[4:7]
	v_mfma_f32_16x16x32_bf16 v[0:3], v[164:167], v[214:217], v[0:3]
	v_mfma_f32_16x16x32_bf16 v[52:55], v[160:163], v[180:183], v[52:55]
	v_mfma_f32_16x16x32_bf16 v[48:51], v[168:171], v[180:183], v[48:51]
	v_mfma_f32_16x16x32_bf16 v[36:39], v[160:163], v[188:191], v[36:39]
	v_mfma_f32_16x16x32_bf16 v[32:35], v[168:171], v[188:191], v[32:35]
	v_mfma_f32_16x16x32_bf16 v[20:23], v[160:163], v[210:213], v[20:23]
	v_mfma_f32_16x16x32_bf16 v[16:19], v[168:171], v[210:213], v[16:19]
	s_barrier
	v_mfma_f32_16x16x32_bf16 v[4:7], v[160:163], v[218:221], v[4:7]
	v_mfma_f32_16x16x32_bf16 v[0:3], v[168:171], v[218:221], v[0:3]
	s_setprio 0
	s_add_i32 s42, s42, 2
	s_add_u32 s0, s0, 0x100
	s_addc_u32 s1, s1, 0
	s_add_u32 s34, s34, 0x100
	s_addc_u32 s41, s41, 0
	s_cmp_gt_u32 s42, 29
	s_cbranch_scc0 .LBB0_129
	s_and_b64 vcc, exec, s[62:63]
	s_cbranch_vccz .LBB0_132
	s_barrier

; #define PG8_STAGE(bufoff, gbase, voff) do { _Pragma("unroll") for (int _i = 0; _i < 2; ++_i) \
;         __builtin_amdgcn_global_load_lds((const unsigned*)((const char*)(gbase) + (voff)[_i]), (PG8_LAS unsigned*)(lds + (bufoff) + ldsw + _i * 8192), 16, 0, 0); } while (0)
; #define PG8_LDA(dst, b, h) do { _Pragma("unroll") for (int m = 0; m < 4; ++m) _Pragma("unroll") for (int k = 0; k < 2; ++k) dst[m][k] = *(const PG8_LAS bf16x8*)(lds + PG8_SA(b, h) + aoff + m * 2048 + k * 1024); } while (0)
; #define PG8_LDB(dst, b, h) do { _Pragma("unroll") for (int n = 0; n < 2; ++n) _Pragma("unroll") for (int k = 0; k < 2; ++k) dst[n][k] = *(const PG8_LAS bf16x8*)(lds + PG8_SB(b, h) + boff + n * 2048 + k * 1024); } while (0)
; #define PG8_WAIT_V(n) asm volatile("s_waitcnt vmcnt(" #n ")" ::: "memory")
; #define PG8_WAIT_L(n) asm volatile("s_waitcnt lgkmcnt(" #n ")" ::: "memory")
; #define PG8_BAR __builtin_amdgcn_s_barrier()
; #define PG8_SCHED __builtin_amdgcn_sched_barrier(0)
; template <class Epi, class Sched, bool ALIGN_EPI = false, bool SP2 = false>
; __device__ __forceinline__ void gemm_phase(PG8_LAS unsigned char* lds, const Gemm g, const Sched& S, const Epi& E) {
;     ...
;         const char* nA = has_next ? (const char*)g.A + (size_t)nxt.pm * tstep : cA; const char* nB = has_next ? (const char*)g.Bt + (size_t)nxt.pn * tstep : cB;
;         for (int t = 0; t < nt; t += 2) {
;             if constexpr (Epi::MID_HOOK) { if (t == Epi::MID_T) E.mid(acc, cur, wr, wc, fr, fq); }
;             const bool last = (t == nt - 2);
;             const char* a1 = cA + (size_t)(t + 1) * kstep;
;             const char* a2 = last ? nA : cA + (size_t)(t + 2) * kstep; const char* b2 = last ? nB : cB + (size_t)(t + 2) * kstep;
;             const char* a3 = a2 + kstep; const char* b3 = b2 + kstep;
;             if (last && has_next) S.a_ready(nxt);
;             if constexpr (SP2) {
;             PG8_LDB(B0, 0, 0); PG8_LDB(B1, 0, 1); PG8_SCHED; PG8_LDA(At, 0, 0); PG8_STAGE(PG8_SA(1, 1), a1 + hstep, voffA);
;             PG8_WAIT_V(8); PG8_WAIT_L(0); PG8_BAR; PG8_MMA(0, 0, At, B0); PG8_MMA(0, 1, At, B1); PG8_BAR; PG8_SCHED;
;             PG8_LDA(At, 0, 1); PG8_STAGE(PG8_SB(0, 0), b2, voffB); PG8_STAGE(PG8_SB(0, 1), b2 + hstep, voffB); PG8_STAGE(PG8_SA(0, 0), a2, voffA);
;             PG8_WAIT_V(8); PG8_WAIT_L(0); PG8_BAR; PG8_MMA(1, 0, At, B0); PG8_MMA(1, 1, At, B1); PG8_BAR; PG8_SCHED;
.LBB0_634:
	s_ashr_i32 s15, s14, 31
	s_lshl_b64 s[18:19], s[14:15], 20
	s_add_u32 s18, s45, s18
	s_addc_u32 s19, s46, s19
	s_and_b64 s[30:31], s[0:1], exec
	s_cselect_b32 s15, s19, s37
	s_cselect_b32 s61, s18, s36
	s_ashr_i32 s13, s12, 31
	s_lshl_b64 s[30:31], s[12:13], 20
	s_add_u32 s30, s34, s30
	s_addc_u32 s31, s44, s31
	s_and_b64 s[42:43], s[0:1], exec
	s_cselect_b32 s13, s31, s39
	s_cselect_b32 s62, s30, s38
	s_add_u32 s36, s36, 0x80080
	s_addc_u32 s37, s37, 0
	s_add_u32 s63, s38, 0x100
	s_addc_u32 s64, s39, 0
	s_mov_b32 s65, -2
	s_waitcnt lgkmcnt(0)
	v_lshl_add_u64 v[168:169], s[36:37], 0, v[160:161]
	s_add_i32 m0, s2, 0xc000
	global_load_lds_dwordx4 v[168:169], off
	s_add_i32 m0, s2, 0xe000
	v_lshl_add_u64 v[168:169], s[36:37], 0, v[162:163]
	global_load_lds_dwordx4 v[168:169], off
	s_add_u32 s24, s36, 0xfff80080
	s_addc_u32 s25, s37, -1
	s_add_i32 s33, 0, 0x10000
	s_cmp_eq_u32 s65, 28
	s_cselect_b32 s43, s15, s25
	s_cselect_b32 s42, s61, s24
	s_cselect_b32 s39, s13, s64
	s_cselect_b32 s38, s62, s63
	s_add_i32 s24, 0, 0x14000
	s_waitcnt vmcnt(8)
	s_waitcnt lgkmcnt(0)
	s_barrier
	s_setprio 1
	s_waitcnt lgkmcnt(0)
	v_mfma_f32_16x16x32_bf16 v[124:127], v[128:131], v[178:181], 0
	v_mfma_f32_16x16x32_bf16 v[120:123], v[136:139], v[178:181], 0
	v_mfma_f32_16x16x32_bf16 v[108:111], v[128:131], v[186:189], 0
	v_mfma_f32_16x16x32_bf16 v[104:107], v[136:139], v[186:189], 0
	v_mfma_f32_16x16x32_bf16 v[92:95], v[128:131], v[202:205], 0
	v_mfma_f32_16x16x32_bf16 v[88:91], v[136:139], v[202:205], 0
	v_mfma_f32_16x16x32_bf16 v[76:79], v[128:131], v[210:213], 0
	v_mfma_f32_16x16x32_bf16 v[72:75], v[136:139], v[210:213], 0
	v_mfma_f32_16x16x32_bf16 v[124:127], v[132:135], v[182:185], v[124:127]
	v_mfma_f32_16x16x32_bf16 v[120:123], v[140:143], v[182:185], v[120:123]
	v_mfma_f32_16x16x32_bf16 v[108:111], v[132:135], v[194:197], v[108:111]
	v_mfma_f32_16x16x32_bf16 v[104:107], v[140:143], v[194:197], v[104:107]
	v_mfma_f32_16x16x32_bf16 v[92:95], v[132:135], v[206:209], v[92:95]
	v_mfma_f32_16x16x32_bf16 v[88:91], v[140:143], v[206:209], v[88:91]
	v_mfma_f32_16x16x32_bf16 v[76:79], v[132:135], v[214:217], v[76:79]
	v_mfma_f32_16x16x32_bf16 v[72:75], v[140:143], v[214:217], v[72:75]
	s_setprio 0
	s_setprio 1
	v_mfma_f32_16x16x32_bf16 v[116:119], v[144:147], v[178:181], 0
	v_mfma_f32_16x16x32_bf16 v[112:115], v[164:167], v[178:181], 0
	v_mfma_f32_16x16x32_bf16 v[100:103], v[144:147], v[186:189], 0
	v_mfma_f32_16x16x32_bf16 v[96:99], v[164:167], v[186:189], 0
	v_mfma_f32_16x16x32_bf16 v[84:87], v[144:147], v[202:205], 0
	v_mfma_f32_16x16x32_bf16 v[80:83], v[164:167], v[202:205], 0
	v_mfma_f32_16x16x32_bf16 v[68:71], v[144:147], v[210:213], 0
	v_mfma_f32_16x16x32_bf16 v[64:67], v[164:167], v[210:213], 0
	v_mfma_f32_16x16x32_bf16 v[116:119], v[148:151], v[182:185], v[116:119]
	v_mfma_f32_16x16x32_bf16 v[112:115], v[174:177], v[182:185], v[112:115]
	v_mfma_f32_16x16x32_bf16 v[100:103], v[148:151], v[194:197], v[100:103]
	v_mfma_f32_16x16x32_bf16 v[96:99], v[174:177], v[194:197], v[96:99]
	v_mfma_f32_16x16x32_bf16 v[84:87], v[148:151], v[206:209], v[84:87]
	v_mfma_f32_16x16x32_bf16 v[80:83], v[174:177], v[206:209], v[80:83]
	s_barrier
	v_mfma_f32_16x16x32_bf16 v[68:71], v[148:151], v[214:217], v[68:71]
	v_mfma_f32_16x16x32_bf16 v[64:67], v[174:177], v[214:217], v[64:67]
	s_setprio 0
	s_add_i32 s25, s33, s47
	v_lshl_add_u64 v[168:169], s[38:39], 0, v[156:157]
	s_mov_b32 m0, s25
	ds_read_b128 v[178:181], v173 offset:16384
	ds_read_b128 v[182:185], v173 offset:17408
	ds_read_b128 v[186:189], v173 offset:18432
	ds_read_b128 v[194:197], v173 offset:19456
	ds_read_b128 v[202:205], v173 offset:20480
	ds_read_b128 v[206:209], v173 offset:21504
	ds_read_b128 v[210:213], v173 offset:22528
	ds_read_b128 v[214:217], v173 offset:23552
	global_load_lds_dwordx4 v[168:169], off
	s_add_i32 m0, s25, 0x2000
	s_add_u32 s66, s38, 0x80000
	v_lshl_add_u64 v[190:191], s[38:39], 0, v[152:153]
	s_addc_u32 s67, s39, 0
	s_add_i32 s24, s24, s47
	global_load_lds_dwordx4 v[190:191], off
	v_lshl_add_u64 v[218:219], s[66:67], 0, v[156:157]
	s_mov_b32 m0, s24
	v_lshl_add_u64 v[220:221], s[42:43], 0, v[154:155]
	global_load_lds_dwordx4 v[218:219], off
	s_add_i32 m0, s24, 0x2000
	v_lshl_add_u64 v[218:219], s[66:67], 0, v[152:153]
	global_load_lds_dwordx4 v[218:219], off
	s_mov_b32 m0, s2
	v_lshl_add_u64 v[218:219], s[42:43], 0, v[158:159]
	global_load_lds_dwordx4 v[218:219], off
	s_mov_b32 m0, s48
	s_nop 0
	global_load_lds_dwordx4 v[220:221], off
	s_waitcnt vmcnt(8)
	s_waitcnt lgkmcnt(0)
	s_barrier
	s_setprio 1
	s_waitcnt lgkmcnt(0)
	v_mfma_f32_16x16x32_bf16 v[60:63], v[128:131], v[178:181], 0
	v_mfma_f32_16x16x32_bf16 v[56:59], v[136:139], v[178:181], 0
	v_mfma_f32_16x16x32_bf16 v[44:47], v[128:131], v[186:189], 0
	v_mfma_f32_16x16x32_bf16 v[40:43], v[136:139], v[186:189], 0
	v_mfma_f32_16x16x32_bf16 v[28:31], v[128:131], v[202:205], 0
	v_mfma_f32_16x16x32_bf16 v[24:27], v[136:139], v[202:205], 0
	v_mfma_f32_16x16x32_bf16 v[12:15], v[128:131], v[210:213], 0
	v_mfma_f32_16x16x32_bf16 v[8:11], v[136:139], v[210:213], 0
	v_mfma_f32_16x16x32_bf16 v[60:63], v[132:135], v[182:185], v[60:63]
	v_mfma_f32_16x16x32_bf16 v[56:59], v[140:143], v[182:185], v[56:59]
	v_mfma_f32_16x16x32_bf16 v[44:47], v[132:135], v[194:197], v[44:47]
	v_mfma_f32_16x16x32_bf16 v[40:43], v[140:143], v[194:197], v[40:43]
	v_mfma_f32_16x16x32_bf16 v[28:31], v[132:135], v[206:209], v[28:31]
	v_mfma_f32_16x16x32_bf16 v[24:27], v[140:143], v[206:209], v[24:27]
	v_mfma_f32_16x16x32_bf16 v[12:15], v[132:135], v[214:217], v[12:15]
	v_mfma_f32_16x16x32_bf16 v[8:11], v[140:143], v[214:217], v[8:11]
	s_setprio 0
	s_setprio 1
	v_mfma_f32_16x16x32_bf16 v[52:55], v[144:147], v[178:181], 0
	v_mfma_f32_16x16x32_bf16 v[48:51], v[164:167], v[178:181], 0
	v_mfma_f32_16x16x32_bf16 v[36:39], v[144:147], v[186:189], 0
	v_mfma_f32_16x16x32_bf16 v[32:35], v[164:167], v[186:189], 0
	v_mfma_f32_16x16x32_bf16 v[20:23], v[144:147], v[202:205], 0
	v_mfma_f32_16x16x32_bf16 v[16:19], v[164:167], v[202:205], 0
	v_mfma_f32_16x16x32_bf16 v[4:7], v[144:147], v[210:213], 0
	v_mfma_f32_16x16x32_bf16 v[0:3], v[164:167], v[210:213], 0
	v_mfma_f32_16x16x32_bf16 v[52:55], v[148:151], v[182:185], v[52:55]
	v_mfma_f32_16x16x32_bf16 v[48:51], v[174:177], v[182:185], v[48:51]
	v_mfma_f32_16x16x32_bf16 v[36:39], v[148:151], v[194:197], v[36:39]
	v_mfma_f32_16x16x32_bf16 v[32:35], v[174:177], v[194:197], v[32:35]
	v_mfma_f32_16x16x32_bf16 v[20:23], v[148:151], v[206:209], v[20:23]
	v_mfma_f32_16x16x32_bf16 v[16:19], v[174:177], v[206:209], v[16:19]
	s_barrier
; #define PG8_STAGE(bufoff, gbase, voff) do { _Pragma("unroll") for (int _i = 0; _i < 2; ++_i) \
;         __builtin_amdgcn_global_load_lds((const unsigned*)((const char*)(gbase) + (voff)[_i]), (PG8_LAS unsigned*)(lds + (bufoff) + ldsw + _i * 8192), 16, 0, 0); } while (0)
; #define PG8_LDA(dst, b, h) do { _Pragma("unroll") for (int m = 0; m < 4; ++m) _Pragma("unroll") for (int k = 0; k < 2; ++k) dst[m][k] = *(const PG8_LAS bf16x8*)(lds + PG8_SA(b, h) + aoff + m * 2048 + k * 1024); } while (0)
; #define PG8_LDB(dst, b, h) do { _Pragma("unroll") for (int n = 0; n < 2; ++n) _Pragma("unroll") for (int k = 0; k < 2; ++k) dst[n][k] = *(const PG8_LAS bf16x8*)(lds + PG8_SB(b, h) + boff + n * 2048 + k * 1024); } while (0)
; #define PG8_MMA(ai, bj, At, Bt) do { __builtin_amdgcn_s_setprio(1); _Pragma("unroll") for (int m = 0; m < 4; ++m) _Pragma("unroll") for (int n = 0; n < 2; ++n) _Pragma("unroll") for (int k = 0; k < 2; ++k) \
;         acc[ai][bj][m][n] = __builtin_amdgcn_mfma_f32_16x16x32_bf16(Bt[n][k], At[m][k], acc[ai][bj][m][n], 0, 0, 0); __builtin_amdgcn_s_setprio(0); } while (0)
; #define PG8_WAIT_V(n) asm volatile("s_waitcnt vmcnt(" #n ")" ::: "memory")
; #define PG8_WAIT_L(n) asm volatile("s_waitcnt lgkmcnt(" #n ")" ::: "memory")
; #define PG8_BAR __builtin_amdgcn_s_barrier()
; #define PG8_SCHED __builtin_amdgcn_sched_barrier(0)
; template <class Epi, class Sched, bool ALIGN_EPI = false, bool SP2 = false>
; __device__ __forceinline__ void gemm_phase(PG8_LAS unsigned char* lds, const Gemm g, const Sched& S, const Epi& E) {
;     ...
;             PG8_WAIT_V(8); PG8_WAIT_L(0); PG8_BAR; PG8_MMA(1, 0, At, B0); PG8_MMA(1, 1, At, B1); PG8_BAR; PG8_SCHED;
;             PG8_LDB(B0, 1, 0); PG8_LDB(B1, 1, 1); PG8_SCHED; PG8_LDA(At, 1, 0); PG8_STAGE(PG8_SA(0, 1), a2 + hstep, voffA);
;             PG8_WAIT_V(8); PG8_WAIT_L(0); PG8_BAR; PG8_MMA(0, 0, At, B0); PG8_MMA(0, 1, At, B1); PG8_BAR; PG8_SCHED;
;             PG8_LDA(At, 1, 1); PG8_STAGE(PG8_SB(1, 0), b3, voffB); PG8_STAGE(PG8_SB(1, 1), b3 + hstep, voffB); PG8_STAGE(PG8_SA(1, 0), a3, voffA);
	v_mfma_f32_16x16x32_bf16 v[4:7], v[148:151], v[214:217], v[4:7]
	v_mfma_f32_16x16x32_bf16 v[0:3], v[174:177], v[214:217], v[0:3]
	s_setprio 0
	s_add_i32 s24, 0, 0x18000
	s_add_i32 s25, 0, 0x1c000
	v_add_u32_e32 v140, 0x18000, v172
	v_add_u32_e32 v174, 0x1c000, v172
	ds_read_b128 v[128:131], v140
	ds_read_b128 v[132:135], v140 offset:1024
	ds_read_b128 v[136:139], v140 offset:2048
	ds_read_b128 v[140:143], v140 offset:3072
	ds_read_b128 v[144:147], v174
	ds_read_b128 v[148:151], v174 offset:1024
	ds_read_b128 v[164:167], v174 offset:2048
	ds_read_b128 v[174:177], v174 offset:3072
	s_add_u32 s42, s42, 0x80000
	s_addc_u32 s43, s43, 0
	s_mov_b32 m0, s49
	v_lshl_add_u64 v[230:231], s[42:43], 0, v[158:159]
	ds_read_b128 v[178:181], v173 offset:32768
	ds_read_b128 v[182:185], v173 offset:33792
	ds_read_b128 v[186:189], v173 offset:34816
	ds_read_b128 v[194:197], v173 offset:35840
	ds_read_b128 v[202:205], v173 offset:36864
	ds_read_b128 v[206:209], v173 offset:37888
	ds_read_b128 v[210:213], v173 offset:38912
	ds_read_b128 v[214:217], v173 offset:39936
	global_load_lds_dwordx4 v[230:231], off
	s_mov_b32 m0, s50
	v_lshl_add_u64 v[230:231], s[42:43], 0, v[154:155]
	global_load_lds_dwordx4 v[230:231], off
	s_waitcnt vmcnt(8)
	s_waitcnt lgkmcnt(0)
	s_barrier
	s_setprio 1
	s_waitcnt lgkmcnt(0)
	v_mfma_f32_16x16x32_bf16 v[124:127], v[128:131], v[178:181], v[124:127]
	v_mfma_f32_16x16x32_bf16 v[120:123], v[136:139], v[178:181], v[120:123]
	v_mfma_f32_16x16x32_bf16 v[108:111], v[128:131], v[186:189], v[108:111]
	v_mfma_f32_16x16x32_bf16 v[104:107], v[136:139], v[186:189], v[104:107]
	v_mfma_f32_16x16x32_bf16 v[92:95], v[128:131], v[202:205], v[92:95]
	v_mfma_f32_16x16x32_bf16 v[88:91], v[136:139], v[202:205], v[88:91]
	v_mfma_f32_16x16x32_bf16 v[76:79], v[128:131], v[210:213], v[76:79]
	v_mfma_f32_16x16x32_bf16 v[72:75], v[136:139], v[210:213], v[72:75]
	v_mfma_f32_16x16x32_bf16 v[124:127], v[132:135], v[182:185], v[124:127]
	v_mfma_f32_16x16x32_bf16 v[120:123], v[140:143], v[182:185], v[120:123]
	v_mfma_f32_16x16x32_bf16 v[108:111], v[132:135], v[194:197], v[108:111]
	v_mfma_f32_16x16x32_bf16 v[104:107], v[140:143], v[194:197], v[104:107]
	v_mfma_f32_16x16x32_bf16 v[92:95], v[132:135], v[206:209], v[92:95]
	v_mfma_f32_16x16x32_bf16 v[88:91], v[140:143], v[206:209], v[88:91]
	v_mfma_f32_16x16x32_bf16 v[76:79], v[132:135], v[214:217], v[76:79]
	v_mfma_f32_16x16x32_bf16 v[72:75], v[140:143], v[214:217], v[72:75]
	s_setprio 0
	s_setprio 1
	v_mfma_f32_16x16x32_bf16 v[116:119], v[144:147], v[178:181], v[116:119]
	v_mfma_f32_16x16x32_bf16 v[112:115], v[164:167], v[178:181], v[112:115]
	v_mfma_f32_16x16x32_bf16 v[100:103], v[144:147], v[186:189], v[100:103]
	v_mfma_f32_16x16x32_bf16 v[96:99], v[164:167], v[186:189], v[96:99]
	v_mfma_f32_16x16x32_bf16 v[84:87], v[144:147], v[202:205], v[84:87]
	v_mfma_f32_16x16x32_bf16 v[80:83], v[164:167], v[202:205], v[80:83]
	v_mfma_f32_16x16x32_bf16 v[68:71], v[144:147], v[210:213], v[68:71]
	v_mfma_f32_16x16x32_bf16 v[64:67], v[164:167], v[210:213], v[64:67]
	v_mfma_f32_16x16x32_bf16 v[116:119], v[148:151], v[182:185], v[116:119]
	v_mfma_f32_16x16x32_bf16 v[112:115], v[174:177], v[182:185], v[112:115]
	v_mfma_f32_16x16x32_bf16 v[100:103], v[148:151], v[194:197], v[100:103]
	v_mfma_f32_16x16x32_bf16 v[96:99], v[174:177], v[194:197], v[96:99]
	v_mfma_f32_16x16x32_bf16 v[84:87], v[148:151], v[206:209], v[84:87]
	v_mfma_f32_16x16x32_bf16 v[80:83], v[174:177], v[206:209], v[80:83]
	s_barrier
	v_mfma_f32_16x16x32_bf16 v[68:71], v[148:151], v[214:217], v[68:71]
	v_mfma_f32_16x16x32_bf16 v[64:67], v[174:177], v[214:217], v[64:67]
	s_setprio 0
	s_add_i32 s24, s24, s47
	v_lshl_add_u64 v[168:169], v[168:169], 0, s[16:17]
	s_mov_b32 m0, s24
	ds_read_b128 v[178:181], v173 offset:49152
	ds_read_b128 v[182:185], v173 offset:50176
	ds_read_b128 v[186:189], v173 offset:51200
	ds_read_b128 v[194:197], v173 offset:52224
	ds_read_b128 v[202:205], v173 offset:53248
	ds_read_b128 v[206:209], v173 offset:54272
	ds_read_b128 v[210:213], v173 offset:55296
	ds_read_b128 v[214:217], v173 offset:56320
	global_load_lds_dwordx4 v[168:169], off
	s_add_i32 m0, s24, 0x2000
	s_add_u32 s38, s38, 0x80080
	v_lshl_add_u64 v[168:169], v[190:191], 0, s[16:17]
	s_addc_u32 s39, s39, 0
	s_add_i32 s24, s25, s47
	global_load_lds_dwordx4 v[168:169], off
	s_mov_b32 m0, s24
	v_lshl_add_u64 v[168:169], s[38:39], 0, v[156:157]
	global_load_lds_dwordx4 v[168:169], off
	s_add_i32 m0, s24, 0x2000
	v_lshl_add_u64 v[168:169], s[38:39], 0, v[152:153]
	global_load_lds_dwordx4 v[168:169], off
	s_mov_b32 m0, s55
	v_lshl_add_u64 v[168:169], v[218:219], 0, s[16:17]
	global_load_lds_dwordx4 v[168:169], off
	s_mov_b32 m0, s56
	v_lshl_add_u64 v[168:169], v[220:221], 0, s[16:17]
	global_load_lds_dwordx4 v[168:169], off
	s_waitcnt vmcnt(8)
	s_waitcnt lgkmcnt(0)
	s_barrier
; #define PG8_STAGE(bufoff, gbase, voff) do { _Pragma("unroll") for (int _i = 0; _i < 2; ++_i) \
;         __builtin_amdgcn_global_load_lds((const unsigned*)((const char*)(gbase) + (voff)[_i]), (PG8_LAS unsigned*)(lds + (bufoff) + ldsw + _i * 8192), 16, 0, 0); } while (0)
; #define PG8_LDA(dst, b, h) do { _Pragma("unroll") for (int m = 0; m < 4; ++m) _Pragma("unroll") for (int k = 0; k < 2; ++k) dst[m][k] = *(const PG8_LAS bf16x8*)(lds + PG8_SA(b, h) + aoff + m * 2048 + k * 1024); } while (0)
; #define PG8_LDB(dst, b, h) do { _Pragma("unroll") for (int n = 0; n < 2; ++n) _Pragma("unroll") for (int k = 0; k < 2; ++k) dst[n][k] = *(const PG8_LAS bf16x8*)(lds + PG8_SB(b, h) + boff + n * 2048 + k * 1024); } while (0)
; #define PG8_MMA(ai, bj, At, Bt) do { __builtin_amdgcn_s_setprio(1); _Pragma("unroll") for (int m = 0; m < 4; ++m) _Pragma("unroll") for (int n = 0; n < 2; ++n) _Pragma("unroll") for (int k = 0; k < 2; ++k) \
;         acc[ai][bj][m][n] = __builtin_amdgcn_mfma_f32_16x16x32_bf16(Bt[n][k], At[m][k], acc[ai][bj][m][n], 0, 0, 0); __builtin_amdgcn_s_setprio(0); } while (0)
; #define PG8_WAIT_V(n) asm volatile("s_waitcnt vmcnt(" #n ")" ::: "memory")
; template <class Epi, class Sched, bool ALIGN_EPI = false, bool SP2 = false>
; __device__ __forceinline__ void gemm_phase(PG8_LAS unsigned char* lds, const Gemm g, const Sched& S, const Epi& E) {
;     ...
;             PG8_LDB(B0, 0, 0); PG8_LDB(B1, 0, 1); PG8_SCHED; PG8_LDA(At, 0, 0); PG8_STAGE(PG8_SA(1, 1), a1 + hstep, voffA);
;             PG8_WAIT_V(8); PG8_WAIT_L(0); PG8_BAR; PG8_MMA(0, 0, At, B0); PG8_MMA(0, 1, At, B1); PG8_BAR; PG8_SCHED;
;             PG8_LDA(At, 0, 1); PG8_STAGE(PG8_SB(0, 0), b2, voffB); PG8_STAGE(PG8_SB(0, 1), b2 + hstep, voffB); PG8_STAGE(PG8_SA(0, 0), a2, voffA);
;             PG8_WAIT_V(8); PG8_WAIT_L(0); PG8_BAR; PG8_MMA(1, 0, At, B0); PG8_MMA(1, 1, At, B1); PG8_BAR; PG8_SCHED;
;             PG8_LDB(B0, 1, 0); PG8_LDB(B1, 1, 1); PG8_SCHED; PG8_LDA(At, 1, 0); PG8_STAGE(PG8_SA(0, 1), a2 + hstep, voffA);
;             PG8_WAIT_V(8); PG8_WAIT_L(0); PG8_BAR; PG8_MMA(0, 0, At, B0); PG8_MMA(0, 1, At, B1); PG8_BAR; PG8_SCHED;
;             PG8_LDA(At, 1, 1); PG8_STAGE(PG8_SB(1, 0), b3, voffB); PG8_STAGE(PG8_SB(1, 1), b3 + hstep, voffB); PG8_STAGE(PG8_SA(1, 0), a3, voffA);
;             PG8_WAIT_V(8); PG8_WAIT_L(0); PG8_BAR; PG8_MMA(1, 0, At, B0); PG8_MMA(1, 1, At, B1); PG8_BAR; PG8_SCHED;
	s_setprio 1
	s_waitcnt lgkmcnt(0)
	v_mfma_f32_16x16x32_bf16 v[60:63], v[128:131], v[178:181], v[60:63]
	v_mfma_f32_16x16x32_bf16 v[56:59], v[136:139], v[178:181], v[56:59]
	v_mfma_f32_16x16x32_bf16 v[44:47], v[128:131], v[186:189], v[44:47]
	v_mfma_f32_16x16x32_bf16 v[40:43], v[136:139], v[186:189], v[40:43]
	v_mfma_f32_16x16x32_bf16 v[28:31], v[128:131], v[202:205], v[28:31]
	v_mfma_f32_16x16x32_bf16 v[24:27], v[136:139], v[202:205], v[24:27]
	v_mfma_f32_16x16x32_bf16 v[12:15], v[128:131], v[210:213], v[12:15]
	v_mfma_f32_16x16x32_bf16 v[8:11], v[136:139], v[210:213], v[8:11]
	v_mfma_f32_16x16x32_bf16 v[60:63], v[132:135], v[182:185], v[60:63]
	v_mfma_f32_16x16x32_bf16 v[56:59], v[140:143], v[182:185], v[56:59]
	v_mfma_f32_16x16x32_bf16 v[44:47], v[132:135], v[194:197], v[44:47]
	v_mfma_f32_16x16x32_bf16 v[40:43], v[140:143], v[194:197], v[40:43]
	v_mfma_f32_16x16x32_bf16 v[28:31], v[132:135], v[206:209], v[28:31]
	v_mfma_f32_16x16x32_bf16 v[24:27], v[140:143], v[206:209], v[24:27]
	v_mfma_f32_16x16x32_bf16 v[12:15], v[132:135], v[214:217], v[12:15]
	v_mfma_f32_16x16x32_bf16 v[8:11], v[140:143], v[214:217], v[8:11]
	s_setprio 0
	s_setprio 1
	v_mfma_f32_16x16x32_bf16 v[52:55], v[144:147], v[178:181], v[52:55]
	v_mfma_f32_16x16x32_bf16 v[48:51], v[164:167], v[178:181], v[48:51]
	v_mfma_f32_16x16x32_bf16 v[36:39], v[144:147], v[186:189], v[36:39]
	v_mfma_f32_16x16x32_bf16 v[32:35], v[164:167], v[186:189], v[32:35]
	v_mfma_f32_16x16x32_bf16 v[20:23], v[144:147], v[202:205], v[20:23]
	v_mfma_f32_16x16x32_bf16 v[16:19], v[164:167], v[202:205], v[16:19]
	v_mfma_f32_16x16x32_bf16 v[4:7], v[144:147], v[210:213], v[4:7]
	v_mfma_f32_16x16x32_bf16 v[0:3], v[164:167], v[210:213], v[0:3]
	v_mfma_f32_16x16x32_bf16 v[52:55], v[148:151], v[182:185], v[52:55]
	v_mfma_f32_16x16x32_bf16 v[48:51], v[174:177], v[182:185], v[48:51]
	v_mfma_f32_16x16x32_bf16 v[36:39], v[148:151], v[194:197], v[36:39]
	v_mfma_f32_16x16x32_bf16 v[32:35], v[174:177], v[194:197], v[32:35]
	v_mfma_f32_16x16x32_bf16 v[20:23], v[148:151], v[206:209], v[20:23]
	v_mfma_f32_16x16x32_bf16 v[16:19], v[174:177], v[206:209], v[16:19]
	s_barrier
	v_mfma_f32_16x16x32_bf16 v[4:7], v[148:151], v[214:217], v[4:7]
	v_mfma_f32_16x16x32_bf16 v[0:3], v[174:177], v[214:217], v[0:3]
	s_setprio 0
	s_add_i32 s65, s65, 2
	s_add_u32 s36, s36, 0x100
	s_addc_u32 s37, s37, 0
	s_add_u32 s63, s63, 0x100
	s_addc_u32 s64, s64, 0
	s_cmp_gt_u32 s65, 29
	s_branch .LBB0_635
.LBB0_635:
	v_add_u32_e32 v140, 0x10000, v172
	v_add_u32_e32 v168, 0x14000, v172
	ds_read_b128 v[128:131], v140
	ds_read_b128 v[132:135], v140 offset:1024
	ds_read_b128 v[136:139], v140 offset:2048
	ds_read_b128 v[140:143], v140 offset:3072
	ds_read_b128 v[144:147], v168
	ds_read_b128 v[148:151], v168 offset:1024
	ds_read_b128 v[164:167], v168 offset:2048
	ds_read_b128 v[174:177], v168 offset:3072
	v_lshl_add_u64 v[168:169], s[36:37], 0, v[160:161]
	s_add_i32 m0, s2, 0xc000
	ds_read_b128 v[178:181], v173
	ds_read_b128 v[182:185], v173 offset:1024
	ds_read_b128 v[186:189], v173 offset:2048
	ds_read_b128 v[194:197], v173 offset:3072
	ds_read_b128 v[202:205], v173 offset:4096
	ds_read_b128 v[206:209], v173 offset:5120
	ds_read_b128 v[210:213], v173 offset:6144
	ds_read_b128 v[214:217], v173 offset:7168
	global_load_lds_dwordx4 v[168:169], off
	s_add_i32 m0, s2, 0xe000
	v_lshl_add_u64 v[168:169], s[36:37], 0, v[162:163]
	global_load_lds_dwordx4 v[168:169], off
	s_add_u32 s24, s36, 0xfff80080
	s_addc_u32 s25, s37, -1
	s_add_i32 s33, 0, 0x10000
	s_cmp_eq_u32 s65, 28
	s_cselect_b32 s43, s15, s25
	s_cselect_b32 s42, s61, s24
	s_cselect_b32 s39, s13, s64
	s_cselect_b32 s38, s62, s63
	s_add_i32 s24, 0, 0x14000
	s_waitcnt vmcnt(8)
	s_waitcnt lgkmcnt(0)
	s_barrier
	s_setprio 1
	s_waitcnt lgkmcnt(0)
	v_mfma_f32_16x16x32_bf16 v[124:127], v[128:131], v[178:181], v[124:127]
	v_mfma_f32_16x16x32_bf16 v[120:123], v[136:139], v[178:181], v[120:123]
	v_mfma_f32_16x16x32_bf16 v[108:111], v[128:131], v[186:189], v[108:111]
	v_mfma_f32_16x16x32_bf16 v[104:107], v[136:139], v[186:189], v[104:107]
	v_mfma_f32_16x16x32_bf16 v[92:95], v[128:131], v[202:205], v[92:95]
	v_mfma_f32_16x16x32_bf16 v[88:91], v[136:139], v[202:205], v[88:91]
	v_mfma_f32_16x16x32_bf16 v[76:79], v[128:131], v[210:213], v[76:79]
	v_mfma_f32_16x16x32_bf16 v[72:75], v[136:139], v[210:213], v[72:75]
	v_mfma_f32_16x16x32_bf16 v[124:127], v[132:135], v[182:185], v[124:127]
	v_mfma_f32_16x16x32_bf16 v[120:123], v[140:143], v[182:185], v[120:123]
	v_mfma_f32_16x16x32_bf16 v[108:111], v[132:135], v[194:197], v[108:111]
	v_mfma_f32_16x16x32_bf16 v[104:107], v[140:143], v[194:197], v[104:107]
	v_mfma_f32_16x16x32_bf16 v[92:95], v[132:135], v[206:209], v[92:95]
	v_mfma_f32_16x16x32_bf16 v[88:91], v[140:143], v[206:209], v[88:91]
	v_mfma_f32_16x16x32_bf16 v[76:79], v[132:135], v[214:217], v[76:79]
	v_mfma_f32_16x16x32_bf16 v[72:75], v[140:143], v[214:217], v[72:75]
	s_setprio 0
	s_setprio 1
	v_mfma_f32_16x16x32_bf16 v[116:119], v[144:147], v[178:181], v[116:119]
	v_mfma_f32_16x16x32_bf16 v[112:115], v[164:167], v[178:181], v[112:115]
	v_mfma_f32_16x16x32_bf16 v[100:103], v[144:147], v[186:189], v[100:103]
	v_mfma_f32_16x16x32_bf16 v[96:99], v[164:167], v[186:189], v[96:99]
	v_mfma_f32_16x16x32_bf16 v[84:87], v[144:147], v[202:205], v[84:87]
	v_mfma_f32_16x16x32_bf16 v[80:83], v[164:167], v[202:205], v[80:83]
	v_mfma_f32_16x16x32_bf16 v[68:71], v[144:147], v[210:213], v[68:71]
	v_mfma_f32_16x16x32_bf16 v[64:67], v[164:167], v[210:213], v[64:67]
	v_mfma_f32_16x16x32_bf16 v[116:119], v[148:151], v[182:185], v[116:119]
	v_mfma_f32_16x16x32_bf16 v[112:115], v[174:177], v[182:185], v[112:115]
	v_mfma_f32_16x16x32_bf16 v[100:103], v[148:151], v[194:197], v[100:103]
	v_mfma_f32_16x16x32_bf16 v[96:99], v[174:177], v[194:197], v[96:99]
	v_mfma_f32_16x16x32_bf16 v[84:87], v[148:151], v[206:209], v[84:87]
	v_mfma_f32_16x16x32_bf16 v[80:83], v[174:177], v[206:209], v[80:83]
	s_barrier
; #define PG8_STAGE(bufoff, gbase, voff) do { _Pragma("unroll") for (int _i = 0; _i < 2; ++_i) \
;         __builtin_amdgcn_global_load_lds((const unsigned*)((const char*)(gbase) + (voff)[_i]), (PG8_LAS unsigned*)(lds + (bufoff) + ldsw + _i * 8192), 16, 0, 0); } while (0)
; #define PG8_LDA(dst, b, h) do { _Pragma("unroll") for (int m = 0; m < 4; ++m) _Pragma("unroll") for (int k = 0; k < 2; ++k) dst[m][k] = *(const PG8_LAS bf16x8*)(lds + PG8_SA(b, h) + aoff + m * 2048 + k * 1024); } while (0)
; #define PG8_LDB(dst, b, h) do { _Pragma("unroll") for (int n = 0; n < 2; ++n) _Pragma("unroll") for (int k = 0; k < 2; ++k) dst[n][k] = *(const PG8_LAS bf16x8*)(lds + PG8_SB(b, h) + boff + n * 2048 + k * 1024); } while (0)
; #define PG8_MMA(ai, bj, At, Bt) do { __builtin_amdgcn_s_setprio(1); _Pragma("unroll") for (int m = 0; m < 4; ++m) _Pragma("unroll") for (int n = 0; n < 2; ++n) _Pragma("unroll") for (int k = 0; k < 2; ++k) \
;         acc[ai][bj][m][n] = __builtin_amdgcn_mfma_f32_16x16x32_bf16(Bt[n][k], At[m][k], acc[ai][bj][m][n], 0, 0, 0); __builtin_amdgcn_s_setprio(0); } while (0)
; #define PG8_WAIT_V(n) asm volatile("s_waitcnt vmcnt(" #n ")" ::: "memory")
; #define PG8_WAIT_L(n) asm volatile("s_waitcnt lgkmcnt(" #n ")" ::: "memory")
; #define PG8_BAR __builtin_amdgcn_s_barrier()
; #define PG8_SCHED __builtin_amdgcn_sched_barrier(0)
; template <class Epi, class Sched, bool ALIGN_EPI = false, bool SP2 = false>
; __device__ __forceinline__ void gemm_phase(PG8_LAS unsigned char* lds, const Gemm g, const Sched& S, const Epi& E) {
;     ...
;             PG8_WAIT_V(8); PG8_WAIT_L(0); PG8_BAR; PG8_MMA(0, 0, At, B0); PG8_MMA(0, 1, At, B1); PG8_BAR; PG8_SCHED;
;             PG8_LDA(At, 0, 1); PG8_STAGE(PG8_SB(0, 0), b2, voffB); PG8_STAGE(PG8_SB(0, 1), b2 + hstep, voffB); PG8_STAGE(PG8_SA(0, 0), a2, voffA);
;             PG8_WAIT_V(8); PG8_WAIT_L(0); PG8_BAR; PG8_MMA(1, 0, At, B0); PG8_MMA(1, 1, At, B1); PG8_BAR; PG8_SCHED;
;             PG8_LDB(B0, 1, 0); PG8_LDB(B1, 1, 1); PG8_SCHED; PG8_LDA(At, 1, 0); PG8_STAGE(PG8_SA(0, 1), a2 + hstep, voffA);
	v_mfma_f32_16x16x32_bf16 v[68:71], v[148:151], v[214:217], v[68:71]
	v_mfma_f32_16x16x32_bf16 v[64:67], v[174:177], v[214:217], v[64:67]
	s_setprio 0
	s_add_i32 s25, s33, s47
	v_lshl_add_u64 v[168:169], s[38:39], 0, v[156:157]
	s_mov_b32 m0, s25
	ds_read_b128 v[178:181], v173 offset:16384
	ds_read_b128 v[182:185], v173 offset:17408
	ds_read_b128 v[186:189], v173 offset:18432
	ds_read_b128 v[194:197], v173 offset:19456
	ds_read_b128 v[202:205], v173 offset:20480
	ds_read_b128 v[206:209], v173 offset:21504
	ds_read_b128 v[210:213], v173 offset:22528
	ds_read_b128 v[214:217], v173 offset:23552
	global_load_lds_dwordx4 v[168:169], off
	s_add_i32 m0, s25, 0x2000
	s_add_u32 s66, s38, 0x80000
	v_lshl_add_u64 v[190:191], s[38:39], 0, v[152:153]
	s_addc_u32 s67, s39, 0
	s_add_i32 s24, s24, s47
	global_load_lds_dwordx4 v[190:191], off
	v_lshl_add_u64 v[218:219], s[66:67], 0, v[156:157]
	s_mov_b32 m0, s24
	v_lshl_add_u64 v[220:221], s[42:43], 0, v[154:155]
	global_load_lds_dwordx4 v[218:219], off
	s_add_i32 m0, s24, 0x2000
	v_lshl_add_u64 v[218:219], s[66:67], 0, v[152:153]
	global_load_lds_dwordx4 v[218:219], off
	s_mov_b32 m0, s2
	v_lshl_add_u64 v[218:219], s[42:43], 0, v[158:159]
	global_load_lds_dwordx4 v[218:219], off
	s_mov_b32 m0, s48
	s_nop 0
	global_load_lds_dwordx4 v[220:221], off
	s_waitcnt vmcnt(8)
	s_waitcnt lgkmcnt(0)
	s_barrier
	s_setprio 1
	s_waitcnt lgkmcnt(0)
	v_mfma_f32_16x16x32_bf16 v[60:63], v[128:131], v[178:181], v[60:63]
	v_mfma_f32_16x16x32_bf16 v[56:59], v[136:139], v[178:181], v[56:59]
	v_mfma_f32_16x16x32_bf16 v[44:47], v[128:131], v[186:189], v[44:47]
	v_mfma_f32_16x16x32_bf16 v[40:43], v[136:139], v[186:189], v[40:43]
	v_mfma_f32_16x16x32_bf16 v[28:31], v[128:131], v[202:205], v[28:31]
	v_mfma_f32_16x16x32_bf16 v[24:27], v[136:139], v[202:205], v[24:27]
	v_mfma_f32_16x16x32_bf16 v[12:15], v[128:131], v[210:213], v[12:15]
	v_mfma_f32_16x16x32_bf16 v[8:11], v[136:139], v[210:213], v[8:11]
	v_mfma_f32_16x16x32_bf16 v[60:63], v[132:135], v[182:185], v[60:63]
	v_mfma_f32_16x16x32_bf16 v[56:59], v[140:143], v[182:185], v[56:59]
	v_mfma_f32_16x16x32_bf16 v[44:47], v[132:135], v[194:197], v[44:47]
	v_mfma_f32_16x16x32_bf16 v[40:43], v[140:143], v[194:197], v[40:43]
	v_mfma_f32_16x16x32_bf16 v[28:31], v[132:135], v[206:209], v[28:31]
	v_mfma_f32_16x16x32_bf16 v[24:27], v[140:143], v[206:209], v[24:27]
	v_mfma_f32_16x16x32_bf16 v[12:15], v[132:135], v[214:217], v[12:15]
	v_mfma_f32_16x16x32_bf16 v[8:11], v[140:143], v[214:217], v[8:11]
	s_setprio 0
	s_setprio 1
	v_mfma_f32_16x16x32_bf16 v[52:55], v[144:147], v[178:181], v[52:55]
	v_mfma_f32_16x16x32_bf16 v[48:51], v[164:167], v[178:181], v[48:51]
	v_mfma_f32_16x16x32_bf16 v[36:39], v[144:147], v[186:189], v[36:39]
	v_mfma_f32_16x16x32_bf16 v[32:35], v[164:167], v[186:189], v[32:35]
	v_mfma_f32_16x16x32_bf16 v[20:23], v[144:147], v[202:205], v[20:23]
	v_mfma_f32_16x16x32_bf16 v[16:19], v[164:167], v[202:205], v[16:19]
	v_mfma_f32_16x16x32_bf16 v[4:7], v[144:147], v[210:213], v[4:7]
	v_mfma_f32_16x16x32_bf16 v[0:3], v[164:167], v[210:213], v[0:3]
	v_mfma_f32_16x16x32_bf16 v[52:55], v[148:151], v[182:185], v[52:55]
	v_mfma_f32_16x16x32_bf16 v[48:51], v[174:177], v[182:185], v[48:51]
	v_mfma_f32_16x16x32_bf16 v[36:39], v[148:151], v[194:197], v[36:39]
	v_mfma_f32_16x16x32_bf16 v[32:35], v[174:177], v[194:197], v[32:35]
	v_mfma_f32_16x16x32_bf16 v[20:23], v[148:151], v[206:209], v[20:23]
	v_mfma_f32_16x16x32_bf16 v[16:19], v[174:177], v[206:209], v[16:19]
	s_barrier
	v_mfma_f32_16x16x32_bf16 v[4:7], v[148:151], v[214:217], v[4:7]
	v_mfma_f32_16x16x32_bf16 v[0:3], v[174:177], v[214:217], v[0:3]
	s_setprio 0
	s_add_i32 s24, 0, 0x18000
	s_add_i32 s25, 0, 0x1c000
	v_add_u32_e32 v140, 0x18000, v172
	v_add_u32_e32 v174, 0x1c000, v172
	ds_read_b128 v[128:131], v140
	ds_read_b128 v[132:135], v140 offset:1024
	ds_read_b128 v[136:139], v140 offset:2048
	ds_read_b128 v[140:143], v140 offset:3072
	ds_read_b128 v[144:147], v174
	ds_read_b128 v[148:151], v174 offset:1024
	ds_read_b128 v[164:167], v174 offset:2048
	ds_read_b128 v[174:177], v174 offset:3072
	s_add_u32 s42, s42, 0x80000
	s_addc_u32 s43, s43, 0
	s_mov_b32 m0, s49
	v_lshl_add_u64 v[230:231], s[42:43], 0, v[158:159]
	ds_read_b128 v[178:181], v173 offset:32768
	ds_read_b128 v[182:185], v173 offset:33792
	ds_read_b128 v[186:189], v173 offset:34816
	ds_read_b128 v[194:197], v173 offset:35840
	ds_read_b128 v[202:205], v173 offset:36864
	ds_read_b128 v[206:209], v173 offset:37888
	ds_read_b128 v[210:213], v173 offset:38912
	ds_read_b128 v[214:217], v173 offset:39936
	global_load_lds_dwordx4 v[230:231], off
	s_mov_b32 m0, s50
	v_lshl_add_u64 v[230:231], s[42:43], 0, v[154:155]
	global_load_lds_dwordx4 v[230:231], off
	s_waitcnt vmcnt(8)
	s_waitcnt lgkmcnt(0)
	s_barrier
; #define PG8_STAGE(bufoff, gbase, voff) do { _Pragma("unroll") for (int _i = 0; _i < 2; ++_i) \
;         __builtin_amdgcn_global_load_lds((const unsigned*)((const char*)(gbase) + (voff)[_i]), (PG8_LAS unsigned*)(lds + (bufoff) + ldsw + _i * 8192), 16, 0, 0); } while (0)
; #define PG8_LDA(dst, b, h) do { _Pragma("unroll") for (int m = 0; m < 4; ++m) _Pragma("unroll") for (int k = 0; k < 2; ++k) dst[m][k] = *(const PG8_LAS bf16x8*)(lds + PG8_SA(b, h) + aoff + m * 2048 + k * 1024); } while (0)
; #define PG8_MMA(ai, bj, At, Bt) do { __builtin_amdgcn_s_setprio(1); _Pragma("unroll") for (int m = 0; m < 4; ++m) _Pragma("unroll") for (int n = 0; n < 2; ++n) _Pragma("unroll") for (int k = 0; k < 2; ++k) \
;         acc[ai][bj][m][n] = __builtin_amdgcn_mfma_f32_16x16x32_bf16(Bt[n][k], At[m][k], acc[ai][bj][m][n], 0, 0, 0); __builtin_amdgcn_s_setprio(0); } while (0)
; #define PG8_WAIT_V(n) asm volatile("s_waitcnt vmcnt(" #n ")" ::: "memory")
; #define PG8_WAIT_L(n) asm volatile("s_waitcnt lgkmcnt(" #n ")" ::: "memory")
; #define PG8_BAR __builtin_amdgcn_s_barrier()
; #define PG8_SCHED __builtin_amdgcn_sched_barrier(0)
; template <class Epi, class Sched, bool ALIGN_EPI = false, bool SP2 = false>
; __device__ __forceinline__ void gemm_phase(PG8_LAS unsigned char* lds, const Gemm g, const Sched& S, const Epi& E) {
;     ...
;             PG8_WAIT_V(8); PG8_WAIT_L(0); PG8_BAR; PG8_MMA(0, 0, At, B0); PG8_MMA(0, 1, At, B1); PG8_BAR; PG8_SCHED;
;             PG8_LDA(At, 1, 1); PG8_STAGE(PG8_SB(1, 0), b3, voffB); PG8_STAGE(PG8_SB(1, 1), b3 + hstep, voffB); PG8_STAGE(PG8_SA(1, 0), a3, voffA);
;             PG8_WAIT_V(8); PG8_WAIT_L(0); PG8_BAR; PG8_MMA(1, 0, At, B0); PG8_MMA(1, 1, At, B1); PG8_BAR; PG8_SCHED;
;     ...
;         if constexpr (ALIGN_EPI) { if (wr == 0) PG8_BAR; }
	s_setprio 1
	s_waitcnt lgkmcnt(0)
	v_mfma_f32_16x16x32_bf16 v[124:127], v[128:131], v[178:181], v[124:127]
	v_mfma_f32_16x16x32_bf16 v[120:123], v[136:139], v[178:181], v[120:123]
	v_mfma_f32_16x16x32_bf16 v[108:111], v[128:131], v[186:189], v[108:111]
	v_mfma_f32_16x16x32_bf16 v[104:107], v[136:139], v[186:189], v[104:107]
	v_mfma_f32_16x16x32_bf16 v[92:95], v[128:131], v[202:205], v[92:95]
	v_mfma_f32_16x16x32_bf16 v[88:91], v[136:139], v[202:205], v[88:91]
	v_mfma_f32_16x16x32_bf16 v[76:79], v[128:131], v[210:213], v[76:79]
	v_mfma_f32_16x16x32_bf16 v[72:75], v[136:139], v[210:213], v[72:75]
	v_mfma_f32_16x16x32_bf16 v[124:127], v[132:135], v[182:185], v[124:127]
	v_mfma_f32_16x16x32_bf16 v[120:123], v[140:143], v[182:185], v[120:123]
	v_mfma_f32_16x16x32_bf16 v[108:111], v[132:135], v[194:197], v[108:111]
	v_mfma_f32_16x16x32_bf16 v[104:107], v[140:143], v[194:197], v[104:107]
	v_mfma_f32_16x16x32_bf16 v[92:95], v[132:135], v[206:209], v[92:95]
	v_mfma_f32_16x16x32_bf16 v[88:91], v[140:143], v[206:209], v[88:91]
	v_mfma_f32_16x16x32_bf16 v[76:79], v[132:135], v[214:217], v[76:79]
	v_mfma_f32_16x16x32_bf16 v[72:75], v[140:143], v[214:217], v[72:75]
	s_setprio 0
	s_setprio 1
	v_mfma_f32_16x16x32_bf16 v[116:119], v[144:147], v[178:181], v[116:119]
	v_mfma_f32_16x16x32_bf16 v[112:115], v[164:167], v[178:181], v[112:115]
	v_mfma_f32_16x16x32_bf16 v[100:103], v[144:147], v[186:189], v[100:103]
	v_mfma_f32_16x16x32_bf16 v[96:99], v[164:167], v[186:189], v[96:99]
	v_mfma_f32_16x16x32_bf16 v[84:87], v[144:147], v[202:205], v[84:87]
	v_mfma_f32_16x16x32_bf16 v[80:83], v[164:167], v[202:205], v[80:83]
	v_mfma_f32_16x16x32_bf16 v[68:71], v[144:147], v[210:213], v[68:71]
	v_mfma_f32_16x16x32_bf16 v[64:67], v[164:167], v[210:213], v[64:67]
	v_mfma_f32_16x16x32_bf16 v[116:119], v[148:151], v[182:185], v[116:119]
	v_mfma_f32_16x16x32_bf16 v[112:115], v[174:177], v[182:185], v[112:115]
	v_mfma_f32_16x16x32_bf16 v[100:103], v[148:151], v[194:197], v[100:103]
	v_mfma_f32_16x16x32_bf16 v[96:99], v[174:177], v[194:197], v[96:99]
	v_mfma_f32_16x16x32_bf16 v[84:87], v[148:151], v[206:209], v[84:87]
	v_mfma_f32_16x16x32_bf16 v[80:83], v[174:177], v[206:209], v[80:83]
	s_barrier
	v_mfma_f32_16x16x32_bf16 v[68:71], v[148:151], v[214:217], v[68:71]
	v_mfma_f32_16x16x32_bf16 v[64:67], v[174:177], v[214:217], v[64:67]
	s_setprio 0
	s_add_i32 s24, s24, s47
	v_lshl_add_u64 v[168:169], v[168:169], 0, s[16:17]
	s_mov_b32 m0, s24
	ds_read_b128 v[178:181], v173 offset:49152
	ds_read_b128 v[182:185], v173 offset:50176
	ds_read_b128 v[186:189], v173 offset:51200
	ds_read_b128 v[194:197], v173 offset:52224
	ds_read_b128 v[202:205], v173 offset:53248
	ds_read_b128 v[206:209], v173 offset:54272
	ds_read_b128 v[210:213], v173 offset:55296
	ds_read_b128 v[214:217], v173 offset:56320
	global_load_lds_dwordx4 v[168:169], off
	s_add_i32 m0, s24, 0x2000
	s_add_u32 s38, s38, 0x80080
	v_lshl_add_u64 v[168:169], v[190:191], 0, s[16:17]
	s_addc_u32 s39, s39, 0
	s_add_i32 s24, s25, s47
	global_load_lds_dwordx4 v[168:169], off
	s_mov_b32 m0, s24
	v_lshl_add_u64 v[168:169], s[38:39], 0, v[156:157]
	global_load_lds_dwordx4 v[168:169], off
	s_add_i32 m0, s24, 0x2000
	v_lshl_add_u64 v[168:169], s[38:39], 0, v[152:153]
	global_load_lds_dwordx4 v[168:169], off
	s_mov_b32 m0, s55
	v_lshl_add_u64 v[168:169], v[218:219], 0, s[16:17]
	global_load_lds_dwordx4 v[168:169], off
	s_mov_b32 m0, s56
	v_lshl_add_u64 v[168:169], v[220:221], 0, s[16:17]
	global_load_lds_dwordx4 v[168:169], off
	s_waitcnt vmcnt(8)
	s_waitcnt lgkmcnt(0)
	s_barrier
	s_setprio 1
	s_waitcnt lgkmcnt(0)
	v_mfma_f32_16x16x32_bf16 v[60:63], v[128:131], v[178:181], v[60:63]
	v_mfma_f32_16x16x32_bf16 v[56:59], v[136:139], v[178:181], v[56:59]
	v_mfma_f32_16x16x32_bf16 v[44:47], v[128:131], v[186:189], v[44:47]
	v_mfma_f32_16x16x32_bf16 v[40:43], v[136:139], v[186:189], v[40:43]
	v_mfma_f32_16x16x32_bf16 v[28:31], v[128:131], v[202:205], v[28:31]
	v_mfma_f32_16x16x32_bf16 v[24:27], v[136:139], v[202:205], v[24:27]
	v_mfma_f32_16x16x32_bf16 v[12:15], v[128:131], v[210:213], v[12:15]
	v_mfma_f32_16x16x32_bf16 v[8:11], v[136:139], v[210:213], v[8:11]
	v_mfma_f32_16x16x32_bf16 v[60:63], v[132:135], v[182:185], v[60:63]
	v_mfma_f32_16x16x32_bf16 v[56:59], v[140:143], v[182:185], v[56:59]
	v_mfma_f32_16x16x32_bf16 v[44:47], v[132:135], v[194:197], v[44:47]
	v_mfma_f32_16x16x32_bf16 v[40:43], v[140:143], v[194:197], v[40:43]
	v_mfma_f32_16x16x32_bf16 v[28:31], v[132:135], v[206:209], v[28:31]
	v_mfma_f32_16x16x32_bf16 v[24:27], v[140:143], v[206:209], v[24:27]
	v_mfma_f32_16x16x32_bf16 v[12:15], v[132:135], v[214:217], v[12:15]
	v_mfma_f32_16x16x32_bf16 v[8:11], v[140:143], v[214:217], v[8:11]
	s_setprio 0
	s_setprio 1
	v_mfma_f32_16x16x32_bf16 v[52:55], v[144:147], v[178:181], v[52:55]
	v_mfma_f32_16x16x32_bf16 v[48:51], v[164:167], v[178:181], v[48:51]
	v_mfma_f32_16x16x32_bf16 v[36:39], v[144:147], v[186:189], v[36:39]
	v_mfma_f32_16x16x32_bf16 v[32:35], v[164:167], v[186:189], v[32:35]
	v_mfma_f32_16x16x32_bf16 v[20:23], v[144:147], v[202:205], v[20:23]
	v_mfma_f32_16x16x32_bf16 v[16:19], v[164:167], v[202:205], v[16:19]
	v_mfma_f32_16x16x32_bf16 v[4:7], v[144:147], v[210:213], v[4:7]
	v_mfma_f32_16x16x32_bf16 v[0:3], v[164:167], v[210:213], v[0:3]
	v_mfma_f32_16x16x32_bf16 v[52:55], v[148:151], v[182:185], v[52:55]
	v_mfma_f32_16x16x32_bf16 v[48:51], v[174:177], v[182:185], v[48:51]
	v_mfma_f32_16x16x32_bf16 v[36:39], v[148:151], v[194:197], v[36:39]
	v_mfma_f32_16x16x32_bf16 v[32:35], v[174:177], v[194:197], v[32:35]
	v_mfma_f32_16x16x32_bf16 v[20:23], v[148:151], v[206:209], v[20:23]
	v_mfma_f32_16x16x32_bf16 v[16:19], v[174:177], v[206:209], v[16:19]
	s_barrier
	v_mfma_f32_16x16x32_bf16 v[4:7], v[148:151], v[214:217], v[4:7]
	v_mfma_f32_16x16x32_bf16 v[0:3], v[174:177], v[214:217], v[0:3]
	s_setprio 0
	s_add_i32 s65, s65, 2
	s_add_u32 s36, s36, 0x100
	s_addc_u32 s37, s37, 0
	s_add_u32 s63, s63, 0x100
	s_addc_u32 s64, s64, 0
	s_cmp_gt_u32 s65, 29
	s_cbranch_scc0 .LBB0_635
	s_and_b64 vcc, exec, s[10:11]
	s_cbranch_vccz .LBB0_638
	s_barrier

; #define PG8_STAGE(bufoff, gbase, voff) do { _Pragma("unroll") for (int _i = 0; _i < 2; ++_i) \
;         __builtin_amdgcn_global_load_lds((const unsigned*)((const char*)(gbase) + (voff)[_i]), (PG8_LAS unsigned*)(lds + (bufoff) + ldsw + _i * 8192), 16, 0, 0); } while (0)
; #define PG8_LDA(dst, b, h) do { _Pragma("unroll") for (int m = 0; m < 4; ++m) _Pragma("unroll") for (int k = 0; k < 2; ++k) dst[m][k] = *(const PG8_LAS bf16x8*)(lds + PG8_SA(b, h) + aoff + m * 2048 + k * 1024); } while (0)
; #define PG8_LDB(dst, b, h) do { _Pragma("unroll") for (int n = 0; n < 2; ++n) _Pragma("unroll") for (int k = 0; k < 2; ++k) dst[n][k] = *(const PG8_LAS bf16x8*)(lds + PG8_SB(b, h) + boff + n * 2048 + k * 1024); } while (0)
; #define PG8_WAIT_V(n) asm volatile("s_waitcnt vmcnt(" #n ")" ::: "memory")
; #define PG8_WAIT_L(n) asm volatile("s_waitcnt lgkmcnt(" #n ")" ::: "memory")
; #define PG8_BAR __builtin_amdgcn_s_barrier()
; #define PG8_SCHED __builtin_amdgcn_sched_barrier(0)
; template <class Epi, class Sched, bool ALIGN_EPI = false, bool SP2 = false>
; __device__ __forceinline__ void gemm_phase(PG8_LAS unsigned char* lds, const Gemm g, const Sched& S, const Epi& E) {
;     ...
;         const char* nA = has_next ? (const char*)g.A + (size_t)nxt.pm * tstep : cA; const char* nB = has_next ? (const char*)g.Bt + (size_t)nxt.pn * tstep : cB;
;         for (int t = 0; t < nt; t += 2) {
;             if constexpr (Epi::MID_HOOK) { if (t == Epi::MID_T) E.mid(acc, cur, wr, wc, fr, fq); }
;             const bool last = (t == nt - 2);
;             const char* a1 = cA + (size_t)(t + 1) * kstep;
;             const char* a2 = last ? nA : cA + (size_t)(t + 2) * kstep; const char* b2 = last ? nB : cB + (size_t)(t + 2) * kstep;
;             const char* a3 = a2 + kstep; const char* b3 = b2 + kstep;
;             if (last && has_next) S.a_ready(nxt);
;             if constexpr (SP2) {
;             PG8_LDB(B0, 0, 0); PG8_LDB(B1, 0, 1); PG8_SCHED; PG8_LDA(At, 0, 0); PG8_STAGE(PG8_SA(1, 1), a1 + hstep, voffA);
;             PG8_WAIT_V(8); PG8_WAIT_L(0); PG8_BAR; PG8_MMA(0, 0, At, B0); PG8_MMA(0, 1, At, B1); PG8_BAR; PG8_SCHED;
;             PG8_LDA(At, 0, 1); PG8_STAGE(PG8_SB(0, 0), b2, voffB); PG8_STAGE(PG8_SB(0, 1), b2 + hstep, voffB); PG8_STAGE(PG8_SA(0, 0), a2, voffA);
;             PG8_WAIT_V(8); PG8_WAIT_L(0); PG8_BAR; PG8_MMA(1, 0, At, B0); PG8_MMA(1, 1, At, B1); PG8_BAR; PG8_SCHED;
.LBB0_729:
	s_ashr_i32 s49, s48, 31
	s_lshl_b64 s[12:13], s[48:49], 20
	s_add_u32 s50, s18, s12
	s_addc_u32 s51, s19, s13
	s_and_b64 s[12:13], s[42:43], exec
	s_cselect_b32 s49, s51, s1
	s_cselect_b32 s60, s50, s0
	s_ashr_i32 s47, s46, 31
	s_lshl_b64 s[12:13], s[46:47], 20
	s_add_u32 s52, s14, s12
	s_addc_u32 s53, s15, s13
	s_and_b64 s[12:13], s[42:43], exec
	s_cselect_b32 s47, s53, s11
	s_cselect_b32 s61, s52, s10
	s_add_u32 s0, s0, 0x80080
	s_addc_u32 s1, s1, 0
	s_add_u32 s62, s10, 0x100
	s_addc_u32 s63, s11, 0
	s_mov_b32 s64, -2
	v_lshl_add_u64 v[190:191], s[0:1], 0, v[136:137]
	s_add_i32 m0, s31, 0xc000
	global_load_lds_dwordx4 v[190:191], off
	s_add_i32 m0, s31, 0xe000
	v_lshl_add_u64 v[190:191], s[0:1], 0, v[138:139]
	global_load_lds_dwordx4 v[190:191], off
	s_add_u32 s10, s0, 0xfff80080
	s_addc_u32 s11, s1, -1
	s_add_i32 s24, 0, 0x10000
	s_cmp_eq_u32 s64, 28
	s_cselect_b32 s13, s49, s11
	s_cselect_b32 s12, s60, s10
	s_cselect_b32 s11, s47, s63
	s_cselect_b32 s10, s61, s62
	s_add_i32 s25, 0, 0x14000
	s_waitcnt vmcnt(8)
	s_waitcnt lgkmcnt(0)
	s_barrier
	s_setprio 1
	s_waitcnt lgkmcnt(0)
	v_mfma_f32_16x16x32_bf16 v[124:127], v[140:143], v[178:181], 0
	v_mfma_f32_16x16x32_bf16 v[112:115], v[154:157], v[178:181], 0
	v_mfma_f32_16x16x32_bf16 v[108:111], v[140:143], v[186:189], 0
	v_mfma_f32_16x16x32_bf16 v[100:103], v[154:157], v[186:189], 0
	v_mfma_f32_16x16x32_bf16 v[92:95], v[140:143], v[202:205], 0
	v_mfma_f32_16x16x32_bf16 v[84:87], v[154:157], v[202:205], 0
	v_mfma_f32_16x16x32_bf16 v[76:79], v[140:143], v[210:213], 0
	v_mfma_f32_16x16x32_bf16 v[68:71], v[154:157], v[210:213], 0
	v_mfma_f32_16x16x32_bf16 v[124:127], v[144:147], v[182:185], v[124:127]
	v_mfma_f32_16x16x32_bf16 v[112:115], v[158:161], v[182:185], v[112:115]
	v_mfma_f32_16x16x32_bf16 v[108:111], v[144:147], v[194:197], v[108:111]
	v_mfma_f32_16x16x32_bf16 v[100:103], v[158:161], v[194:197], v[100:103]
	v_mfma_f32_16x16x32_bf16 v[92:95], v[144:147], v[206:209], v[92:95]
	v_mfma_f32_16x16x32_bf16 v[84:87], v[158:161], v[206:209], v[84:87]
	v_mfma_f32_16x16x32_bf16 v[76:79], v[144:147], v[214:217], v[76:79]
	v_mfma_f32_16x16x32_bf16 v[68:71], v[158:161], v[214:217], v[68:71]
	s_setprio 0
	s_setprio 1
	v_mfma_f32_16x16x32_bf16 v[120:123], v[162:165], v[178:181], 0
	v_mfma_f32_16x16x32_bf16 v[116:119], v[170:173], v[178:181], 0
	v_mfma_f32_16x16x32_bf16 v[104:107], v[162:165], v[186:189], 0
	v_mfma_f32_16x16x32_bf16 v[96:99], v[170:173], v[186:189], 0
	v_mfma_f32_16x16x32_bf16 v[88:91], v[162:165], v[202:205], 0
	v_mfma_f32_16x16x32_bf16 v[80:83], v[170:173], v[202:205], 0
	v_mfma_f32_16x16x32_bf16 v[72:75], v[162:165], v[210:213], 0
	v_mfma_f32_16x16x32_bf16 v[64:67], v[170:173], v[210:213], 0
	v_mfma_f32_16x16x32_bf16 v[120:123], v[166:169], v[182:185], v[120:123]
	v_mfma_f32_16x16x32_bf16 v[116:119], v[174:177], v[182:185], v[116:119]
	v_mfma_f32_16x16x32_bf16 v[104:107], v[166:169], v[194:197], v[104:107]
	v_mfma_f32_16x16x32_bf16 v[96:99], v[174:177], v[194:197], v[96:99]
	v_mfma_f32_16x16x32_bf16 v[88:91], v[166:169], v[206:209], v[88:91]
	v_mfma_f32_16x16x32_bf16 v[80:83], v[174:177], v[206:209], v[80:83]
	s_barrier
	v_mfma_f32_16x16x32_bf16 v[72:75], v[166:169], v[214:217], v[72:75]
	v_mfma_f32_16x16x32_bf16 v[64:67], v[174:177], v[214:217], v[64:67]
	s_setprio 0
	s_add_i32 s24, s24, s30
	v_lshl_add_u64 v[190:191], s[10:11], 0, v[132:133]
	s_mov_b32 m0, s24
	ds_read_b128 v[178:181], v152 offset:16384
	ds_read_b128 v[182:185], v152 offset:17408
	ds_read_b128 v[186:189], v152 offset:18432
	ds_read_b128 v[194:197], v152 offset:19456
	ds_read_b128 v[202:205], v152 offset:20480
	ds_read_b128 v[206:209], v152 offset:21504
	ds_read_b128 v[210:213], v152 offset:22528
	ds_read_b128 v[214:217], v152 offset:23552
	global_load_lds_dwordx4 v[190:191], off
	s_add_i32 m0, s24, 0x2000
	s_add_u32 s66, s10, 0x80000
	v_lshl_add_u64 v[218:219], s[10:11], 0, v[128:129]
	s_addc_u32 s67, s11, 0
	s_add_i32 s24, s25, s30
	global_load_lds_dwordx4 v[218:219], off
	v_lshl_add_u64 v[220:221], s[66:67], 0, v[132:133]
	s_mov_b32 m0, s24
	v_lshl_add_u64 v[230:231], s[12:13], 0, v[130:131]
	global_load_lds_dwordx4 v[220:221], off
	s_add_i32 m0, s24, 0x2000
	v_lshl_add_u64 v[220:221], s[66:67], 0, v[128:129]
	global_load_lds_dwordx4 v[220:221], off
	s_mov_b32 m0, s31
	v_lshl_add_u64 v[220:221], s[12:13], 0, v[134:135]
	global_load_lds_dwordx4 v[220:221], off
	s_mov_b32 m0, s34
	s_nop 0
	global_load_lds_dwordx4 v[230:231], off
	s_waitcnt vmcnt(8)
	s_waitcnt lgkmcnt(0)
	s_barrier
	s_setprio 1
	s_waitcnt lgkmcnt(0)
	v_mfma_f32_16x16x32_bf16 v[60:63], v[140:143], v[178:181], 0
	v_mfma_f32_16x16x32_bf16 v[52:55], v[154:157], v[178:181], 0
	v_mfma_f32_16x16x32_bf16 v[44:47], v[140:143], v[186:189], 0
	v_mfma_f32_16x16x32_bf16 v[36:39], v[154:157], v[186:189], 0
	v_mfma_f32_16x16x32_bf16 v[28:31], v[140:143], v[202:205], 0
	v_mfma_f32_16x16x32_bf16 v[20:23], v[154:157], v[202:205], 0
	v_mfma_f32_16x16x32_bf16 v[12:15], v[140:143], v[210:213], 0
	v_mfma_f32_16x16x32_bf16 v[4:7], v[154:157], v[210:213], 0
	v_mfma_f32_16x16x32_bf16 v[60:63], v[144:147], v[182:185], v[60:63]
	v_mfma_f32_16x16x32_bf16 v[52:55], v[158:161], v[182:185], v[52:55]
	v_mfma_f32_16x16x32_bf16 v[44:47], v[144:147], v[194:197], v[44:47]
	v_mfma_f32_16x16x32_bf16 v[36:39], v[158:161], v[194:197], v[36:39]
	v_mfma_f32_16x16x32_bf16 v[28:31], v[144:147], v[206:209], v[28:31]
	v_mfma_f32_16x16x32_bf16 v[20:23], v[158:161], v[206:209], v[20:23]
	v_mfma_f32_16x16x32_bf16 v[12:15], v[144:147], v[214:217], v[12:15]
	v_mfma_f32_16x16x32_bf16 v[4:7], v[158:161], v[214:217], v[4:7]
	s_setprio 0
	s_setprio 1
	v_mfma_f32_16x16x32_bf16 v[56:59], v[162:165], v[178:181], 0
	v_mfma_f32_16x16x32_bf16 v[48:51], v[170:173], v[178:181], 0
	v_mfma_f32_16x16x32_bf16 v[40:43], v[162:165], v[186:189], 0
	v_mfma_f32_16x16x32_bf16 v[32:35], v[170:173], v[186:189], 0
	v_mfma_f32_16x16x32_bf16 v[24:27], v[162:165], v[202:205], 0
	v_mfma_f32_16x16x32_bf16 v[16:19], v[170:173], v[202:205], 0
	v_mfma_f32_16x16x32_bf16 v[8:11], v[162:165], v[210:213], 0
	v_mfma_f32_16x16x32_bf16 v[0:3], v[170:173], v[210:213], 0
	v_mfma_f32_16x16x32_bf16 v[56:59], v[166:169], v[182:185], v[56:59]
	v_mfma_f32_16x16x32_bf16 v[48:51], v[174:177], v[182:185], v[48:51]
	v_mfma_f32_16x16x32_bf16 v[40:43], v[166:169], v[194:197], v[40:43]
	v_mfma_f32_16x16x32_bf16 v[32:35], v[174:177], v[194:197], v[32:35]
	v_mfma_f32_16x16x32_bf16 v[24:27], v[166:169], v[206:209], v[24:27]
	v_mfma_f32_16x16x32_bf16 v[16:19], v[174:177], v[206:209], v[16:19]
	s_barrier
; #define PG8_STAGE(bufoff, gbase, voff) do { _Pragma("unroll") for (int _i = 0; _i < 2; ++_i) \
;         __builtin_amdgcn_global_load_lds((const unsigned*)((const char*)(gbase) + (voff)[_i]), (PG8_LAS unsigned*)(lds + (bufoff) + ldsw + _i * 8192), 16, 0, 0); } while (0)
; #define PG8_LDA(dst, b, h) do { _Pragma("unroll") for (int m = 0; m < 4; ++m) _Pragma("unroll") for (int k = 0; k < 2; ++k) dst[m][k] = *(const PG8_LAS bf16x8*)(lds + PG8_SA(b, h) + aoff + m * 2048 + k * 1024); } while (0)
; #define PG8_LDB(dst, b, h) do { _Pragma("unroll") for (int n = 0; n < 2; ++n) _Pragma("unroll") for (int k = 0; k < 2; ++k) dst[n][k] = *(const PG8_LAS bf16x8*)(lds + PG8_SB(b, h) + boff + n * 2048 + k * 1024); } while (0)
; #define PG8_MMA(ai, bj, At, Bt) do { __builtin_amdgcn_s_setprio(1); _Pragma("unroll") for (int m = 0; m < 4; ++m) _Pragma("unroll") for (int n = 0; n < 2; ++n) _Pragma("unroll") for (int k = 0; k < 2; ++k) \
;         acc[ai][bj][m][n] = __builtin_amdgcn_mfma_f32_16x16x32_bf16(Bt[n][k], At[m][k], acc[ai][bj][m][n], 0, 0, 0); __builtin_amdgcn_s_setprio(0); } while (0)
; #define PG8_WAIT_V(n) asm volatile("s_waitcnt vmcnt(" #n ")" ::: "memory")
; #define PG8_WAIT_L(n) asm volatile("s_waitcnt lgkmcnt(" #n ")" ::: "memory")
; #define PG8_BAR __builtin_amdgcn_s_barrier()
; #define PG8_SCHED __builtin_amdgcn_sched_barrier(0)
; template <class Epi, class Sched, bool ALIGN_EPI = false, bool SP2 = false>
; __device__ __forceinline__ void gemm_phase(PG8_LAS unsigned char* lds, const Gemm g, const Sched& S, const Epi& E) {
;     ...
;             PG8_WAIT_V(8); PG8_WAIT_L(0); PG8_BAR; PG8_MMA(1, 0, At, B0); PG8_MMA(1, 1, At, B1); PG8_BAR; PG8_SCHED;
;             PG8_LDB(B0, 1, 0); PG8_LDB(B1, 1, 1); PG8_SCHED; PG8_LDA(At, 1, 0); PG8_STAGE(PG8_SA(0, 1), a2 + hstep, voffA);
;             PG8_WAIT_V(8); PG8_WAIT_L(0); PG8_BAR; PG8_MMA(0, 0, At, B0); PG8_MMA(0, 1, At, B1); PG8_BAR; PG8_SCHED;
;             PG8_LDA(At, 1, 1); PG8_STAGE(PG8_SB(1, 0), b3, voffB); PG8_STAGE(PG8_SB(1, 1), b3 + hstep, voffB); PG8_STAGE(PG8_SA(1, 0), a3, voffA);
	v_mfma_f32_16x16x32_bf16 v[8:11], v[166:169], v[214:217], v[8:11]
	v_mfma_f32_16x16x32_bf16 v[0:3], v[174:177], v[214:217], v[0:3]
	s_setprio 0
	s_add_i32 s24, 0, 0x18000
	v_add_u32_e32 v148, 0x18000, v151
	s_add_i32 s25, 0, 0x1c000
	ds_read_b128 v[140:143], v148
	ds_read_b128 v[144:147], v148 offset:1024
	ds_read_b128 v[154:157], v148 offset:2048
	ds_read_b128 v[158:161], v148 offset:3072
	v_add_u32_e32 v148, 0x1c000, v151
	ds_read_b128 v[162:165], v148
	ds_read_b128 v[166:169], v148 offset:1024
	ds_read_b128 v[170:173], v148 offset:2048
	ds_read_b128 v[174:177], v148 offset:3072
	s_add_u32 s12, s12, 0x80000
	s_addc_u32 s13, s13, 0
	s_mov_b32 m0, s36
	v_lshl_add_u64 v[232:233], s[12:13], 0, v[134:135]
	ds_read_b128 v[178:181], v152 offset:32768
	ds_read_b128 v[182:185], v152 offset:33792
	ds_read_b128 v[186:189], v152 offset:34816
	ds_read_b128 v[194:197], v152 offset:35840
	ds_read_b128 v[202:205], v152 offset:36864
	ds_read_b128 v[206:209], v152 offset:37888
	ds_read_b128 v[210:213], v152 offset:38912
	ds_read_b128 v[214:217], v152 offset:39936
	global_load_lds_dwordx4 v[232:233], off
	s_mov_b32 m0, s37
	v_lshl_add_u64 v[232:233], s[12:13], 0, v[130:131]
	global_load_lds_dwordx4 v[232:233], off
	s_waitcnt vmcnt(8)
	s_waitcnt lgkmcnt(0)
	s_barrier
	s_setprio 1
	s_waitcnt lgkmcnt(0)
	v_mfma_f32_16x16x32_bf16 v[124:127], v[140:143], v[178:181], v[124:127]
	v_mfma_f32_16x16x32_bf16 v[112:115], v[154:157], v[178:181], v[112:115]
	v_mfma_f32_16x16x32_bf16 v[108:111], v[140:143], v[186:189], v[108:111]
	v_mfma_f32_16x16x32_bf16 v[100:103], v[154:157], v[186:189], v[100:103]
	v_mfma_f32_16x16x32_bf16 v[92:95], v[140:143], v[202:205], v[92:95]
	v_mfma_f32_16x16x32_bf16 v[84:87], v[154:157], v[202:205], v[84:87]
	v_mfma_f32_16x16x32_bf16 v[76:79], v[140:143], v[210:213], v[76:79]
	v_mfma_f32_16x16x32_bf16 v[68:71], v[154:157], v[210:213], v[68:71]
	v_mfma_f32_16x16x32_bf16 v[124:127], v[144:147], v[182:185], v[124:127]
	v_mfma_f32_16x16x32_bf16 v[112:115], v[158:161], v[182:185], v[112:115]
	v_mfma_f32_16x16x32_bf16 v[108:111], v[144:147], v[194:197], v[108:111]
	v_mfma_f32_16x16x32_bf16 v[100:103], v[158:161], v[194:197], v[100:103]
	v_mfma_f32_16x16x32_bf16 v[92:95], v[144:147], v[206:209], v[92:95]
	v_mfma_f32_16x16x32_bf16 v[84:87], v[158:161], v[206:209], v[84:87]
	v_mfma_f32_16x16x32_bf16 v[76:79], v[144:147], v[214:217], v[76:79]
	v_mfma_f32_16x16x32_bf16 v[68:71], v[158:161], v[214:217], v[68:71]
	s_setprio 0
	s_setprio 1
	v_mfma_f32_16x16x32_bf16 v[120:123], v[162:165], v[178:181], v[120:123]
	v_mfma_f32_16x16x32_bf16 v[116:119], v[170:173], v[178:181], v[116:119]
	v_mfma_f32_16x16x32_bf16 v[104:107], v[162:165], v[186:189], v[104:107]
	v_mfma_f32_16x16x32_bf16 v[96:99], v[170:173], v[186:189], v[96:99]
	v_mfma_f32_16x16x32_bf16 v[88:91], v[162:165], v[202:205], v[88:91]
	v_mfma_f32_16x16x32_bf16 v[80:83], v[170:173], v[202:205], v[80:83]
	v_mfma_f32_16x16x32_bf16 v[72:75], v[162:165], v[210:213], v[72:75]
	v_mfma_f32_16x16x32_bf16 v[64:67], v[170:173], v[210:213], v[64:67]
	v_mfma_f32_16x16x32_bf16 v[120:123], v[166:169], v[182:185], v[120:123]
	v_mfma_f32_16x16x32_bf16 v[116:119], v[174:177], v[182:185], v[116:119]
	v_mfma_f32_16x16x32_bf16 v[104:107], v[166:169], v[194:197], v[104:107]
	v_mfma_f32_16x16x32_bf16 v[96:99], v[174:177], v[194:197], v[96:99]
	v_mfma_f32_16x16x32_bf16 v[88:91], v[166:169], v[206:209], v[88:91]
	v_mfma_f32_16x16x32_bf16 v[80:83], v[174:177], v[206:209], v[80:83]
	s_barrier
	v_mfma_f32_16x16x32_bf16 v[72:75], v[166:169], v[214:217], v[72:75]
	v_mfma_f32_16x16x32_bf16 v[64:67], v[174:177], v[214:217], v[64:67]
	s_setprio 0
	s_add_i32 s12, s24, s30
	v_lshl_add_u64 v[190:191], v[190:191], 0, s[16:17]
	s_mov_b32 m0, s12
	ds_read_b128 v[178:181], v152 offset:49152
	ds_read_b128 v[182:185], v152 offset:50176
	ds_read_b128 v[186:189], v152 offset:51200
	ds_read_b128 v[194:197], v152 offset:52224
	ds_read_b128 v[202:205], v152 offset:53248
	ds_read_b128 v[206:209], v152 offset:54272
	ds_read_b128 v[210:213], v152 offset:55296
	ds_read_b128 v[214:217], v152 offset:56320
	global_load_lds_dwordx4 v[190:191], off
	s_add_i32 m0, s12, 0x2000
	s_add_u32 s10, s10, 0x80080
	v_lshl_add_u64 v[190:191], v[218:219], 0, s[16:17]
	s_addc_u32 s11, s11, 0
	s_add_i32 s12, s25, s30
	global_load_lds_dwordx4 v[190:191], off
	s_mov_b32 m0, s12
	v_lshl_add_u64 v[190:191], s[10:11], 0, v[132:133]
	global_load_lds_dwordx4 v[190:191], off
	s_add_i32 m0, s12, 0x2000
	v_lshl_add_u64 v[190:191], s[10:11], 0, v[128:129]
	global_load_lds_dwordx4 v[190:191], off
	s_mov_b32 m0, s56
	v_lshl_add_u64 v[190:191], v[220:221], 0, s[16:17]
	global_load_lds_dwordx4 v[190:191], off
	s_mov_b32 m0, s57
	v_lshl_add_u64 v[190:191], v[230:231], 0, s[16:17]
	global_load_lds_dwordx4 v[190:191], off
	s_waitcnt vmcnt(8)
	s_waitcnt lgkmcnt(0)
	s_barrier
; #define PG8_STAGE(bufoff, gbase, voff) do { _Pragma("unroll") for (int _i = 0; _i < 2; ++_i) \
;         __builtin_amdgcn_global_load_lds((const unsigned*)((const char*)(gbase) + (voff)[_i]), (PG8_LAS unsigned*)(lds + (bufoff) + ldsw + _i * 8192), 16, 0, 0); } while (0)
; #define PG8_LDA(dst, b, h) do { _Pragma("unroll") for (int m = 0; m < 4; ++m) _Pragma("unroll") for (int k = 0; k < 2; ++k) dst[m][k] = *(const PG8_LAS bf16x8*)(lds + PG8_SA(b, h) + aoff + m * 2048 + k * 1024); } while (0)
; #define PG8_LDB(dst, b, h) do { _Pragma("unroll") for (int n = 0; n < 2; ++n) _Pragma("unroll") for (int k = 0; k < 2; ++k) dst[n][k] = *(const PG8_LAS bf16x8*)(lds + PG8_SB(b, h) + boff + n * 2048 + k * 1024); } while (0)
; #define PG8_MMA(ai, bj, At, Bt) do { __builtin_amdgcn_s_setprio(1); _Pragma("unroll") for (int m = 0; m < 4; ++m) _Pragma("unroll") for (int n = 0; n < 2; ++n) _Pragma("unroll") for (int k = 0; k < 2; ++k) \
;         acc[ai][bj][m][n] = __builtin_amdgcn_mfma_f32_16x16x32_bf16(Bt[n][k], At[m][k], acc[ai][bj][m][n], 0, 0, 0); __builtin_amdgcn_s_setprio(0); } while (0)
; #define PG8_WAIT_V(n) asm volatile("s_waitcnt vmcnt(" #n ")" ::: "memory")
; template <class Epi, class Sched, bool ALIGN_EPI = false, bool SP2 = false>
; __device__ __forceinline__ void gemm_phase(PG8_LAS unsigned char* lds, const Gemm g, const Sched& S, const Epi& E) {
;     ...
;             PG8_LDB(B0, 0, 0); PG8_LDB(B1, 0, 1); PG8_SCHED; PG8_LDA(At, 0, 0); PG8_STAGE(PG8_SA(1, 1), a1 + hstep, voffA);
;             PG8_WAIT_V(8); PG8_WAIT_L(0); PG8_BAR; PG8_MMA(0, 0, At, B0); PG8_MMA(0, 1, At, B1); PG8_BAR; PG8_SCHED;
;             PG8_LDA(At, 0, 1); PG8_STAGE(PG8_SB(0, 0), b2, voffB); PG8_STAGE(PG8_SB(0, 1), b2 + hstep, voffB); PG8_STAGE(PG8_SA(0, 0), a2, voffA);
;             PG8_WAIT_V(8); PG8_WAIT_L(0); PG8_BAR; PG8_MMA(1, 0, At, B0); PG8_MMA(1, 1, At, B1); PG8_BAR; PG8_SCHED;
;             PG8_LDB(B0, 1, 0); PG8_LDB(B1, 1, 1); PG8_SCHED; PG8_LDA(At, 1, 0); PG8_STAGE(PG8_SA(0, 1), a2 + hstep, voffA);
;             PG8_WAIT_V(8); PG8_WAIT_L(0); PG8_BAR; PG8_MMA(0, 0, At, B0); PG8_MMA(0, 1, At, B1); PG8_BAR; PG8_SCHED;
;             PG8_LDA(At, 1, 1); PG8_STAGE(PG8_SB(1, 0), b3, voffB); PG8_STAGE(PG8_SB(1, 1), b3 + hstep, voffB); PG8_STAGE(PG8_SA(1, 0), a3, voffA);
;             PG8_WAIT_V(8); PG8_WAIT_L(0); PG8_BAR; PG8_MMA(1, 0, At, B0); PG8_MMA(1, 1, At, B1); PG8_BAR; PG8_SCHED;
	s_setprio 1
	s_waitcnt lgkmcnt(0)
	v_mfma_f32_16x16x32_bf16 v[60:63], v[140:143], v[178:181], v[60:63]
	v_mfma_f32_16x16x32_bf16 v[52:55], v[154:157], v[178:181], v[52:55]
	v_mfma_f32_16x16x32_bf16 v[44:47], v[140:143], v[186:189], v[44:47]
	v_mfma_f32_16x16x32_bf16 v[36:39], v[154:157], v[186:189], v[36:39]
	v_mfma_f32_16x16x32_bf16 v[28:31], v[140:143], v[202:205], v[28:31]
	v_mfma_f32_16x16x32_bf16 v[20:23], v[154:157], v[202:205], v[20:23]
	v_mfma_f32_16x16x32_bf16 v[12:15], v[140:143], v[210:213], v[12:15]
	v_mfma_f32_16x16x32_bf16 v[4:7], v[154:157], v[210:213], v[4:7]
	v_mfma_f32_16x16x32_bf16 v[60:63], v[144:147], v[182:185], v[60:63]
	v_mfma_f32_16x16x32_bf16 v[52:55], v[158:161], v[182:185], v[52:55]
	v_mfma_f32_16x16x32_bf16 v[44:47], v[144:147], v[194:197], v[44:47]
	v_mfma_f32_16x16x32_bf16 v[36:39], v[158:161], v[194:197], v[36:39]
	v_mfma_f32_16x16x32_bf16 v[28:31], v[144:147], v[206:209], v[28:31]
	v_mfma_f32_16x16x32_bf16 v[20:23], v[158:161], v[206:209], v[20:23]
	v_mfma_f32_16x16x32_bf16 v[12:15], v[144:147], v[214:217], v[12:15]
	v_mfma_f32_16x16x32_bf16 v[4:7], v[158:161], v[214:217], v[4:7]
	s_setprio 0
	s_setprio 1
	v_mfma_f32_16x16x32_bf16 v[56:59], v[162:165], v[178:181], v[56:59]
	v_mfma_f32_16x16x32_bf16 v[48:51], v[170:173], v[178:181], v[48:51]
	v_mfma_f32_16x16x32_bf16 v[40:43], v[162:165], v[186:189], v[40:43]
	v_mfma_f32_16x16x32_bf16 v[32:35], v[170:173], v[186:189], v[32:35]
	v_mfma_f32_16x16x32_bf16 v[24:27], v[162:165], v[202:205], v[24:27]
	v_mfma_f32_16x16x32_bf16 v[16:19], v[170:173], v[202:205], v[16:19]
	v_mfma_f32_16x16x32_bf16 v[8:11], v[162:165], v[210:213], v[8:11]
	v_mfma_f32_16x16x32_bf16 v[0:3], v[170:173], v[210:213], v[0:3]
	v_mfma_f32_16x16x32_bf16 v[56:59], v[166:169], v[182:185], v[56:59]
	v_mfma_f32_16x16x32_bf16 v[48:51], v[174:177], v[182:185], v[48:51]
	v_mfma_f32_16x16x32_bf16 v[40:43], v[166:169], v[194:197], v[40:43]
	v_mfma_f32_16x16x32_bf16 v[32:35], v[174:177], v[194:197], v[32:35]
	v_mfma_f32_16x16x32_bf16 v[24:27], v[166:169], v[206:209], v[24:27]
	v_mfma_f32_16x16x32_bf16 v[16:19], v[174:177], v[206:209], v[16:19]
	s_barrier
	v_mfma_f32_16x16x32_bf16 v[8:11], v[166:169], v[214:217], v[8:11]
	v_mfma_f32_16x16x32_bf16 v[0:3], v[174:177], v[214:217], v[0:3]
	s_setprio 0
	s_add_i32 s64, s64, 2
	s_add_u32 s0, s0, 0x100
	s_addc_u32 s1, s1, 0
	s_add_u32 s62, s62, 0x100
	s_addc_u32 s63, s63, 0
	s_cmp_gt_u32 s64, 29
	s_branch .LBB0_730
.LBB0_730:
	v_add_u32_e32 v148, 0x10000, v151
	ds_read_b128 v[140:143], v148
	ds_read_b128 v[144:147], v148 offset:1024
	ds_read_b128 v[154:157], v148 offset:2048
	ds_read_b128 v[158:161], v148 offset:3072
	v_add_u32_e32 v148, 0x14000, v151
	ds_read_b128 v[162:165], v148
	ds_read_b128 v[166:169], v148 offset:1024
	ds_read_b128 v[170:173], v148 offset:2048
	ds_read_b128 v[174:177], v148 offset:3072
	v_lshl_add_u64 v[190:191], s[0:1], 0, v[136:137]
	s_add_i32 m0, s31, 0xc000
	ds_read_b128 v[178:181], v152
	ds_read_b128 v[182:185], v152 offset:1024
	ds_read_b128 v[186:189], v152 offset:2048
	ds_read_b128 v[194:197], v152 offset:3072
	ds_read_b128 v[202:205], v152 offset:4096
	ds_read_b128 v[206:209], v152 offset:5120
	ds_read_b128 v[210:213], v152 offset:6144
	ds_read_b128 v[214:217], v152 offset:7168
	global_load_lds_dwordx4 v[190:191], off
	s_add_i32 m0, s31, 0xe000
	v_lshl_add_u64 v[190:191], s[0:1], 0, v[138:139]
	global_load_lds_dwordx4 v[190:191], off
	s_add_u32 s10, s0, 0xfff80080
	s_addc_u32 s11, s1, -1
	s_add_i32 s24, 0, 0x10000
	s_cmp_eq_u32 s64, 28
	s_cselect_b32 s13, s49, s11
	s_cselect_b32 s12, s60, s10
	s_cselect_b32 s11, s47, s63
	s_cselect_b32 s10, s61, s62
	s_add_i32 s25, 0, 0x14000
	s_waitcnt vmcnt(8)
	s_waitcnt lgkmcnt(0)
	s_barrier
	s_setprio 1
	s_waitcnt lgkmcnt(0)
	v_mfma_f32_16x16x32_bf16 v[124:127], v[140:143], v[178:181], v[124:127]
	v_mfma_f32_16x16x32_bf16 v[112:115], v[154:157], v[178:181], v[112:115]
	v_mfma_f32_16x16x32_bf16 v[108:111], v[140:143], v[186:189], v[108:111]
	v_mfma_f32_16x16x32_bf16 v[100:103], v[154:157], v[186:189], v[100:103]
	v_mfma_f32_16x16x32_bf16 v[92:95], v[140:143], v[202:205], v[92:95]
	v_mfma_f32_16x16x32_bf16 v[84:87], v[154:157], v[202:205], v[84:87]
	v_mfma_f32_16x16x32_bf16 v[76:79], v[140:143], v[210:213], v[76:79]
	v_mfma_f32_16x16x32_bf16 v[68:71], v[154:157], v[210:213], v[68:71]
	v_mfma_f32_16x16x32_bf16 v[124:127], v[144:147], v[182:185], v[124:127]
	v_mfma_f32_16x16x32_bf16 v[112:115], v[158:161], v[182:185], v[112:115]
	v_mfma_f32_16x16x32_bf16 v[108:111], v[144:147], v[194:197], v[108:111]
	v_mfma_f32_16x16x32_bf16 v[100:103], v[158:161], v[194:197], v[100:103]
	v_mfma_f32_16x16x32_bf16 v[92:95], v[144:147], v[206:209], v[92:95]
	v_mfma_f32_16x16x32_bf16 v[84:87], v[158:161], v[206:209], v[84:87]
	v_mfma_f32_16x16x32_bf16 v[76:79], v[144:147], v[214:217], v[76:79]
	v_mfma_f32_16x16x32_bf16 v[68:71], v[158:161], v[214:217], v[68:71]
	s_setprio 0
	s_setprio 1
	v_mfma_f32_16x16x32_bf16 v[120:123], v[162:165], v[178:181], v[120:123]
	v_mfma_f32_16x16x32_bf16 v[116:119], v[170:173], v[178:181], v[116:119]
	v_mfma_f32_16x16x32_bf16 v[104:107], v[162:165], v[186:189], v[104:107]
	v_mfma_f32_16x16x32_bf16 v[96:99], v[170:173], v[186:189], v[96:99]
	v_mfma_f32_16x16x32_bf16 v[88:91], v[162:165], v[202:205], v[88:91]
	v_mfma_f32_16x16x32_bf16 v[80:83], v[170:173], v[202:205], v[80:83]
	v_mfma_f32_16x16x32_bf16 v[72:75], v[162:165], v[210:213], v[72:75]
	v_mfma_f32_16x16x32_bf16 v[64:67], v[170:173], v[210:213], v[64:67]
	v_mfma_f32_16x16x32_bf16 v[120:123], v[166:169], v[182:185], v[120:123]
	v_mfma_f32_16x16x32_bf16 v[116:119], v[174:177], v[182:185], v[116:119]
	v_mfma_f32_16x16x32_bf16 v[104:107], v[166:169], v[194:197], v[104:107]
	v_mfma_f32_16x16x32_bf16 v[96:99], v[174:177], v[194:197], v[96:99]
	v_mfma_f32_16x16x32_bf16 v[88:91], v[166:169], v[206:209], v[88:91]
	v_mfma_f32_16x16x32_bf16 v[80:83], v[174:177], v[206:209], v[80:83]
	s_barrier
; #define PG8_STAGE(bufoff, gbase, voff) do { _Pragma("unroll") for (int _i = 0; _i < 2; ++_i) \
;         __builtin_amdgcn_global_load_lds((const unsigned*)((const char*)(gbase) + (voff)[_i]), (PG8_LAS unsigned*)(lds + (bufoff) + ldsw + _i * 8192), 16, 0, 0); } while (0)
; #define PG8_LDA(dst, b, h) do { _Pragma("unroll") for (int m = 0; m < 4; ++m) _Pragma("unroll") for (int k = 0; k < 2; ++k) dst[m][k] = *(const PG8_LAS bf16x8*)(lds + PG8_SA(b, h) + aoff + m * 2048 + k * 1024); } while (0)
; #define PG8_LDB(dst, b, h) do { _Pragma("unroll") for (int n = 0; n < 2; ++n) _Pragma("unroll") for (int k = 0; k < 2; ++k) dst[n][k] = *(const PG8_LAS bf16x8*)(lds + PG8_SB(b, h) + boff + n * 2048 + k * 1024); } while (0)
; #define PG8_MMA(ai, bj, At, Bt) do { __builtin_amdgcn_s_setprio(1); _Pragma("unroll") for (int m = 0; m < 4; ++m) _Pragma("unroll") for (int n = 0; n < 2; ++n) _Pragma("unroll") for (int k = 0; k < 2; ++k) \
;         acc[ai][bj][m][n] = __builtin_amdgcn_mfma_f32_16x16x32_bf16(Bt[n][k], At[m][k], acc[ai][bj][m][n], 0, 0, 0); __builtin_amdgcn_s_setprio(0); } while (0)
; #define PG8_WAIT_V(n) asm volatile("s_waitcnt vmcnt(" #n ")" ::: "memory")
; #define PG8_WAIT_L(n) asm volatile("s_waitcnt lgkmcnt(" #n ")" ::: "memory")
; #define PG8_BAR __builtin_amdgcn_s_barrier()
; #define PG8_SCHED __builtin_amdgcn_sched_barrier(0)
; template <class Epi, class Sched, bool ALIGN_EPI = false, bool SP2 = false>
; __device__ __forceinline__ void gemm_phase(PG8_LAS unsigned char* lds, const Gemm g, const Sched& S, const Epi& E) {
;     ...
;             PG8_WAIT_V(8); PG8_WAIT_L(0); PG8_BAR; PG8_MMA(0, 0, At, B0); PG8_MMA(0, 1, At, B1); PG8_BAR; PG8_SCHED;
;             PG8_LDA(At, 0, 1); PG8_STAGE(PG8_SB(0, 0), b2, voffB); PG8_STAGE(PG8_SB(0, 1), b2 + hstep, voffB); PG8_STAGE(PG8_SA(0, 0), a2, voffA);
;             PG8_WAIT_V(8); PG8_WAIT_L(0); PG8_BAR; PG8_MMA(1, 0, At, B0); PG8_MMA(1, 1, At, B1); PG8_BAR; PG8_SCHED;
;             PG8_LDB(B0, 1, 0); PG8_LDB(B1, 1, 1); PG8_SCHED; PG8_LDA(At, 1, 0); PG8_STAGE(PG8_SA(0, 1), a2 + hstep, voffA);
	v_mfma_f32_16x16x32_bf16 v[72:75], v[166:169], v[214:217], v[72:75]
	v_mfma_f32_16x16x32_bf16 v[64:67], v[174:177], v[214:217], v[64:67]
	s_setprio 0
	s_add_i32 s24, s24, s30
	v_lshl_add_u64 v[190:191], s[10:11], 0, v[132:133]
	s_mov_b32 m0, s24
	ds_read_b128 v[178:181], v152 offset:16384
	ds_read_b128 v[182:185], v152 offset:17408
	ds_read_b128 v[186:189], v152 offset:18432
	ds_read_b128 v[194:197], v152 offset:19456
	ds_read_b128 v[202:205], v152 offset:20480
	ds_read_b128 v[206:209], v152 offset:21504
	ds_read_b128 v[210:213], v152 offset:22528
	ds_read_b128 v[214:217], v152 offset:23552
	global_load_lds_dwordx4 v[190:191], off
	s_add_i32 m0, s24, 0x2000
	s_add_u32 s66, s10, 0x80000
	v_lshl_add_u64 v[218:219], s[10:11], 0, v[128:129]
	s_addc_u32 s67, s11, 0
	s_add_i32 s24, s25, s30
	global_load_lds_dwordx4 v[218:219], off
	v_lshl_add_u64 v[220:221], s[66:67], 0, v[132:133]
	s_mov_b32 m0, s24
	v_lshl_add_u64 v[230:231], s[12:13], 0, v[130:131]
	global_load_lds_dwordx4 v[220:221], off
	s_add_i32 m0, s24, 0x2000
	v_lshl_add_u64 v[220:221], s[66:67], 0, v[128:129]
	global_load_lds_dwordx4 v[220:221], off
	s_mov_b32 m0, s31
	v_lshl_add_u64 v[220:221], s[12:13], 0, v[134:135]
	global_load_lds_dwordx4 v[220:221], off
	s_mov_b32 m0, s34
	s_nop 0
	global_load_lds_dwordx4 v[230:231], off
	s_waitcnt vmcnt(8)
	s_waitcnt lgkmcnt(0)
	s_barrier
	s_setprio 1
	s_waitcnt lgkmcnt(0)
	v_mfma_f32_16x16x32_bf16 v[60:63], v[140:143], v[178:181], v[60:63]
	v_mfma_f32_16x16x32_bf16 v[52:55], v[154:157], v[178:181], v[52:55]
	v_mfma_f32_16x16x32_bf16 v[44:47], v[140:143], v[186:189], v[44:47]
	v_mfma_f32_16x16x32_bf16 v[36:39], v[154:157], v[186:189], v[36:39]
	v_mfma_f32_16x16x32_bf16 v[28:31], v[140:143], v[202:205], v[28:31]
	v_mfma_f32_16x16x32_bf16 v[20:23], v[154:157], v[202:205], v[20:23]
	v_mfma_f32_16x16x32_bf16 v[12:15], v[140:143], v[210:213], v[12:15]
	v_mfma_f32_16x16x32_bf16 v[4:7], v[154:157], v[210:213], v[4:7]
	v_mfma_f32_16x16x32_bf16 v[60:63], v[144:147], v[182:185], v[60:63]
	v_mfma_f32_16x16x32_bf16 v[52:55], v[158:161], v[182:185], v[52:55]
	v_mfma_f32_16x16x32_bf16 v[44:47], v[144:147], v[194:197], v[44:47]
	v_mfma_f32_16x16x32_bf16 v[36:39], v[158:161], v[194:197], v[36:39]
	v_mfma_f32_16x16x32_bf16 v[28:31], v[144:147], v[206:209], v[28:31]
	v_mfma_f32_16x16x32_bf16 v[20:23], v[158:161], v[206:209], v[20:23]
	v_mfma_f32_16x16x32_bf16 v[12:15], v[144:147], v[214:217], v[12:15]
	v_mfma_f32_16x16x32_bf16 v[4:7], v[158:161], v[214:217], v[4:7]
	s_setprio 0
	s_setprio 1
	v_mfma_f32_16x16x32_bf16 v[56:59], v[162:165], v[178:181], v[56:59]
	v_mfma_f32_16x16x32_bf16 v[48:51], v[170:173], v[178:181], v[48:51]
	v_mfma_f32_16x16x32_bf16 v[40:43], v[162:165], v[186:189], v[40:43]
	v_mfma_f32_16x16x32_bf16 v[32:35], v[170:173], v[186:189], v[32:35]
	v_mfma_f32_16x16x32_bf16 v[24:27], v[162:165], v[202:205], v[24:27]
	v_mfma_f32_16x16x32_bf16 v[16:19], v[170:173], v[202:205], v[16:19]
	v_mfma_f32_16x16x32_bf16 v[8:11], v[162:165], v[210:213], v[8:11]
	v_mfma_f32_16x16x32_bf16 v[0:3], v[170:173], v[210:213], v[0:3]
	v_mfma_f32_16x16x32_bf16 v[56:59], v[166:169], v[182:185], v[56:59]
	v_mfma_f32_16x16x32_bf16 v[48:51], v[174:177], v[182:185], v[48:51]
	v_mfma_f32_16x16x32_bf16 v[40:43], v[166:169], v[194:197], v[40:43]
	v_mfma_f32_16x16x32_bf16 v[32:35], v[174:177], v[194:197], v[32:35]
	v_mfma_f32_16x16x32_bf16 v[24:27], v[166:169], v[206:209], v[24:27]
	v_mfma_f32_16x16x32_bf16 v[16:19], v[174:177], v[206:209], v[16:19]
	s_barrier
	v_mfma_f32_16x16x32_bf16 v[8:11], v[166:169], v[214:217], v[8:11]
	v_mfma_f32_16x16x32_bf16 v[0:3], v[174:177], v[214:217], v[0:3]
	s_setprio 0
	s_add_i32 s24, 0, 0x18000
	v_add_u32_e32 v148, 0x18000, v151
	s_add_i32 s25, 0, 0x1c000
	ds_read_b128 v[140:143], v148
	ds_read_b128 v[144:147], v148 offset:1024
	ds_read_b128 v[154:157], v148 offset:2048
	ds_read_b128 v[158:161], v148 offset:3072
	v_add_u32_e32 v148, 0x1c000, v151
	ds_read_b128 v[162:165], v148
	ds_read_b128 v[166:169], v148 offset:1024
	ds_read_b128 v[170:173], v148 offset:2048
	ds_read_b128 v[174:177], v148 offset:3072
	s_add_u32 s12, s12, 0x80000
	s_addc_u32 s13, s13, 0
	s_mov_b32 m0, s36
	v_lshl_add_u64 v[232:233], s[12:13], 0, v[134:135]
	ds_read_b128 v[178:181], v152 offset:32768
	ds_read_b128 v[182:185], v152 offset:33792
	ds_read_b128 v[186:189], v152 offset:34816
	ds_read_b128 v[194:197], v152 offset:35840
	ds_read_b128 v[202:205], v152 offset:36864
	ds_read_b128 v[206:209], v152 offset:37888
	ds_read_b128 v[210:213], v152 offset:38912
	ds_read_b128 v[214:217], v152 offset:39936
	global_load_lds_dwordx4 v[232:233], off
	s_mov_b32 m0, s37
	v_lshl_add_u64 v[232:233], s[12:13], 0, v[130:131]
	global_load_lds_dwordx4 v[232:233], off
	s_waitcnt vmcnt(8)
	s_waitcnt lgkmcnt(0)
	s_barrier
; #define PG8_STAGE(bufoff, gbase, voff) do { _Pragma("unroll") for (int _i = 0; _i < 2; ++_i) \
;         __builtin_amdgcn_global_load_lds((const unsigned*)((const char*)(gbase) + (voff)[_i]), (PG8_LAS unsigned*)(lds + (bufoff) + ldsw + _i * 8192), 16, 0, 0); } while (0)
; #define PG8_LDA(dst, b, h) do { _Pragma("unroll") for (int m = 0; m < 4; ++m) _Pragma("unroll") for (int k = 0; k < 2; ++k) dst[m][k] = *(const PG8_LAS bf16x8*)(lds + PG8_SA(b, h) + aoff + m * 2048 + k * 1024); } while (0)
; #define PG8_MMA(ai, bj, At, Bt) do { __builtin_amdgcn_s_setprio(1); _Pragma("unroll") for (int m = 0; m < 4; ++m) _Pragma("unroll") for (int n = 0; n < 2; ++n) _Pragma("unroll") for (int k = 0; k < 2; ++k) \
;         acc[ai][bj][m][n] = __builtin_amdgcn_mfma_f32_16x16x32_bf16(Bt[n][k], At[m][k], acc[ai][bj][m][n], 0, 0, 0); __builtin_amdgcn_s_setprio(0); } while (0)
; #define PG8_WAIT_V(n) asm volatile("s_waitcnt vmcnt(" #n ")" ::: "memory")
; #define PG8_WAIT_L(n) asm volatile("s_waitcnt lgkmcnt(" #n ")" ::: "memory")
; #define PG8_BAR __builtin_amdgcn_s_barrier()
; #define PG8_SCHED __builtin_amdgcn_sched_barrier(0)
; template <class Epi, class Sched, bool ALIGN_EPI = false, bool SP2 = false>
; __device__ __forceinline__ void gemm_phase(PG8_LAS unsigned char* lds, const Gemm g, const Sched& S, const Epi& E) {
;     ...
;             PG8_WAIT_V(8); PG8_WAIT_L(0); PG8_BAR; PG8_MMA(0, 0, At, B0); PG8_MMA(0, 1, At, B1); PG8_BAR; PG8_SCHED;
;             PG8_LDA(At, 1, 1); PG8_STAGE(PG8_SB(1, 0), b3, voffB); PG8_STAGE(PG8_SB(1, 1), b3 + hstep, voffB); PG8_STAGE(PG8_SA(1, 0), a3, voffA);
;             PG8_WAIT_V(8); PG8_WAIT_L(0); PG8_BAR; PG8_MMA(1, 0, At, B0); PG8_MMA(1, 1, At, B1); PG8_BAR; PG8_SCHED;
;     ...
;         if constexpr (ALIGN_EPI) { if (wr == 0) PG8_BAR; }
	s_setprio 1
	s_waitcnt lgkmcnt(0)
	v_mfma_f32_16x16x32_bf16 v[124:127], v[140:143], v[178:181], v[124:127]
	v_mfma_f32_16x16x32_bf16 v[112:115], v[154:157], v[178:181], v[112:115]
	v_mfma_f32_16x16x32_bf16 v[108:111], v[140:143], v[186:189], v[108:111]
	v_mfma_f32_16x16x32_bf16 v[100:103], v[154:157], v[186:189], v[100:103]
	v_mfma_f32_16x16x32_bf16 v[92:95], v[140:143], v[202:205], v[92:95]
	v_mfma_f32_16x16x32_bf16 v[84:87], v[154:157], v[202:205], v[84:87]
	v_mfma_f32_16x16x32_bf16 v[76:79], v[140:143], v[210:213], v[76:79]
	v_mfma_f32_16x16x32_bf16 v[68:71], v[154:157], v[210:213], v[68:71]
	v_mfma_f32_16x16x32_bf16 v[124:127], v[144:147], v[182:185], v[124:127]
	v_mfma_f32_16x16x32_bf16 v[112:115], v[158:161], v[182:185], v[112:115]
	v_mfma_f32_16x16x32_bf16 v[108:111], v[144:147], v[194:197], v[108:111]
	v_mfma_f32_16x16x32_bf16 v[100:103], v[158:161], v[194:197], v[100:103]
	v_mfma_f32_16x16x32_bf16 v[92:95], v[144:147], v[206:209], v[92:95]
	v_mfma_f32_16x16x32_bf16 v[84:87], v[158:161], v[206:209], v[84:87]
	v_mfma_f32_16x16x32_bf16 v[76:79], v[144:147], v[214:217], v[76:79]
	v_mfma_f32_16x16x32_bf16 v[68:71], v[158:161], v[214:217], v[68:71]
	s_setprio 0
	s_setprio 1
	v_mfma_f32_16x16x32_bf16 v[120:123], v[162:165], v[178:181], v[120:123]
	v_mfma_f32_16x16x32_bf16 v[116:119], v[170:173], v[178:181], v[116:119]
	v_mfma_f32_16x16x32_bf16 v[104:107], v[162:165], v[186:189], v[104:107]
	v_mfma_f32_16x16x32_bf16 v[96:99], v[170:173], v[186:189], v[96:99]
	v_mfma_f32_16x16x32_bf16 v[88:91], v[162:165], v[202:205], v[88:91]
	v_mfma_f32_16x16x32_bf16 v[80:83], v[170:173], v[202:205], v[80:83]
	v_mfma_f32_16x16x32_bf16 v[72:75], v[162:165], v[210:213], v[72:75]
	v_mfma_f32_16x16x32_bf16 v[64:67], v[170:173], v[210:213], v[64:67]
	v_mfma_f32_16x16x32_bf16 v[120:123], v[166:169], v[182:185], v[120:123]
	v_mfma_f32_16x16x32_bf16 v[116:119], v[174:177], v[182:185], v[116:119]
	v_mfma_f32_16x16x32_bf16 v[104:107], v[166:169], v[194:197], v[104:107]
	v_mfma_f32_16x16x32_bf16 v[96:99], v[174:177], v[194:197], v[96:99]
	v_mfma_f32_16x16x32_bf16 v[88:91], v[166:169], v[206:209], v[88:91]
	v_mfma_f32_16x16x32_bf16 v[80:83], v[174:177], v[206:209], v[80:83]
	s_barrier
	v_mfma_f32_16x16x32_bf16 v[72:75], v[166:169], v[214:217], v[72:75]
	v_mfma_f32_16x16x32_bf16 v[64:67], v[174:177], v[214:217], v[64:67]
	s_setprio 0
	s_add_i32 s12, s24, s30
	v_lshl_add_u64 v[190:191], v[190:191], 0, s[16:17]
	s_mov_b32 m0, s12
	ds_read_b128 v[178:181], v152 offset:49152
	ds_read_b128 v[182:185], v152 offset:50176
	ds_read_b128 v[186:189], v152 offset:51200
	ds_read_b128 v[194:197], v152 offset:52224
	ds_read_b128 v[202:205], v152 offset:53248
	ds_read_b128 v[206:209], v152 offset:54272
	ds_read_b128 v[210:213], v152 offset:55296
	ds_read_b128 v[214:217], v152 offset:56320
	global_load_lds_dwordx4 v[190:191], off
	s_add_i32 m0, s12, 0x2000
	s_add_u32 s10, s10, 0x80080
	v_lshl_add_u64 v[190:191], v[218:219], 0, s[16:17]
	s_addc_u32 s11, s11, 0
	s_add_i32 s12, s25, s30
	global_load_lds_dwordx4 v[190:191], off
	s_mov_b32 m0, s12
	v_lshl_add_u64 v[190:191], s[10:11], 0, v[132:133]
	global_load_lds_dwordx4 v[190:191], off
	s_add_i32 m0, s12, 0x2000
	v_lshl_add_u64 v[190:191], s[10:11], 0, v[128:129]
	global_load_lds_dwordx4 v[190:191], off
	s_mov_b32 m0, s56
	v_lshl_add_u64 v[190:191], v[220:221], 0, s[16:17]
	global_load_lds_dwordx4 v[190:191], off
	s_mov_b32 m0, s57
	v_lshl_add_u64 v[190:191], v[230:231], 0, s[16:17]
	global_load_lds_dwordx4 v[190:191], off
	s_waitcnt vmcnt(8)
	s_waitcnt lgkmcnt(0)
	s_barrier
	s_setprio 1
	s_waitcnt lgkmcnt(0)
	v_mfma_f32_16x16x32_bf16 v[60:63], v[140:143], v[178:181], v[60:63]
	v_mfma_f32_16x16x32_bf16 v[52:55], v[154:157], v[178:181], v[52:55]
	v_mfma_f32_16x16x32_bf16 v[44:47], v[140:143], v[186:189], v[44:47]
	v_mfma_f32_16x16x32_bf16 v[36:39], v[154:157], v[186:189], v[36:39]
	v_mfma_f32_16x16x32_bf16 v[28:31], v[140:143], v[202:205], v[28:31]
	v_mfma_f32_16x16x32_bf16 v[20:23], v[154:157], v[202:205], v[20:23]
	v_mfma_f32_16x16x32_bf16 v[12:15], v[140:143], v[210:213], v[12:15]
	v_mfma_f32_16x16x32_bf16 v[4:7], v[154:157], v[210:213], v[4:7]
	v_mfma_f32_16x16x32_bf16 v[60:63], v[144:147], v[182:185], v[60:63]
	v_mfma_f32_16x16x32_bf16 v[52:55], v[158:161], v[182:185], v[52:55]
	v_mfma_f32_16x16x32_bf16 v[44:47], v[144:147], v[194:197], v[44:47]
	v_mfma_f32_16x16x32_bf16 v[36:39], v[158:161], v[194:197], v[36:39]
	v_mfma_f32_16x16x32_bf16 v[28:31], v[144:147], v[206:209], v[28:31]
	v_mfma_f32_16x16x32_bf16 v[20:23], v[158:161], v[206:209], v[20:23]
	v_mfma_f32_16x16x32_bf16 v[12:15], v[144:147], v[214:217], v[12:15]
	v_mfma_f32_16x16x32_bf16 v[4:7], v[158:161], v[214:217], v[4:7]
	s_setprio 0
	s_setprio 1
	v_mfma_f32_16x16x32_bf16 v[56:59], v[162:165], v[178:181], v[56:59]
	v_mfma_f32_16x16x32_bf16 v[48:51], v[170:173], v[178:181], v[48:51]
	v_mfma_f32_16x16x32_bf16 v[40:43], v[162:165], v[186:189], v[40:43]
	v_mfma_f32_16x16x32_bf16 v[32:35], v[170:173], v[186:189], v[32:35]
	v_mfma_f32_16x16x32_bf16 v[24:27], v[162:165], v[202:205], v[24:27]
	v_mfma_f32_16x16x32_bf16 v[16:19], v[170:173], v[202:205], v[16:19]
	v_mfma_f32_16x16x32_bf16 v[8:11], v[162:165], v[210:213], v[8:11]
	v_mfma_f32_16x16x32_bf16 v[0:3], v[170:173], v[210:213], v[0:3]
	v_mfma_f32_16x16x32_bf16 v[56:59], v[166:169], v[182:185], v[56:59]
	v_mfma_f32_16x16x32_bf16 v[48:51], v[174:177], v[182:185], v[48:51]
	v_mfma_f32_16x16x32_bf16 v[40:43], v[166:169], v[194:197], v[40:43]
	v_mfma_f32_16x16x32_bf16 v[32:35], v[174:177], v[194:197], v[32:35]
	v_mfma_f32_16x16x32_bf16 v[24:27], v[166:169], v[206:209], v[24:27]
	v_mfma_f32_16x16x32_bf16 v[16:19], v[174:177], v[206:209], v[16:19]
	s_barrier
	v_mfma_f32_16x16x32_bf16 v[8:11], v[166:169], v[214:217], v[8:11]
	v_mfma_f32_16x16x32_bf16 v[0:3], v[174:177], v[214:217], v[0:3]
	s_setprio 0
	s_add_i32 s64, s64, 2
	s_add_u32 s0, s0, 0x100
	s_addc_u32 s1, s1, 0
	s_add_u32 s62, s62, 0x100
	s_addc_u32 s63, s63, 0
	s_cmp_gt_u32 s64, 29
	s_cbranch_scc0 .LBB0_730
	s_and_b64 vcc, exec, s[44:45]
	s_cbranch_vccz .LBB0_733
	s_barrier

; #define PG8_STAGE(bufoff, gbase, voff) do { _Pragma("unroll") for (int _i = 0; _i < 2; ++_i) \
;         __builtin_amdgcn_global_load_lds((const unsigned*)((const char*)(gbase) + (voff)[_i]), (PG8_LAS unsigned*)(lds + (bufoff) + ldsw + _i * 8192), 16, 0, 0); } while (0)
; #define PG8_LDA(dst, b, h) do { _Pragma("unroll") for (int m = 0; m < 4; ++m) _Pragma("unroll") for (int k = 0; k < 2; ++k) dst[m][k] = *(const PG8_LAS bf16x8*)(lds + PG8_SA(b, h) + aoff + m * 2048 + k * 1024); } while (0)
; #define PG8_LDB(dst, b, h) do { _Pragma("unroll") for (int n = 0; n < 2; ++n) _Pragma("unroll") for (int k = 0; k < 2; ++k) dst[n][k] = *(const PG8_LAS bf16x8*)(lds + PG8_SB(b, h) + boff + n * 2048 + k * 1024); } while (0)
; #define PG8_WAIT_V(n) asm volatile("s_waitcnt vmcnt(" #n ")" ::: "memory")
; #define PG8_WAIT_L(n) asm volatile("s_waitcnt lgkmcnt(" #n ")" ::: "memory")
; #define PG8_BAR __builtin_amdgcn_s_barrier()
; #define PG8_SCHED __builtin_amdgcn_sched_barrier(0)
; template <class Epi, class Sched, bool ALIGN_EPI = false, bool SP2 = false>
; __device__ __forceinline__ void gemm_phase(PG8_LAS unsigned char* lds, const Gemm g, const Sched& S, const Epi& E) {
;     ...
;         const char* nA = has_next ? (const char*)g.A + (size_t)nxt.pm * tstep : cA; const char* nB = has_next ? (const char*)g.Bt + (size_t)nxt.pn * tstep : cB;
;         for (int t = 0; t < nt; t += 2) {
;             if constexpr (Epi::MID_HOOK) { if (t == Epi::MID_T) E.mid(acc, cur, wr, wc, fr, fq); }
;             const bool last = (t == nt - 2);
;             const char* a1 = cA + (size_t)(t + 1) * kstep;
;             const char* a2 = last ? nA : cA + (size_t)(t + 2) * kstep; const char* b2 = last ? nB : cB + (size_t)(t + 2) * kstep;
;             const char* a3 = a2 + kstep; const char* b3 = b2 + kstep;
;             if (last && has_next) S.a_ready(nxt);
;             if constexpr (SP2) {
;             PG8_LDB(B0, 0, 0); PG8_LDB(B1, 0, 1); PG8_SCHED; PG8_LDA(At, 0, 0); PG8_STAGE(PG8_SA(1, 1), a1 + hstep, voffA);
;             PG8_WAIT_V(8); PG8_WAIT_L(0); PG8_BAR; PG8_MMA(0, 0, At, B0); PG8_MMA(0, 1, At, B1); PG8_BAR; PG8_SCHED;
;             PG8_LDA(At, 0, 1); PG8_STAGE(PG8_SB(0, 0), b2, voffB); PG8_STAGE(PG8_SB(0, 1), b2 + hstep, voffB); PG8_STAGE(PG8_SA(0, 0), a2, voffA);
;             PG8_WAIT_V(8); PG8_WAIT_L(0); PG8_BAR; PG8_MMA(1, 0, At, B0); PG8_MMA(1, 1, At, B1); PG8_BAR; PG8_SCHED;
.LBB0_816:
	s_add_u32 s59, s30, 0x100
	s_addc_u32 s60, s31, 0
	s_mov_b32 s61, -2
	s_waitcnt lgkmcnt(0)
	v_lshl_add_u64 v[168:169], s[18:19], 0, v[160:161]
	s_add_i32 m0, s2, 0xc000
	global_load_lds_dwordx4 v[168:169], off
	s_add_i32 m0, s2, 0xe000
	v_lshl_add_u64 v[168:169], s[18:19], 0, v[162:163]
	global_load_lds_dwordx4 v[168:169], off
	s_add_u32 s30, s18, 0x100
	s_addc_u32 s31, s19, 0
	s_add_i32 s24, 0, 0x10000
	s_cmpk_eq_i32 s61, 0x54
	s_cselect_b32 s39, s5, s31
	s_cselect_b32 s38, s4, s30
	s_cselect_b32 s37, s15, s60
	s_cselect_b32 s36, s14, s59
	s_add_i32 s25, 0, 0x14000
	s_waitcnt vmcnt(8)
	s_waitcnt lgkmcnt(0)
	s_barrier
	s_setprio 1
	s_waitcnt lgkmcnt(0)
	v_mfma_f32_16x16x32_bf16 v[124:127], v[128:131], v[178:181], 0
	v_mfma_f32_16x16x32_bf16 v[120:123], v[136:139], v[178:181], 0
	v_mfma_f32_16x16x32_bf16 v[108:111], v[128:131], v[186:189], 0
	v_mfma_f32_16x16x32_bf16 v[104:107], v[136:139], v[186:189], 0
	v_mfma_f32_16x16x32_bf16 v[92:95], v[128:131], v[202:205], 0
	v_mfma_f32_16x16x32_bf16 v[88:91], v[136:139], v[202:205], 0
	v_mfma_f32_16x16x32_bf16 v[76:79], v[128:131], v[210:213], 0
	v_mfma_f32_16x16x32_bf16 v[72:75], v[136:139], v[210:213], 0
	v_mfma_f32_16x16x32_bf16 v[124:127], v[132:135], v[182:185], v[124:127]
	v_mfma_f32_16x16x32_bf16 v[120:123], v[140:143], v[182:185], v[120:123]
	v_mfma_f32_16x16x32_bf16 v[108:111], v[132:135], v[194:197], v[108:111]
	v_mfma_f32_16x16x32_bf16 v[104:107], v[140:143], v[194:197], v[104:107]
	v_mfma_f32_16x16x32_bf16 v[92:95], v[132:135], v[206:209], v[92:95]
	v_mfma_f32_16x16x32_bf16 v[88:91], v[140:143], v[206:209], v[88:91]
	v_mfma_f32_16x16x32_bf16 v[76:79], v[132:135], v[214:217], v[76:79]
	v_mfma_f32_16x16x32_bf16 v[72:75], v[140:143], v[214:217], v[72:75]
	s_setprio 0
	s_setprio 1
	v_mfma_f32_16x16x32_bf16 v[116:119], v[144:147], v[178:181], 0
	v_mfma_f32_16x16x32_bf16 v[112:115], v[164:167], v[178:181], 0
	v_mfma_f32_16x16x32_bf16 v[100:103], v[144:147], v[186:189], 0
	v_mfma_f32_16x16x32_bf16 v[96:99], v[164:167], v[186:189], 0
	v_mfma_f32_16x16x32_bf16 v[84:87], v[144:147], v[202:205], 0
	v_mfma_f32_16x16x32_bf16 v[80:83], v[164:167], v[202:205], 0
	v_mfma_f32_16x16x32_bf16 v[68:71], v[144:147], v[210:213], 0
	v_mfma_f32_16x16x32_bf16 v[64:67], v[164:167], v[210:213], 0
	v_mfma_f32_16x16x32_bf16 v[116:119], v[148:151], v[182:185], v[116:119]
	v_mfma_f32_16x16x32_bf16 v[112:115], v[174:177], v[182:185], v[112:115]
	v_mfma_f32_16x16x32_bf16 v[100:103], v[148:151], v[194:197], v[100:103]
	v_mfma_f32_16x16x32_bf16 v[96:99], v[174:177], v[194:197], v[96:99]
	v_mfma_f32_16x16x32_bf16 v[84:87], v[148:151], v[206:209], v[84:87]
	v_mfma_f32_16x16x32_bf16 v[80:83], v[174:177], v[206:209], v[80:83]
	s_barrier
	v_mfma_f32_16x16x32_bf16 v[68:71], v[148:151], v[214:217], v[68:71]
	v_mfma_f32_16x16x32_bf16 v[64:67], v[174:177], v[214:217], v[64:67]
	s_setprio 0
	s_add_i32 s18, s24, s43
	v_lshl_add_u64 v[168:169], s[36:37], 0, v[156:157]
	s_mov_b32 m0, s18
	ds_read_b128 v[178:181], v173 offset:16384
	ds_read_b128 v[182:185], v173 offset:17408
	ds_read_b128 v[186:189], v173 offset:18432
	ds_read_b128 v[194:197], v173 offset:19456
	ds_read_b128 v[202:205], v173 offset:20480
	ds_read_b128 v[206:209], v173 offset:21504
	ds_read_b128 v[210:213], v173 offset:22528
	ds_read_b128 v[214:217], v173 offset:23552
	global_load_lds_dwordx4 v[168:169], off
	s_add_i32 m0, s18, 0x2000
	s_add_u32 s18, s36, 0x160000
	v_lshl_add_u64 v[190:191], s[36:37], 0, v[152:153]
	s_addc_u32 s19, s37, 0
	s_add_i32 s24, s25, s43
	global_load_lds_dwordx4 v[190:191], off
	v_lshl_add_u64 v[218:219], s[18:19], 0, v[156:157]
	s_mov_b32 m0, s24
	v_lshl_add_u64 v[220:221], s[38:39], 0, v[154:155]
	global_load_lds_dwordx4 v[218:219], off
	s_add_i32 m0, s24, 0x2000
	v_lshl_add_u64 v[218:219], s[18:19], 0, v[152:153]
	global_load_lds_dwordx4 v[218:219], off
	s_mov_b32 m0, s2
	v_lshl_add_u64 v[218:219], s[38:39], 0, v[158:159]
	global_load_lds_dwordx4 v[218:219], off
	s_mov_b32 m0, s44
	s_nop 0
	global_load_lds_dwordx4 v[220:221], off
	s_waitcnt vmcnt(8)
	s_waitcnt lgkmcnt(0)
	s_barrier
	s_setprio 1
	s_waitcnt lgkmcnt(0)
	v_mfma_f32_16x16x32_bf16 v[60:63], v[128:131], v[178:181], 0
	v_mfma_f32_16x16x32_bf16 v[56:59], v[136:139], v[178:181], 0
	v_mfma_f32_16x16x32_bf16 v[44:47], v[128:131], v[186:189], 0
	v_mfma_f32_16x16x32_bf16 v[40:43], v[136:139], v[186:189], 0
	v_mfma_f32_16x16x32_bf16 v[28:31], v[128:131], v[202:205], 0
	v_mfma_f32_16x16x32_bf16 v[24:27], v[136:139], v[202:205], 0
	v_mfma_f32_16x16x32_bf16 v[12:15], v[128:131], v[210:213], 0
	v_mfma_f32_16x16x32_bf16 v[8:11], v[136:139], v[210:213], 0
	v_mfma_f32_16x16x32_bf16 v[60:63], v[132:135], v[182:185], v[60:63]
	v_mfma_f32_16x16x32_bf16 v[56:59], v[140:143], v[182:185], v[56:59]
	v_mfma_f32_16x16x32_bf16 v[44:47], v[132:135], v[194:197], v[44:47]
	v_mfma_f32_16x16x32_bf16 v[40:43], v[140:143], v[194:197], v[40:43]
	v_mfma_f32_16x16x32_bf16 v[28:31], v[132:135], v[206:209], v[28:31]
	v_mfma_f32_16x16x32_bf16 v[24:27], v[140:143], v[206:209], v[24:27]
	v_mfma_f32_16x16x32_bf16 v[12:15], v[132:135], v[214:217], v[12:15]
	v_mfma_f32_16x16x32_bf16 v[8:11], v[140:143], v[214:217], v[8:11]
	s_setprio 0
	s_setprio 1
	v_mfma_f32_16x16x32_bf16 v[52:55], v[144:147], v[178:181], 0
	v_mfma_f32_16x16x32_bf16 v[48:51], v[164:167], v[178:181], 0
	v_mfma_f32_16x16x32_bf16 v[36:39], v[144:147], v[186:189], 0
	v_mfma_f32_16x16x32_bf16 v[32:35], v[164:167], v[186:189], 0
	v_mfma_f32_16x16x32_bf16 v[20:23], v[144:147], v[202:205], 0
	v_mfma_f32_16x16x32_bf16 v[16:19], v[164:167], v[202:205], 0
	v_mfma_f32_16x16x32_bf16 v[4:7], v[144:147], v[210:213], 0
	v_mfma_f32_16x16x32_bf16 v[0:3], v[164:167], v[210:213], 0
	v_mfma_f32_16x16x32_bf16 v[52:55], v[148:151], v[182:185], v[52:55]
	v_mfma_f32_16x16x32_bf16 v[48:51], v[174:177], v[182:185], v[48:51]
	v_mfma_f32_16x16x32_bf16 v[36:39], v[148:151], v[194:197], v[36:39]
	v_mfma_f32_16x16x32_bf16 v[32:35], v[174:177], v[194:197], v[32:35]
	v_mfma_f32_16x16x32_bf16 v[20:23], v[148:151], v[206:209], v[20:23]
	v_mfma_f32_16x16x32_bf16 v[16:19], v[174:177], v[206:209], v[16:19]
	s_barrier
; #define PG8_STAGE(bufoff, gbase, voff) do { _Pragma("unroll") for (int _i = 0; _i < 2; ++_i) \
;         __builtin_amdgcn_global_load_lds((const unsigned*)((const char*)(gbase) + (voff)[_i]), (PG8_LAS unsigned*)(lds + (bufoff) + ldsw + _i * 8192), 16, 0, 0); } while (0)
; #define PG8_LDA(dst, b, h) do { _Pragma("unroll") for (int m = 0; m < 4; ++m) _Pragma("unroll") for (int k = 0; k < 2; ++k) dst[m][k] = *(const PG8_LAS bf16x8*)(lds + PG8_SA(b, h) + aoff + m * 2048 + k * 1024); } while (0)
; #define PG8_LDB(dst, b, h) do { _Pragma("unroll") for (int n = 0; n < 2; ++n) _Pragma("unroll") for (int k = 0; k < 2; ++k) dst[n][k] = *(const PG8_LAS bf16x8*)(lds + PG8_SB(b, h) + boff + n * 2048 + k * 1024); } while (0)
; #define PG8_MMA(ai, bj, At, Bt) do { __builtin_amdgcn_s_setprio(1); _Pragma("unroll") for (int m = 0; m < 4; ++m) _Pragma("unroll") for (int n = 0; n < 2; ++n) _Pragma("unroll") for (int k = 0; k < 2; ++k) \
;         acc[ai][bj][m][n] = __builtin_amdgcn_mfma_f32_16x16x32_bf16(Bt[n][k], At[m][k], acc[ai][bj][m][n], 0, 0, 0); __builtin_amdgcn_s_setprio(0); } while (0)
; #define PG8_WAIT_V(n) asm volatile("s_waitcnt vmcnt(" #n ")" ::: "memory")
; #define PG8_WAIT_L(n) asm volatile("s_waitcnt lgkmcnt(" #n ")" ::: "memory")
; #define PG8_BAR __builtin_amdgcn_s_barrier()
; #define PG8_SCHED __builtin_amdgcn_sched_barrier(0)
; template <class Epi, class Sched, bool ALIGN_EPI = false, bool SP2 = false>
; __device__ __forceinline__ void gemm_phase(PG8_LAS unsigned char* lds, const Gemm g, const Sched& S, const Epi& E) {
;     ...
;             PG8_WAIT_V(8); PG8_WAIT_L(0); PG8_BAR; PG8_MMA(1, 0, At, B0); PG8_MMA(1, 1, At, B1); PG8_BAR; PG8_SCHED;
;             PG8_LDB(B0, 1, 0); PG8_LDB(B1, 1, 1); PG8_SCHED; PG8_LDA(At, 1, 0); PG8_STAGE(PG8_SA(0, 1), a2 + hstep, voffA);
;             PG8_WAIT_V(8); PG8_WAIT_L(0); PG8_BAR; PG8_MMA(0, 0, At, B0); PG8_MMA(0, 1, At, B1); PG8_BAR; PG8_SCHED;
;             PG8_LDA(At, 1, 1); PG8_STAGE(PG8_SB(1, 0), b3, voffB); PG8_STAGE(PG8_SB(1, 1), b3 + hstep, voffB); PG8_STAGE(PG8_SA(1, 0), a3, voffA);
	v_mfma_f32_16x16x32_bf16 v[4:7], v[148:151], v[214:217], v[4:7]
	v_mfma_f32_16x16x32_bf16 v[0:3], v[174:177], v[214:217], v[0:3]
	s_setprio 0
	s_add_i32 s24, 0, 0x18000
	s_add_i32 s25, 0, 0x1c000
	v_add_u32_e32 v140, 0x18000, v172
	v_add_u32_e32 v174, 0x1c000, v172
	ds_read_b128 v[128:131], v140
	ds_read_b128 v[132:135], v140 offset:1024
	ds_read_b128 v[136:139], v140 offset:2048
	ds_read_b128 v[140:143], v140 offset:3072
	ds_read_b128 v[144:147], v174
	ds_read_b128 v[148:151], v174 offset:1024
	ds_read_b128 v[164:167], v174 offset:2048
	ds_read_b128 v[174:177], v174 offset:3072
	s_add_u32 s18, s38, 0x160000
	s_addc_u32 s19, s39, 0
	s_mov_b32 m0, s45
	v_lshl_add_u64 v[230:231], s[18:19], 0, v[158:159]
	ds_read_b128 v[178:181], v173 offset:32768
	ds_read_b128 v[182:185], v173 offset:33792
	ds_read_b128 v[186:189], v173 offset:34816
	ds_read_b128 v[194:197], v173 offset:35840
	ds_read_b128 v[202:205], v173 offset:36864
	ds_read_b128 v[206:209], v173 offset:37888
	ds_read_b128 v[210:213], v173 offset:38912
	ds_read_b128 v[214:217], v173 offset:39936
	global_load_lds_dwordx4 v[230:231], off
	s_mov_b32 m0, s46
	v_lshl_add_u64 v[230:231], s[18:19], 0, v[154:155]
	global_load_lds_dwordx4 v[230:231], off
	s_waitcnt vmcnt(8)
	s_waitcnt lgkmcnt(0)
	s_barrier
	s_setprio 1
	s_waitcnt lgkmcnt(0)
	v_mfma_f32_16x16x32_bf16 v[124:127], v[128:131], v[178:181], v[124:127]
	v_mfma_f32_16x16x32_bf16 v[120:123], v[136:139], v[178:181], v[120:123]
	v_mfma_f32_16x16x32_bf16 v[108:111], v[128:131], v[186:189], v[108:111]
	v_mfma_f32_16x16x32_bf16 v[104:107], v[136:139], v[186:189], v[104:107]
	v_mfma_f32_16x16x32_bf16 v[92:95], v[128:131], v[202:205], v[92:95]
	v_mfma_f32_16x16x32_bf16 v[88:91], v[136:139], v[202:205], v[88:91]
	v_mfma_f32_16x16x32_bf16 v[76:79], v[128:131], v[210:213], v[76:79]
	v_mfma_f32_16x16x32_bf16 v[72:75], v[136:139], v[210:213], v[72:75]
	v_mfma_f32_16x16x32_bf16 v[124:127], v[132:135], v[182:185], v[124:127]
	v_mfma_f32_16x16x32_bf16 v[120:123], v[140:143], v[182:185], v[120:123]
	v_mfma_f32_16x16x32_bf16 v[108:111], v[132:135], v[194:197], v[108:111]
	v_mfma_f32_16x16x32_bf16 v[104:107], v[140:143], v[194:197], v[104:107]
	v_mfma_f32_16x16x32_bf16 v[92:95], v[132:135], v[206:209], v[92:95]
	v_mfma_f32_16x16x32_bf16 v[88:91], v[140:143], v[206:209], v[88:91]
	v_mfma_f32_16x16x32_bf16 v[76:79], v[132:135], v[214:217], v[76:79]
	v_mfma_f32_16x16x32_bf16 v[72:75], v[140:143], v[214:217], v[72:75]
	s_setprio 0
	s_setprio 1
	v_mfma_f32_16x16x32_bf16 v[116:119], v[144:147], v[178:181], v[116:119]
	v_mfma_f32_16x16x32_bf16 v[112:115], v[164:167], v[178:181], v[112:115]
	v_mfma_f32_16x16x32_bf16 v[100:103], v[144:147], v[186:189], v[100:103]
	v_mfma_f32_16x16x32_bf16 v[96:99], v[164:167], v[186:189], v[96:99]
	v_mfma_f32_16x16x32_bf16 v[84:87], v[144:147], v[202:205], v[84:87]
	v_mfma_f32_16x16x32_bf16 v[80:83], v[164:167], v[202:205], v[80:83]
	v_mfma_f32_16x16x32_bf16 v[68:71], v[144:147], v[210:213], v[68:71]
	v_mfma_f32_16x16x32_bf16 v[64:67], v[164:167], v[210:213], v[64:67]
	v_mfma_f32_16x16x32_bf16 v[116:119], v[148:151], v[182:185], v[116:119]
	v_mfma_f32_16x16x32_bf16 v[112:115], v[174:177], v[182:185], v[112:115]
	v_mfma_f32_16x16x32_bf16 v[100:103], v[148:151], v[194:197], v[100:103]
	v_mfma_f32_16x16x32_bf16 v[96:99], v[174:177], v[194:197], v[96:99]
	v_mfma_f32_16x16x32_bf16 v[84:87], v[148:151], v[206:209], v[84:87]
	v_mfma_f32_16x16x32_bf16 v[80:83], v[174:177], v[206:209], v[80:83]
	s_barrier
	v_mfma_f32_16x16x32_bf16 v[68:71], v[148:151], v[214:217], v[68:71]
	v_mfma_f32_16x16x32_bf16 v[64:67], v[174:177], v[214:217], v[64:67]
	s_setprio 0
	s_add_i32 s18, s24, s43
	v_lshl_add_u64 v[168:169], v[168:169], 0, s[16:17]
	s_mov_b32 m0, s18
	ds_read_b128 v[178:181], v173 offset:49152
	ds_read_b128 v[182:185], v173 offset:50176
	ds_read_b128 v[186:189], v173 offset:51200
	ds_read_b128 v[194:197], v173 offset:52224
	ds_read_b128 v[202:205], v173 offset:53248
	ds_read_b128 v[206:209], v173 offset:54272
	ds_read_b128 v[210:213], v173 offset:55296
	ds_read_b128 v[214:217], v173 offset:56320
	global_load_lds_dwordx4 v[168:169], off
	s_add_i32 m0, s18, 0x2000
	s_add_u32 s18, s36, 0x160080
	v_lshl_add_u64 v[168:169], v[190:191], 0, s[16:17]
	s_addc_u32 s19, s37, 0
	s_add_i32 s24, s25, s43
	global_load_lds_dwordx4 v[168:169], off
	s_mov_b32 m0, s24
	v_lshl_add_u64 v[168:169], s[18:19], 0, v[156:157]
	global_load_lds_dwordx4 v[168:169], off
	s_add_i32 m0, s24, 0x2000
	v_lshl_add_u64 v[168:169], s[18:19], 0, v[152:153]
	global_load_lds_dwordx4 v[168:169], off
	s_mov_b32 m0, s51
	v_lshl_add_u64 v[168:169], v[218:219], 0, s[16:17]
	global_load_lds_dwordx4 v[168:169], off
	s_mov_b32 m0, s52
	v_lshl_add_u64 v[168:169], v[220:221], 0, s[16:17]
	global_load_lds_dwordx4 v[168:169], off
	s_waitcnt vmcnt(8)
	s_waitcnt lgkmcnt(0)
	s_barrier
; #define PG8_STAGE(bufoff, gbase, voff) do { _Pragma("unroll") for (int _i = 0; _i < 2; ++_i) \
;         __builtin_amdgcn_global_load_lds((const unsigned*)((const char*)(gbase) + (voff)[_i]), (PG8_LAS unsigned*)(lds + (bufoff) + ldsw + _i * 8192), 16, 0, 0); } while (0)
; #define PG8_LDA(dst, b, h) do { _Pragma("unroll") for (int m = 0; m < 4; ++m) _Pragma("unroll") for (int k = 0; k < 2; ++k) dst[m][k] = *(const PG8_LAS bf16x8*)(lds + PG8_SA(b, h) + aoff + m * 2048 + k * 1024); } while (0)
; #define PG8_LDB(dst, b, h) do { _Pragma("unroll") for (int n = 0; n < 2; ++n) _Pragma("unroll") for (int k = 0; k < 2; ++k) dst[n][k] = *(const PG8_LAS bf16x8*)(lds + PG8_SB(b, h) + boff + n * 2048 + k * 1024); } while (0)
; #define PG8_MMA(ai, bj, At, Bt) do { __builtin_amdgcn_s_setprio(1); _Pragma("unroll") for (int m = 0; m < 4; ++m) _Pragma("unroll") for (int n = 0; n < 2; ++n) _Pragma("unroll") for (int k = 0; k < 2; ++k) \
;         acc[ai][bj][m][n] = __builtin_amdgcn_mfma_f32_16x16x32_bf16(Bt[n][k], At[m][k], acc[ai][bj][m][n], 0, 0, 0); __builtin_amdgcn_s_setprio(0); } while (0)
; #define PG8_WAIT_V(n) asm volatile("s_waitcnt vmcnt(" #n ")" ::: "memory")
; template <class Epi, class Sched, bool ALIGN_EPI = false, bool SP2 = false>
; __device__ __forceinline__ void gemm_phase(PG8_LAS unsigned char* lds, const Gemm g, const Sched& S, const Epi& E) {
;     ...
;             PG8_LDB(B0, 0, 0); PG8_LDB(B1, 0, 1); PG8_SCHED; PG8_LDA(At, 0, 0); PG8_STAGE(PG8_SA(1, 1), a1 + hstep, voffA);
;             PG8_WAIT_V(8); PG8_WAIT_L(0); PG8_BAR; PG8_MMA(0, 0, At, B0); PG8_MMA(0, 1, At, B1); PG8_BAR; PG8_SCHED;
;             PG8_LDA(At, 0, 1); PG8_STAGE(PG8_SB(0, 0), b2, voffB); PG8_STAGE(PG8_SB(0, 1), b2 + hstep, voffB); PG8_STAGE(PG8_SA(0, 0), a2, voffA);
;             PG8_WAIT_V(8); PG8_WAIT_L(0); PG8_BAR; PG8_MMA(1, 0, At, B0); PG8_MMA(1, 1, At, B1); PG8_BAR; PG8_SCHED;
;             PG8_LDB(B0, 1, 0); PG8_LDB(B1, 1, 1); PG8_SCHED; PG8_LDA(At, 1, 0); PG8_STAGE(PG8_SA(0, 1), a2 + hstep, voffA);
;             PG8_WAIT_V(8); PG8_WAIT_L(0); PG8_BAR; PG8_MMA(0, 0, At, B0); PG8_MMA(0, 1, At, B1); PG8_BAR; PG8_SCHED;
;             PG8_LDA(At, 1, 1); PG8_STAGE(PG8_SB(1, 0), b3, voffB); PG8_STAGE(PG8_SB(1, 1), b3 + hstep, voffB); PG8_STAGE(PG8_SA(1, 0), a3, voffA);
;             PG8_WAIT_V(8); PG8_WAIT_L(0); PG8_BAR; PG8_MMA(1, 0, At, B0); PG8_MMA(1, 1, At, B1); PG8_BAR; PG8_SCHED;
	s_setprio 1
	s_waitcnt lgkmcnt(0)
	v_mfma_f32_16x16x32_bf16 v[60:63], v[128:131], v[178:181], v[60:63]
	v_mfma_f32_16x16x32_bf16 v[56:59], v[136:139], v[178:181], v[56:59]
	v_mfma_f32_16x16x32_bf16 v[44:47], v[128:131], v[186:189], v[44:47]
	v_mfma_f32_16x16x32_bf16 v[40:43], v[136:139], v[186:189], v[40:43]
	v_mfma_f32_16x16x32_bf16 v[28:31], v[128:131], v[202:205], v[28:31]
	v_mfma_f32_16x16x32_bf16 v[24:27], v[136:139], v[202:205], v[24:27]
	v_mfma_f32_16x16x32_bf16 v[12:15], v[128:131], v[210:213], v[12:15]
	v_mfma_f32_16x16x32_bf16 v[8:11], v[136:139], v[210:213], v[8:11]
	v_mfma_f32_16x16x32_bf16 v[60:63], v[132:135], v[182:185], v[60:63]
	v_mfma_f32_16x16x32_bf16 v[56:59], v[140:143], v[182:185], v[56:59]
	v_mfma_f32_16x16x32_bf16 v[44:47], v[132:135], v[194:197], v[44:47]
	v_mfma_f32_16x16x32_bf16 v[40:43], v[140:143], v[194:197], v[40:43]
	v_mfma_f32_16x16x32_bf16 v[28:31], v[132:135], v[206:209], v[28:31]
	v_mfma_f32_16x16x32_bf16 v[24:27], v[140:143], v[206:209], v[24:27]
	v_mfma_f32_16x16x32_bf16 v[12:15], v[132:135], v[214:217], v[12:15]
	v_mfma_f32_16x16x32_bf16 v[8:11], v[140:143], v[214:217], v[8:11]
	s_setprio 0
	s_setprio 1
	v_mfma_f32_16x16x32_bf16 v[52:55], v[144:147], v[178:181], v[52:55]
	v_mfma_f32_16x16x32_bf16 v[48:51], v[164:167], v[178:181], v[48:51]
	v_mfma_f32_16x16x32_bf16 v[36:39], v[144:147], v[186:189], v[36:39]
	v_mfma_f32_16x16x32_bf16 v[32:35], v[164:167], v[186:189], v[32:35]
	v_mfma_f32_16x16x32_bf16 v[20:23], v[144:147], v[202:205], v[20:23]
	v_mfma_f32_16x16x32_bf16 v[16:19], v[164:167], v[202:205], v[16:19]
	v_mfma_f32_16x16x32_bf16 v[4:7], v[144:147], v[210:213], v[4:7]
	v_mfma_f32_16x16x32_bf16 v[0:3], v[164:167], v[210:213], v[0:3]
	v_mfma_f32_16x16x32_bf16 v[52:55], v[148:151], v[182:185], v[52:55]
	v_mfma_f32_16x16x32_bf16 v[48:51], v[174:177], v[182:185], v[48:51]
	v_mfma_f32_16x16x32_bf16 v[36:39], v[148:151], v[194:197], v[36:39]
	v_mfma_f32_16x16x32_bf16 v[32:35], v[174:177], v[194:197], v[32:35]
	v_mfma_f32_16x16x32_bf16 v[20:23], v[148:151], v[206:209], v[20:23]
	v_mfma_f32_16x16x32_bf16 v[16:19], v[174:177], v[206:209], v[16:19]
	s_barrier
	v_mfma_f32_16x16x32_bf16 v[4:7], v[148:151], v[214:217], v[4:7]
	v_mfma_f32_16x16x32_bf16 v[0:3], v[174:177], v[214:217], v[0:3]
	s_setprio 0
	s_add_i32 s61, s61, 2
	s_add_u32 s59, s59, 0x100
	s_addc_u32 s60, s60, 0
	s_cmpk_gt_u32 s61, 0x55
	s_mov_b64 s[18:19], s[30:31]
	s_branch .LBB0_817
.LBB0_817:
	v_add_u32_e32 v140, 0x10000, v172
	v_add_u32_e32 v168, 0x14000, v172
	ds_read_b128 v[128:131], v140
	ds_read_b128 v[132:135], v140 offset:1024
	ds_read_b128 v[136:139], v140 offset:2048
	ds_read_b128 v[140:143], v140 offset:3072
	ds_read_b128 v[144:147], v168
	ds_read_b128 v[148:151], v168 offset:1024
	ds_read_b128 v[164:167], v168 offset:2048
	ds_read_b128 v[174:177], v168 offset:3072
	v_lshl_add_u64 v[168:169], s[18:19], 0, v[160:161]
	s_add_i32 m0, s2, 0xc000
	ds_read_b128 v[178:181], v173
	ds_read_b128 v[182:185], v173 offset:1024
	ds_read_b128 v[186:189], v173 offset:2048
	ds_read_b128 v[194:197], v173 offset:3072
	ds_read_b128 v[202:205], v173 offset:4096
	ds_read_b128 v[206:209], v173 offset:5120
	ds_read_b128 v[210:213], v173 offset:6144
	ds_read_b128 v[214:217], v173 offset:7168
	global_load_lds_dwordx4 v[168:169], off
	s_add_i32 m0, s2, 0xe000
	v_lshl_add_u64 v[168:169], s[18:19], 0, v[162:163]
	global_load_lds_dwordx4 v[168:169], off
	s_add_u32 s30, s18, 0x100
	s_addc_u32 s31, s19, 0
	s_add_i32 s24, 0, 0x10000
	s_cmpk_eq_i32 s61, 0x54
	s_cselect_b32 s39, s5, s31
	s_cselect_b32 s38, s4, s30
	s_cselect_b32 s37, s15, s60
	s_cselect_b32 s36, s14, s59
	s_add_i32 s25, 0, 0x14000
	s_waitcnt vmcnt(8)
	s_waitcnt lgkmcnt(0)
	s_barrier
	s_setprio 1
	s_waitcnt lgkmcnt(0)
	v_mfma_f32_16x16x32_bf16 v[124:127], v[128:131], v[178:181], v[124:127]
	v_mfma_f32_16x16x32_bf16 v[120:123], v[136:139], v[178:181], v[120:123]
	v_mfma_f32_16x16x32_bf16 v[108:111], v[128:131], v[186:189], v[108:111]
	v_mfma_f32_16x16x32_bf16 v[104:107], v[136:139], v[186:189], v[104:107]
	v_mfma_f32_16x16x32_bf16 v[92:95], v[128:131], v[202:205], v[92:95]
	v_mfma_f32_16x16x32_bf16 v[88:91], v[136:139], v[202:205], v[88:91]
	v_mfma_f32_16x16x32_bf16 v[76:79], v[128:131], v[210:213], v[76:79]
	v_mfma_f32_16x16x32_bf16 v[72:75], v[136:139], v[210:213], v[72:75]
	v_mfma_f32_16x16x32_bf16 v[124:127], v[132:135], v[182:185], v[124:127]
	v_mfma_f32_16x16x32_bf16 v[120:123], v[140:143], v[182:185], v[120:123]
	v_mfma_f32_16x16x32_bf16 v[108:111], v[132:135], v[194:197], v[108:111]
	v_mfma_f32_16x16x32_bf16 v[104:107], v[140:143], v[194:197], v[104:107]
	v_mfma_f32_16x16x32_bf16 v[92:95], v[132:135], v[206:209], v[92:95]
	v_mfma_f32_16x16x32_bf16 v[88:91], v[140:143], v[206:209], v[88:91]
	v_mfma_f32_16x16x32_bf16 v[76:79], v[132:135], v[214:217], v[76:79]
	v_mfma_f32_16x16x32_bf16 v[72:75], v[140:143], v[214:217], v[72:75]
	s_setprio 0
	s_setprio 1
	v_mfma_f32_16x16x32_bf16 v[116:119], v[144:147], v[178:181], v[116:119]
	v_mfma_f32_16x16x32_bf16 v[112:115], v[164:167], v[178:181], v[112:115]
	v_mfma_f32_16x16x32_bf16 v[100:103], v[144:147], v[186:189], v[100:103]
	v_mfma_f32_16x16x32_bf16 v[96:99], v[164:167], v[186:189], v[96:99]
	v_mfma_f32_16x16x32_bf16 v[84:87], v[144:147], v[202:205], v[84:87]
	v_mfma_f32_16x16x32_bf16 v[80:83], v[164:167], v[202:205], v[80:83]
	v_mfma_f32_16x16x32_bf16 v[68:71], v[144:147], v[210:213], v[68:71]
	v_mfma_f32_16x16x32_bf16 v[64:67], v[164:167], v[210:213], v[64:67]
	v_mfma_f32_16x16x32_bf16 v[116:119], v[148:151], v[182:185], v[116:119]
	v_mfma_f32_16x16x32_bf16 v[112:115], v[174:177], v[182:185], v[112:115]
	v_mfma_f32_16x16x32_bf16 v[100:103], v[148:151], v[194:197], v[100:103]
	v_mfma_f32_16x16x32_bf16 v[96:99], v[174:177], v[194:197], v[96:99]
	v_mfma_f32_16x16x32_bf16 v[84:87], v[148:151], v[206:209], v[84:87]
	v_mfma_f32_16x16x32_bf16 v[80:83], v[174:177], v[206:209], v[80:83]
	s_barrier
; #define PG8_STAGE(bufoff, gbase, voff) do { _Pragma("unroll") for (int _i = 0; _i < 2; ++_i) \
;         __builtin_amdgcn_global_load_lds((const unsigned*)((const char*)(gbase) + (voff)[_i]), (PG8_LAS unsigned*)(lds + (bufoff) + ldsw + _i * 8192), 16, 0, 0); } while (0)
; #define PG8_LDA(dst, b, h) do { _Pragma("unroll") for (int m = 0; m < 4; ++m) _Pragma("unroll") for (int k = 0; k < 2; ++k) dst[m][k] = *(const PG8_LAS bf16x8*)(lds + PG8_SA(b, h) + aoff + m * 2048 + k * 1024); } while (0)
; #define PG8_LDB(dst, b, h) do { _Pragma("unroll") for (int n = 0; n < 2; ++n) _Pragma("unroll") for (int k = 0; k < 2; ++k) dst[n][k] = *(const PG8_LAS bf16x8*)(lds + PG8_SB(b, h) + boff + n * 2048 + k * 1024); } while (0)
; #define PG8_MMA(ai, bj, At, Bt) do { __builtin_amdgcn_s_setprio(1); _Pragma("unroll") for (int m = 0; m < 4; ++m) _Pragma("unroll") for (int n = 0; n < 2; ++n) _Pragma("unroll") for (int k = 0; k < 2; ++k) \
;         acc[ai][bj][m][n] = __builtin_amdgcn_mfma_f32_16x16x32_bf16(Bt[n][k], At[m][k], acc[ai][bj][m][n], 0, 0, 0); __builtin_amdgcn_s_setprio(0); } while (0)
; #define PG8_WAIT_V(n) asm volatile("s_waitcnt vmcnt(" #n ")" ::: "memory")
; #define PG8_WAIT_L(n) asm volatile("s_waitcnt lgkmcnt(" #n ")" ::: "memory")
; #define PG8_BAR __builtin_amdgcn_s_barrier()
; #define PG8_SCHED __builtin_amdgcn_sched_barrier(0)
; template <class Epi, class Sched, bool ALIGN_EPI = false, bool SP2 = false>
; __device__ __forceinline__ void gemm_phase(PG8_LAS unsigned char* lds, const Gemm g, const Sched& S, const Epi& E) {
;     ...
;             PG8_WAIT_V(8); PG8_WAIT_L(0); PG8_BAR; PG8_MMA(0, 0, At, B0); PG8_MMA(0, 1, At, B1); PG8_BAR; PG8_SCHED;
;             PG8_LDA(At, 0, 1); PG8_STAGE(PG8_SB(0, 0), b2, voffB); PG8_STAGE(PG8_SB(0, 1), b2 + hstep, voffB); PG8_STAGE(PG8_SA(0, 0), a2, voffA);
;             PG8_WAIT_V(8); PG8_WAIT_L(0); PG8_BAR; PG8_MMA(1, 0, At, B0); PG8_MMA(1, 1, At, B1); PG8_BAR; PG8_SCHED;
;             PG8_LDB(B0, 1, 0); PG8_LDB(B1, 1, 1); PG8_SCHED; PG8_LDA(At, 1, 0); PG8_STAGE(PG8_SA(0, 1), a2 + hstep, voffA);
;             PG8_WAIT_V(8); PG8_WAIT_L(0); PG8_BAR; PG8_MMA(0, 0, At, B0); PG8_MMA(0, 1, At, B1); PG8_BAR; PG8_SCHED;
	v_mfma_f32_16x16x32_bf16 v[68:71], v[148:151], v[214:217], v[68:71]
	v_mfma_f32_16x16x32_bf16 v[64:67], v[174:177], v[214:217], v[64:67]
	s_setprio 0
	s_add_i32 s18, s24, s43
	v_lshl_add_u64 v[168:169], s[36:37], 0, v[156:157]
	s_mov_b32 m0, s18
	ds_read_b128 v[178:181], v173 offset:16384
	ds_read_b128 v[182:185], v173 offset:17408
	ds_read_b128 v[186:189], v173 offset:18432
	ds_read_b128 v[194:197], v173 offset:19456
	ds_read_b128 v[202:205], v173 offset:20480
	ds_read_b128 v[206:209], v173 offset:21504
	ds_read_b128 v[210:213], v173 offset:22528
	ds_read_b128 v[214:217], v173 offset:23552
	global_load_lds_dwordx4 v[168:169], off
	s_add_i32 m0, s18, 0x2000
	s_add_u32 s18, s36, 0x160000
	v_lshl_add_u64 v[190:191], s[36:37], 0, v[152:153]
	s_addc_u32 s19, s37, 0
	s_add_i32 s24, s25, s43
	global_load_lds_dwordx4 v[190:191], off
	v_lshl_add_u64 v[218:219], s[18:19], 0, v[156:157]
	s_mov_b32 m0, s24
	v_lshl_add_u64 v[220:221], s[38:39], 0, v[154:155]
	global_load_lds_dwordx4 v[218:219], off
	s_add_i32 m0, s24, 0x2000
	v_lshl_add_u64 v[218:219], s[18:19], 0, v[152:153]
	global_load_lds_dwordx4 v[218:219], off
	s_mov_b32 m0, s2
	v_lshl_add_u64 v[218:219], s[38:39], 0, v[158:159]
	global_load_lds_dwordx4 v[218:219], off
	s_mov_b32 m0, s44
	s_nop 0
	global_load_lds_dwordx4 v[220:221], off
	s_waitcnt vmcnt(8)
	s_waitcnt lgkmcnt(0)
	s_barrier
	s_setprio 1
	s_waitcnt lgkmcnt(0)
	v_mfma_f32_16x16x32_bf16 v[60:63], v[128:131], v[178:181], v[60:63]
	v_mfma_f32_16x16x32_bf16 v[56:59], v[136:139], v[178:181], v[56:59]
	v_mfma_f32_16x16x32_bf16 v[44:47], v[128:131], v[186:189], v[44:47]
	v_mfma_f32_16x16x32_bf16 v[40:43], v[136:139], v[186:189], v[40:43]
	v_mfma_f32_16x16x32_bf16 v[28:31], v[128:131], v[202:205], v[28:31]
	v_mfma_f32_16x16x32_bf16 v[24:27], v[136:139], v[202:205], v[24:27]
	v_mfma_f32_16x16x32_bf16 v[12:15], v[128:131], v[210:213], v[12:15]
	v_mfma_f32_16x16x32_bf16 v[8:11], v[136:139], v[210:213], v[8:11]
	v_mfma_f32_16x16x32_bf16 v[60:63], v[132:135], v[182:185], v[60:63]
	v_mfma_f32_16x16x32_bf16 v[56:59], v[140:143], v[182:185], v[56:59]
	v_mfma_f32_16x16x32_bf16 v[44:47], v[132:135], v[194:197], v[44:47]
	v_mfma_f32_16x16x32_bf16 v[40:43], v[140:143], v[194:197], v[40:43]
	v_mfma_f32_16x16x32_bf16 v[28:31], v[132:135], v[206:209], v[28:31]
	v_mfma_f32_16x16x32_bf16 v[24:27], v[140:143], v[206:209], v[24:27]
	v_mfma_f32_16x16x32_bf16 v[12:15], v[132:135], v[214:217], v[12:15]
	v_mfma_f32_16x16x32_bf16 v[8:11], v[140:143], v[214:217], v[8:11]
	s_setprio 0
	s_setprio 1
	v_mfma_f32_16x16x32_bf16 v[52:55], v[144:147], v[178:181], v[52:55]
	v_mfma_f32_16x16x32_bf16 v[48:51], v[164:167], v[178:181], v[48:51]
	v_mfma_f32_16x16x32_bf16 v[36:39], v[144:147], v[186:189], v[36:39]
	v_mfma_f32_16x16x32_bf16 v[32:35], v[164:167], v[186:189], v[32:35]
	v_mfma_f32_16x16x32_bf16 v[20:23], v[144:147], v[202:205], v[20:23]
	v_mfma_f32_16x16x32_bf16 v[16:19], v[164:167], v[202:205], v[16:19]
	v_mfma_f32_16x16x32_bf16 v[4:7], v[144:147], v[210:213], v[4:7]
	v_mfma_f32_16x16x32_bf16 v[0:3], v[164:167], v[210:213], v[0:3]
	v_mfma_f32_16x16x32_bf16 v[52:55], v[148:151], v[182:185], v[52:55]
	v_mfma_f32_16x16x32_bf16 v[48:51], v[174:177], v[182:185], v[48:51]
	v_mfma_f32_16x16x32_bf16 v[36:39], v[148:151], v[194:197], v[36:39]
	v_mfma_f32_16x16x32_bf16 v[32:35], v[174:177], v[194:197], v[32:35]
	v_mfma_f32_16x16x32_bf16 v[20:23], v[148:151], v[206:209], v[20:23]
	v_mfma_f32_16x16x32_bf16 v[16:19], v[174:177], v[206:209], v[16:19]
	s_barrier
	v_mfma_f32_16x16x32_bf16 v[4:7], v[148:151], v[214:217], v[4:7]
	v_mfma_f32_16x16x32_bf16 v[0:3], v[174:177], v[214:217], v[0:3]
	s_setprio 0
	s_add_i32 s24, 0, 0x18000
	s_add_i32 s25, 0, 0x1c000
	v_add_u32_e32 v140, 0x18000, v172
	v_add_u32_e32 v174, 0x1c000, v172
	ds_read_b128 v[128:131], v140
	ds_read_b128 v[132:135], v140 offset:1024
	ds_read_b128 v[136:139], v140 offset:2048
	ds_read_b128 v[140:143], v140 offset:3072
	ds_read_b128 v[144:147], v174
	ds_read_b128 v[148:151], v174 offset:1024
	ds_read_b128 v[164:167], v174 offset:2048
	ds_read_b128 v[174:177], v174 offset:3072
	s_add_u32 s18, s38, 0x160000
	s_addc_u32 s19, s39, 0
	s_mov_b32 m0, s45
	v_lshl_add_u64 v[230:231], s[18:19], 0, v[158:159]
	ds_read_b128 v[178:181], v173 offset:32768
	ds_read_b128 v[182:185], v173 offset:33792
	ds_read_b128 v[186:189], v173 offset:34816
	ds_read_b128 v[194:197], v173 offset:35840
	ds_read_b128 v[202:205], v173 offset:36864
	ds_read_b128 v[206:209], v173 offset:37888
	ds_read_b128 v[210:213], v173 offset:38912
	ds_read_b128 v[214:217], v173 offset:39936
	global_load_lds_dwordx4 v[230:231], off
	s_mov_b32 m0, s46
	v_lshl_add_u64 v[230:231], s[18:19], 0, v[154:155]
	global_load_lds_dwordx4 v[230:231], off
	s_waitcnt vmcnt(8)
	s_waitcnt lgkmcnt(0)
	s_barrier
; #define PG8_STAGE(bufoff, gbase, voff) do { _Pragma("unroll") for (int _i = 0; _i < 2; ++_i) \
;         __builtin_amdgcn_global_load_lds((const unsigned*)((const char*)(gbase) + (voff)[_i]), (PG8_LAS unsigned*)(lds + (bufoff) + ldsw + _i * 8192), 16, 0, 0); } while (0)
; #define PG8_LDA(dst, b, h) do { _Pragma("unroll") for (int m = 0; m < 4; ++m) _Pragma("unroll") for (int k = 0; k < 2; ++k) dst[m][k] = *(const PG8_LAS bf16x8*)(lds + PG8_SA(b, h) + aoff + m * 2048 + k * 1024); } while (0)
; #define PG8_MMA(ai, bj, At, Bt) do { __builtin_amdgcn_s_setprio(1); _Pragma("unroll") for (int m = 0; m < 4; ++m) _Pragma("unroll") for (int n = 0; n < 2; ++n) _Pragma("unroll") for (int k = 0; k < 2; ++k) \
;         acc[ai][bj][m][n] = __builtin_amdgcn_mfma_f32_16x16x32_bf16(Bt[n][k], At[m][k], acc[ai][bj][m][n], 0, 0, 0); __builtin_amdgcn_s_setprio(0); } while (0)
; #define PG8_WAIT_V(n) asm volatile("s_waitcnt vmcnt(" #n ")" ::: "memory")
; #define PG8_WAIT_L(n) asm volatile("s_waitcnt lgkmcnt(" #n ")" ::: "memory")
; #define PG8_BAR __builtin_amdgcn_s_barrier()
; #define PG8_SCHED __builtin_amdgcn_sched_barrier(0)
; template <class Epi, class Sched, bool ALIGN_EPI = false, bool SP2 = false>
; __device__ __forceinline__ void gemm_phase(PG8_LAS unsigned char* lds, const Gemm g, const Sched& S, const Epi& E) {
;     ...
;             PG8_WAIT_V(8); PG8_WAIT_L(0); PG8_BAR; PG8_MMA(0, 0, At, B0); PG8_MMA(0, 1, At, B1); PG8_BAR; PG8_SCHED;
;             PG8_LDA(At, 1, 1); PG8_STAGE(PG8_SB(1, 0), b3, voffB); PG8_STAGE(PG8_SB(1, 1), b3 + hstep, voffB); PG8_STAGE(PG8_SA(1, 0), a3, voffA);
;             PG8_WAIT_V(8); PG8_WAIT_L(0); PG8_BAR; PG8_MMA(1, 0, At, B0); PG8_MMA(1, 1, At, B1); PG8_BAR; PG8_SCHED;
;     ...
;         if constexpr (ALIGN_EPI) { if (wr == 0) PG8_BAR; }
	s_setprio 1
	s_waitcnt lgkmcnt(0)
	v_mfma_f32_16x16x32_bf16 v[124:127], v[128:131], v[178:181], v[124:127]
	v_mfma_f32_16x16x32_bf16 v[120:123], v[136:139], v[178:181], v[120:123]
	v_mfma_f32_16x16x32_bf16 v[108:111], v[128:131], v[186:189], v[108:111]
	v_mfma_f32_16x16x32_bf16 v[104:107], v[136:139], v[186:189], v[104:107]
	v_mfma_f32_16x16x32_bf16 v[92:95], v[128:131], v[202:205], v[92:95]
	v_mfma_f32_16x16x32_bf16 v[88:91], v[136:139], v[202:205], v[88:91]
	v_mfma_f32_16x16x32_bf16 v[76:79], v[128:131], v[210:213], v[76:79]
	v_mfma_f32_16x16x32_bf16 v[72:75], v[136:139], v[210:213], v[72:75]
	v_mfma_f32_16x16x32_bf16 v[124:127], v[132:135], v[182:185], v[124:127]
	v_mfma_f32_16x16x32_bf16 v[120:123], v[140:143], v[182:185], v[120:123]
	v_mfma_f32_16x16x32_bf16 v[108:111], v[132:135], v[194:197], v[108:111]
	v_mfma_f32_16x16x32_bf16 v[104:107], v[140:143], v[194:197], v[104:107]
	v_mfma_f32_16x16x32_bf16 v[92:95], v[132:135], v[206:209], v[92:95]
	v_mfma_f32_16x16x32_bf16 v[88:91], v[140:143], v[206:209], v[88:91]
	v_mfma_f32_16x16x32_bf16 v[76:79], v[132:135], v[214:217], v[76:79]
	v_mfma_f32_16x16x32_bf16 v[72:75], v[140:143], v[214:217], v[72:75]
	s_setprio 0
	s_setprio 1
	v_mfma_f32_16x16x32_bf16 v[116:119], v[144:147], v[178:181], v[116:119]
	v_mfma_f32_16x16x32_bf16 v[112:115], v[164:167], v[178:181], v[112:115]
	v_mfma_f32_16x16x32_bf16 v[100:103], v[144:147], v[186:189], v[100:103]
	v_mfma_f32_16x16x32_bf16 v[96:99], v[164:167], v[186:189], v[96:99]
	v_mfma_f32_16x16x32_bf16 v[84:87], v[144:147], v[202:205], v[84:87]
	v_mfma_f32_16x16x32_bf16 v[80:83], v[164:167], v[202:205], v[80:83]
	v_mfma_f32_16x16x32_bf16 v[68:71], v[144:147], v[210:213], v[68:71]
	v_mfma_f32_16x16x32_bf16 v[64:67], v[164:167], v[210:213], v[64:67]
	v_mfma_f32_16x16x32_bf16 v[116:119], v[148:151], v[182:185], v[116:119]
	v_mfma_f32_16x16x32_bf16 v[112:115], v[174:177], v[182:185], v[112:115]
	v_mfma_f32_16x16x32_bf16 v[100:103], v[148:151], v[194:197], v[100:103]
	v_mfma_f32_16x16x32_bf16 v[96:99], v[174:177], v[194:197], v[96:99]
	v_mfma_f32_16x16x32_bf16 v[84:87], v[148:151], v[206:209], v[84:87]
	v_mfma_f32_16x16x32_bf16 v[80:83], v[174:177], v[206:209], v[80:83]
	s_barrier
	v_mfma_f32_16x16x32_bf16 v[68:71], v[148:151], v[214:217], v[68:71]
	v_mfma_f32_16x16x32_bf16 v[64:67], v[174:177], v[214:217], v[64:67]
	s_setprio 0
	s_add_i32 s18, s24, s43
	v_lshl_add_u64 v[168:169], v[168:169], 0, s[16:17]
	s_mov_b32 m0, s18
	ds_read_b128 v[178:181], v173 offset:49152
	ds_read_b128 v[182:185], v173 offset:50176
	ds_read_b128 v[186:189], v173 offset:51200
	ds_read_b128 v[194:197], v173 offset:52224
	ds_read_b128 v[202:205], v173 offset:53248
	ds_read_b128 v[206:209], v173 offset:54272
	ds_read_b128 v[210:213], v173 offset:55296
	ds_read_b128 v[214:217], v173 offset:56320
	global_load_lds_dwordx4 v[168:169], off
	s_add_i32 m0, s18, 0x2000
	s_add_u32 s18, s36, 0x160080
	v_lshl_add_u64 v[168:169], v[190:191], 0, s[16:17]
	s_addc_u32 s19, s37, 0
	s_add_i32 s24, s25, s43
	global_load_lds_dwordx4 v[168:169], off
	s_mov_b32 m0, s24
	v_lshl_add_u64 v[168:169], s[18:19], 0, v[156:157]
	global_load_lds_dwordx4 v[168:169], off
	s_add_i32 m0, s24, 0x2000
	v_lshl_add_u64 v[168:169], s[18:19], 0, v[152:153]
	global_load_lds_dwordx4 v[168:169], off
	s_mov_b32 m0, s51
	v_lshl_add_u64 v[168:169], v[218:219], 0, s[16:17]
	global_load_lds_dwordx4 v[168:169], off
	s_mov_b32 m0, s52
	v_lshl_add_u64 v[168:169], v[220:221], 0, s[16:17]
	global_load_lds_dwordx4 v[168:169], off
	s_waitcnt vmcnt(8)
	s_waitcnt lgkmcnt(0)
	s_barrier
	s_setprio 1
	s_waitcnt lgkmcnt(0)
	v_mfma_f32_16x16x32_bf16 v[60:63], v[128:131], v[178:181], v[60:63]
	v_mfma_f32_16x16x32_bf16 v[56:59], v[136:139], v[178:181], v[56:59]
	v_mfma_f32_16x16x32_bf16 v[44:47], v[128:131], v[186:189], v[44:47]
	v_mfma_f32_16x16x32_bf16 v[40:43], v[136:139], v[186:189], v[40:43]
	v_mfma_f32_16x16x32_bf16 v[28:31], v[128:131], v[202:205], v[28:31]
	v_mfma_f32_16x16x32_bf16 v[24:27], v[136:139], v[202:205], v[24:27]
	v_mfma_f32_16x16x32_bf16 v[12:15], v[128:131], v[210:213], v[12:15]
	v_mfma_f32_16x16x32_bf16 v[8:11], v[136:139], v[210:213], v[8:11]
	v_mfma_f32_16x16x32_bf16 v[60:63], v[132:135], v[182:185], v[60:63]
	v_mfma_f32_16x16x32_bf16 v[56:59], v[140:143], v[182:185], v[56:59]
	v_mfma_f32_16x16x32_bf16 v[44:47], v[132:135], v[194:197], v[44:47]
	v_mfma_f32_16x16x32_bf16 v[40:43], v[140:143], v[194:197], v[40:43]
	v_mfma_f32_16x16x32_bf16 v[28:31], v[132:135], v[206:209], v[28:31]
	v_mfma_f32_16x16x32_bf16 v[24:27], v[140:143], v[206:209], v[24:27]
	v_mfma_f32_16x16x32_bf16 v[12:15], v[132:135], v[214:217], v[12:15]
	v_mfma_f32_16x16x32_bf16 v[8:11], v[140:143], v[214:217], v[8:11]
	s_setprio 0
	s_setprio 1
	v_mfma_f32_16x16x32_bf16 v[52:55], v[144:147], v[178:181], v[52:55]
	v_mfma_f32_16x16x32_bf16 v[48:51], v[164:167], v[178:181], v[48:51]
	v_mfma_f32_16x16x32_bf16 v[36:39], v[144:147], v[186:189], v[36:39]
	v_mfma_f32_16x16x32_bf16 v[32:35], v[164:167], v[186:189], v[32:35]
	v_mfma_f32_16x16x32_bf16 v[20:23], v[144:147], v[202:205], v[20:23]
	v_mfma_f32_16x16x32_bf16 v[16:19], v[164:167], v[202:205], v[16:19]
	v_mfma_f32_16x16x32_bf16 v[4:7], v[144:147], v[210:213], v[4:7]
	v_mfma_f32_16x16x32_bf16 v[0:3], v[164:167], v[210:213], v[0:3]
	v_mfma_f32_16x16x32_bf16 v[52:55], v[148:151], v[182:185], v[52:55]
	v_mfma_f32_16x16x32_bf16 v[48:51], v[174:177], v[182:185], v[48:51]
	v_mfma_f32_16x16x32_bf16 v[36:39], v[148:151], v[194:197], v[36:39]
	v_mfma_f32_16x16x32_bf16 v[32:35], v[174:177], v[194:197], v[32:35]
	v_mfma_f32_16x16x32_bf16 v[20:23], v[148:151], v[206:209], v[20:23]
	v_mfma_f32_16x16x32_bf16 v[16:19], v[174:177], v[206:209], v[16:19]
	s_barrier
	v_mfma_f32_16x16x32_bf16 v[4:7], v[148:151], v[214:217], v[4:7]
	v_mfma_f32_16x16x32_bf16 v[0:3], v[174:177], v[214:217], v[0:3]
	s_setprio 0
	s_add_i32 s61, s61, 2
	s_add_u32 s59, s59, 0x100
	s_addc_u32 s60, s60, 0
	s_cmpk_gt_u32 s61, 0x55
	s_mov_b64 s[18:19], s[30:31]
	s_cbranch_scc0 .LBB0_817
	s_and_b64 vcc, exec, s[12:13]
	s_cbranch_vccz .LBB0_820
	s_barrier
